# rstd row loads of the GEMM epilogues issued in the last K-iteration's final MFMA segment
# baseline (speedup 1.0000x reference)
.LBB0_111:
	ds_read_b128 v[162:165], v155
	ds_read_b128 v[166:169], v155 offset:1024
	ds_read_b128 v[170:173], v155 offset:2048
	ds_read_b128 v[174:177], v155 offset:3072
	ds_read_b128 v[178:181], v157
	ds_read_b128 v[186:189], v157 offset:1024
	ds_read_b128 v[190:193], v157 offset:2048
	ds_read_b128 v[194:197], v157 offset:3072
	s_add_u32 s19, s40, 0xfffc0080
	s_addc_u32 s20, s41, -1
	s_cmp_eq_u32 s18, 12
	s_cselect_b32 s89, s12, s20
	s_cselect_b32 s88, s13, s19
	s_cselect_b32 s81, s14, s17
	s_cselect_b32 s80, s15, s16
	s_add_i32 m0, s62, 0xc000
	ds_read_b128 v[198:201], v159
	ds_read_b128 v[202:205], v159 offset:1024
	ds_read_b128 v[206:209], v159 offset:2048
	ds_read_b128 v[210:213], v159 offset:3072
	ds_read_b128 v[214:217], v159 offset:4096
	ds_read_b128 v[218:221], v159 offset:5120
	ds_read_b128 v[222:225], v159 offset:6144
	ds_read_b128 v[226:229], v159 offset:7168
	global_load_lds_dwordx4 v136, s[40:41]
	s_add_i32 m0, s62, 0xe000
	s_nop 0
	global_load_lds_dwordx4 v138, s[40:41]
	s_waitcnt vmcnt(8)
	s_waitcnt lgkmcnt(0)
	s_barrier
	s_waitcnt lgkmcnt(0)
	v_mfma_f32_16x16x32_bf16 v[124:127], v[162:165], v[198:201], v[124:127]
	v_mfma_f32_16x16x32_bf16 v[120:123], v[170:173], v[198:201], v[120:123]
	v_mfma_f32_16x16x32_bf16 v[108:111], v[162:165], v[206:209], v[108:111]
	v_mfma_f32_16x16x32_bf16 v[100:103], v[170:173], v[206:209], v[100:103]
	v_mfma_f32_16x16x32_bf16 v[92:95], v[162:165], v[214:217], v[92:95]
	v_mfma_f32_16x16x32_bf16 v[84:87], v[170:173], v[214:217], v[84:87]
	v_mfma_f32_16x16x32_bf16 v[76:79], v[162:165], v[222:225], v[76:79]
	v_mfma_f32_16x16x32_bf16 v[68:71], v[170:173], v[222:225], v[68:71]
	v_mfma_f32_16x16x32_bf16 v[124:127], v[166:169], v[202:205], v[124:127]
	v_mfma_f32_16x16x32_bf16 v[120:123], v[174:177], v[202:205], v[120:123]
	v_mfma_f32_16x16x32_bf16 v[108:111], v[166:169], v[210:213], v[108:111]
	v_mfma_f32_16x16x32_bf16 v[100:103], v[174:177], v[210:213], v[100:103]
	v_mfma_f32_16x16x32_bf16 v[92:95], v[166:169], v[218:221], v[92:95]
	v_mfma_f32_16x16x32_bf16 v[84:87], v[174:177], v[218:221], v[84:87]
	v_mfma_f32_16x16x32_bf16 v[76:79], v[166:169], v[226:229], v[76:79]
	v_mfma_f32_16x16x32_bf16 v[68:71], v[174:177], v[226:229], v[68:71]
	v_mfma_f32_16x16x32_bf16 v[116:119], v[178:181], v[198:201], v[116:119]
	v_mfma_f32_16x16x32_bf16 v[112:115], v[190:193], v[198:201], v[112:115]
	v_mfma_f32_16x16x32_bf16 v[104:107], v[178:181], v[206:209], v[104:107]
	v_mfma_f32_16x16x32_bf16 v[96:99], v[190:193], v[206:209], v[96:99]
	v_mfma_f32_16x16x32_bf16 v[88:91], v[178:181], v[214:217], v[88:91]
	v_mfma_f32_16x16x32_bf16 v[80:83], v[190:193], v[214:217], v[80:83]
	v_mfma_f32_16x16x32_bf16 v[72:75], v[178:181], v[222:225], v[72:75]
	v_mfma_f32_16x16x32_bf16 v[64:67], v[190:193], v[222:225], v[64:67]
	v_mfma_f32_16x16x32_bf16 v[116:119], v[186:189], v[202:205], v[116:119]
	v_mfma_f32_16x16x32_bf16 v[112:115], v[194:197], v[202:205], v[112:115]
	v_mfma_f32_16x16x32_bf16 v[104:107], v[186:189], v[210:213], v[104:107]
	v_mfma_f32_16x16x32_bf16 v[96:99], v[194:197], v[210:213], v[96:99]
	v_mfma_f32_16x16x32_bf16 v[88:91], v[186:189], v[218:221], v[88:91]
	v_mfma_f32_16x16x32_bf16 v[80:83], v[194:197], v[218:221], v[80:83]
	v_mfma_f32_16x16x32_bf16 v[72:75], v[186:189], v[226:229], v[72:75]
	v_mfma_f32_16x16x32_bf16 v[64:67], v[194:197], v[226:229], v[64:67]
	s_barrier
	s_add_i32 s19, s73, s3
	s_mov_b32 m0, s19
	ds_read_b128 v[198:201], v159 offset:16384
	ds_read_b128 v[202:205], v159 offset:17408
	ds_read_b128 v[206:209], v159 offset:18432
	ds_read_b128 v[210:213], v159 offset:19456
	ds_read_b128 v[214:217], v159 offset:20480
	ds_read_b128 v[218:221], v159 offset:21504
	ds_read_b128 v[222:225], v159 offset:22528
	ds_read_b128 v[226:229], v159 offset:23552
	global_load_lds_dwordx4 v132, s[80:81]
	s_add_i32 m0, s19, 0x2000
	s_add_u32 s20, s80, 0x40000
	s_addc_u32 s21, s81, 0
	s_add_i32 s19, s74, s3
	global_load_lds_dwordx4 v128, s[80:81]
	s_mov_b32 m0, s19
	global_load_lds_dwordx4 v132, s[20:21]
	s_add_i32 m0, s19, 0x2000
	s_nop 0
	global_load_lds_dwordx4 v128, s[20:21]
	s_mov_b32 m0, s62
	s_nop 0
	global_load_lds_dwordx4 v134, s[88:89]
	s_mov_b32 m0, s63
	s_nop 0
	global_load_lds_dwordx4 v130, s[88:89]
	s_add_u32 s98, s80, s28
	s_addc_u32 s99, s81, s29
	s_add_u32 s100, s88, s28
	s_addc_u32 s101, s89, s29
	s_waitcnt vmcnt(8)
	s_waitcnt lgkmcnt(0)
	s_barrier
	s_waitcnt lgkmcnt(0)
	v_mfma_f32_16x16x32_bf16 v[60:63], v[162:165], v[198:201], v[60:63]
	v_mfma_f32_16x16x32_bf16 v[52:55], v[170:173], v[198:201], v[52:55]
	v_mfma_f32_16x16x32_bf16 v[44:47], v[162:165], v[206:209], v[44:47]
	v_mfma_f32_16x16x32_bf16 v[36:39], v[170:173], v[206:209], v[36:39]
	v_mfma_f32_16x16x32_bf16 v[28:31], v[162:165], v[214:217], v[28:31]
	v_mfma_f32_16x16x32_bf16 v[20:23], v[170:173], v[214:217], v[20:23]
	v_mfma_f32_16x16x32_bf16 v[12:15], v[162:165], v[222:225], v[12:15]
	v_mfma_f32_16x16x32_bf16 v[4:7], v[170:173], v[222:225], v[4:7]
	v_mfma_f32_16x16x32_bf16 v[60:63], v[166:169], v[202:205], v[60:63]
	v_mfma_f32_16x16x32_bf16 v[52:55], v[174:177], v[202:205], v[52:55]
	v_mfma_f32_16x16x32_bf16 v[44:47], v[166:169], v[210:213], v[44:47]
	v_mfma_f32_16x16x32_bf16 v[36:39], v[174:177], v[210:213], v[36:39]
	v_mfma_f32_16x16x32_bf16 v[28:31], v[166:169], v[218:221], v[28:31]
	v_mfma_f32_16x16x32_bf16 v[20:23], v[174:177], v[218:221], v[20:23]
	v_mfma_f32_16x16x32_bf16 v[12:15], v[166:169], v[226:229], v[12:15]
	v_mfma_f32_16x16x32_bf16 v[4:7], v[174:177], v[226:229], v[4:7]
	v_mfma_f32_16x16x32_bf16 v[56:59], v[178:181], v[198:201], v[56:59]
	v_mfma_f32_16x16x32_bf16 v[48:51], v[190:193], v[198:201], v[48:51]
	v_mfma_f32_16x16x32_bf16 v[40:43], v[178:181], v[206:209], v[40:43]
	v_mfma_f32_16x16x32_bf16 v[32:35], v[190:193], v[206:209], v[32:35]
	v_mfma_f32_16x16x32_bf16 v[24:27], v[178:181], v[214:217], v[24:27]
	v_mfma_f32_16x16x32_bf16 v[16:19], v[190:193], v[214:217], v[16:19]
	v_mfma_f32_16x16x32_bf16 v[8:11], v[178:181], v[222:225], v[8:11]
	v_mfma_f32_16x16x32_bf16 v[0:3], v[190:193], v[222:225], v[0:3]
	v_mfma_f32_16x16x32_bf16 v[56:59], v[186:189], v[202:205], v[56:59]
	v_mfma_f32_16x16x32_bf16 v[48:51], v[194:197], v[202:205], v[48:51]
	v_mfma_f32_16x16x32_bf16 v[40:43], v[186:189], v[210:213], v[40:43]
	v_mfma_f32_16x16x32_bf16 v[32:35], v[194:197], v[210:213], v[32:35]
	v_mfma_f32_16x16x32_bf16 v[24:27], v[186:189], v[218:221], v[24:27]
	v_mfma_f32_16x16x32_bf16 v[16:19], v[194:197], v[218:221], v[16:19]
	v_mfma_f32_16x16x32_bf16 v[8:11], v[186:189], v[226:229], v[8:11]
	v_mfma_f32_16x16x32_bf16 v[0:3], v[194:197], v[226:229], v[0:3]
	s_barrier
	s_add_i32 s19, 0, 0x18000
	v_add_u32_e32 v146, s19, v151
	s_add_i32 s22, 0, 0x1c000
	ds_read_b128 v[162:165], v146
	ds_read_b128 v[166:169], v146 offset:1024
	ds_read_b128 v[170:173], v146 offset:2048
	ds_read_b128 v[174:177], v146 offset:3072
	v_add_u32_e32 v146, s22, v151
	ds_read_b128 v[178:181], v146
	ds_read_b128 v[186:189], v146 offset:1024
	ds_read_b128 v[190:193], v146 offset:2048
	ds_read_b128 v[194:197], v146 offset:3072
	s_add_u32 s20, s88, 0x40000
	s_addc_u32 s21, s89, 0
	s_mov_b32 m0, s64
	ds_read_b128 v[198:201], v159 offset:32768
	ds_read_b128 v[202:205], v159 offset:33792
	ds_read_b128 v[206:209], v159 offset:34816
	ds_read_b128 v[210:213], v159 offset:35840
	ds_read_b128 v[214:217], v159 offset:36864
	ds_read_b128 v[218:221], v159 offset:37888
	ds_read_b128 v[222:225], v159 offset:38912
	ds_read_b128 v[226:229], v159 offset:39936
	global_load_lds_dwordx4 v134, s[20:21]
	s_mov_b32 m0, s65
	s_nop 0
	global_load_lds_dwordx4 v130, s[20:21]
	s_waitcnt vmcnt(8)
	s_waitcnt lgkmcnt(0)
	s_barrier
	s_waitcnt lgkmcnt(0)
	v_mfma_f32_16x16x32_bf16 v[124:127], v[162:165], v[198:201], v[124:127]
	v_mfma_f32_16x16x32_bf16 v[120:123], v[170:173], v[198:201], v[120:123]
	v_mfma_f32_16x16x32_bf16 v[108:111], v[162:165], v[206:209], v[108:111]
	v_mfma_f32_16x16x32_bf16 v[100:103], v[170:173], v[206:209], v[100:103]
	v_mfma_f32_16x16x32_bf16 v[92:95], v[162:165], v[214:217], v[92:95]
	v_mfma_f32_16x16x32_bf16 v[84:87], v[170:173], v[214:217], v[84:87]
	v_mfma_f32_16x16x32_bf16 v[76:79], v[162:165], v[222:225], v[76:79]
	v_mfma_f32_16x16x32_bf16 v[68:71], v[170:173], v[222:225], v[68:71]
	v_mfma_f32_16x16x32_bf16 v[124:127], v[166:169], v[202:205], v[124:127]
	v_mfma_f32_16x16x32_bf16 v[120:123], v[174:177], v[202:205], v[120:123]
	v_mfma_f32_16x16x32_bf16 v[108:111], v[166:169], v[210:213], v[108:111]
	v_mfma_f32_16x16x32_bf16 v[100:103], v[174:177], v[210:213], v[100:103]
	v_mfma_f32_16x16x32_bf16 v[92:95], v[166:169], v[218:221], v[92:95]
	v_mfma_f32_16x16x32_bf16 v[84:87], v[174:177], v[218:221], v[84:87]
	v_mfma_f32_16x16x32_bf16 v[76:79], v[166:169], v[226:229], v[76:79]
	v_mfma_f32_16x16x32_bf16 v[68:71], v[174:177], v[226:229], v[68:71]
	v_mfma_f32_16x16x32_bf16 v[116:119], v[178:181], v[198:201], v[116:119]
	v_mfma_f32_16x16x32_bf16 v[112:115], v[190:193], v[198:201], v[112:115]
	v_mfma_f32_16x16x32_bf16 v[104:107], v[178:181], v[206:209], v[104:107]
	v_mfma_f32_16x16x32_bf16 v[96:99], v[190:193], v[206:209], v[96:99]
	v_mfma_f32_16x16x32_bf16 v[88:91], v[178:181], v[214:217], v[88:91]
	v_mfma_f32_16x16x32_bf16 v[80:83], v[190:193], v[214:217], v[80:83]
	v_mfma_f32_16x16x32_bf16 v[72:75], v[178:181], v[222:225], v[72:75]
	v_mfma_f32_16x16x32_bf16 v[64:67], v[190:193], v[222:225], v[64:67]
	v_mfma_f32_16x16x32_bf16 v[116:119], v[186:189], v[202:205], v[116:119]
	v_mfma_f32_16x16x32_bf16 v[112:115], v[194:197], v[202:205], v[112:115]
	v_mfma_f32_16x16x32_bf16 v[104:107], v[186:189], v[210:213], v[104:107]
	v_mfma_f32_16x16x32_bf16 v[96:99], v[194:197], v[210:213], v[96:99]
	v_mfma_f32_16x16x32_bf16 v[88:91], v[186:189], v[218:221], v[88:91]
	v_mfma_f32_16x16x32_bf16 v[80:83], v[194:197], v[218:221], v[80:83]
	v_mfma_f32_16x16x32_bf16 v[72:75], v[186:189], v[226:229], v[72:75]
	v_mfma_f32_16x16x32_bf16 v[64:67], v[194:197], v[226:229], v[64:67]
	s_barrier
	s_add_i32 s19, s19, s3
	s_mov_b32 m0, s19
	ds_read_b128 v[198:201], v159 offset:49152
	ds_read_b128 v[202:205], v159 offset:50176
	ds_read_b128 v[206:209], v159 offset:51200
	ds_read_b128 v[210:213], v159 offset:52224
	ds_read_b128 v[214:217], v159 offset:53248
	ds_read_b128 v[218:221], v159 offset:54272
	ds_read_b128 v[222:225], v159 offset:55296
	ds_read_b128 v[226:229], v159 offset:56320
	global_load_lds_dwordx4 v132, s[98:99]
	s_add_i32 m0, s19, 0x2000
	s_add_u32 s20, s80, 0x40080
	s_addc_u32 s21, s81, 0
	s_add_i32 s19, s22, s3
	global_load_lds_dwordx4 v128, s[98:99]
	s_mov_b32 m0, s19
	s_nop 0
	global_load_lds_dwordx4 v132, s[20:21]
	s_add_i32 m0, s19, 0x2000
	s_nop 0
	global_load_lds_dwordx4 v128, s[20:21]
	s_mov_b32 m0, s67
	s_nop 0
	global_load_lds_dwordx4 v134, s[100:101]
	s_mov_b32 m0, s70
	s_nop 0
	global_load_lds_dwordx4 v130, s[100:101]
	s_waitcnt vmcnt(8)
	s_waitcnt lgkmcnt(0)
	s_barrier
	s_waitcnt lgkmcnt(0)
	v_mfma_f32_16x16x32_bf16 v[60:63], v[162:165], v[198:201], v[60:63]
	v_mfma_f32_16x16x32_bf16 v[52:55], v[170:173], v[198:201], v[52:55]
	s_cmp_eq_u32 s18, 12
	s_cbranch_scc0 .Lrs_skip_111
	v_lshl_add_u32 v252, s6, 8, v147
	v_ashrrev_i32_e32 v253, 31, v252
	v_lshl_add_u64 v[254:255], v[252:253], 2, s[8:9]
	global_load_dword v243, v[254:255], off
	global_load_dword v244, v[254:255], off offset:64
	global_load_dword v245, v[254:255], off offset:128
	global_load_dword v246, v[254:255], off offset:192
	global_load_dword v247, v[254:255], off offset:512
	global_load_dword v248, v[254:255], off offset:576
	global_load_dword v249, v[254:255], off offset:640
	global_load_dword v250, v[254:255], off offset:704
.Lrs_skip_111:
	v_mfma_f32_16x16x32_bf16 v[44:47], v[162:165], v[206:209], v[44:47]
	v_mfma_f32_16x16x32_bf16 v[36:39], v[170:173], v[206:209], v[36:39]
	v_mfma_f32_16x16x32_bf16 v[28:31], v[162:165], v[214:217], v[28:31]
	v_mfma_f32_16x16x32_bf16 v[20:23], v[170:173], v[214:217], v[20:23]
	v_mfma_f32_16x16x32_bf16 v[12:15], v[162:165], v[222:225], v[12:15]
	v_mfma_f32_16x16x32_bf16 v[4:7], v[170:173], v[222:225], v[4:7]
	v_mfma_f32_16x16x32_bf16 v[60:63], v[166:169], v[202:205], v[60:63]
	v_mfma_f32_16x16x32_bf16 v[52:55], v[174:177], v[202:205], v[52:55]
	v_mfma_f32_16x16x32_bf16 v[44:47], v[166:169], v[210:213], v[44:47]
	v_mfma_f32_16x16x32_bf16 v[36:39], v[174:177], v[210:213], v[36:39]
	v_mfma_f32_16x16x32_bf16 v[28:31], v[166:169], v[218:221], v[28:31]
	v_mfma_f32_16x16x32_bf16 v[20:23], v[174:177], v[218:221], v[20:23]
	v_mfma_f32_16x16x32_bf16 v[12:15], v[166:169], v[226:229], v[12:15]
	v_mfma_f32_16x16x32_bf16 v[4:7], v[174:177], v[226:229], v[4:7]
	v_mfma_f32_16x16x32_bf16 v[56:59], v[178:181], v[198:201], v[56:59]
	v_mfma_f32_16x16x32_bf16 v[48:51], v[190:193], v[198:201], v[48:51]
	v_mfma_f32_16x16x32_bf16 v[40:43], v[178:181], v[206:209], v[40:43]
	v_mfma_f32_16x16x32_bf16 v[32:35], v[190:193], v[206:209], v[32:35]
	v_mfma_f32_16x16x32_bf16 v[24:27], v[178:181], v[214:217], v[24:27]
	v_mfma_f32_16x16x32_bf16 v[16:19], v[190:193], v[214:217], v[16:19]
	v_mfma_f32_16x16x32_bf16 v[8:11], v[178:181], v[222:225], v[8:11]
	v_mfma_f32_16x16x32_bf16 v[0:3], v[190:193], v[222:225], v[0:3]
	v_mfma_f32_16x16x32_bf16 v[56:59], v[186:189], v[202:205], v[56:59]
	v_mfma_f32_16x16x32_bf16 v[48:51], v[194:197], v[202:205], v[48:51]
	v_mfma_f32_16x16x32_bf16 v[40:43], v[186:189], v[210:213], v[40:43]
	v_mfma_f32_16x16x32_bf16 v[32:35], v[194:197], v[210:213], v[32:35]
	v_mfma_f32_16x16x32_bf16 v[24:27], v[186:189], v[218:221], v[24:27]
	v_mfma_f32_16x16x32_bf16 v[16:19], v[194:197], v[218:221], v[16:19]
	v_mfma_f32_16x16x32_bf16 v[8:11], v[186:189], v[226:229], v[8:11]
	v_mfma_f32_16x16x32_bf16 v[0:3], v[194:197], v[226:229], v[0:3]
	s_barrier
	s_add_i32 s18, s18, 2
	s_add_u32 s40, s40, 0x100
	s_addc_u32 s41, s41, 0
	s_add_u32 s16, s16, 0x100
	s_addc_u32 s17, s17, 0
	s_cmp_gt_u32 s18, 13
	s_cbranch_scc0 .LBB0_111
	s_and_b64 vcc, exec, s[30:31]
	s_cbranch_vccz .LBB0_114
	s_barrier
.LBB0_114:
	v_lshl_add_u32 v144, s6, 8, v147
	v_ashrrev_i32_e32 v145, 31, v144
	v_lshl_add_u64 v[162:163], v[144:145], 2, s[8:9]
	s_waitcnt vmcnt(0)
	v_mov_b32_e32 v145, v243
	v_mov_b32_e32 v146, v244
	v_mov_b32_e32 v149, v245
	v_mov_b32_e32 v150, v246
	v_mov_b32_e32 v152, v247
	v_mov_b32_e32 v164, v248
	v_mov_b32_e32 v165, v249
	s_nop 0
	v_mov_b32_e32 v163, v250
	v_lshl_or_b32 v148, s7, 7, v153
	s_andn2_b64 vcc, exec, s[4:5]
	s_waitcnt vmcnt(0)
	v_fmamk_f32 v145, v145, 0x3a800000, v161
	v_rsq_f32_e32 v162, v145
	v_fmamk_f32 v145, v146, 0x3a800000, v161
	v_rsq_f32_e32 v160, v145
	v_fmamk_f32 v145, v149, 0x3a800000, v161
	v_rsq_f32_e32 v158, v145
	v_fmamk_f32 v145, v150, 0x3a800000, v161
	v_rsq_f32_e32 v156, v145
	v_fmamk_f32 v145, v152, 0x3a800000, v161
	v_rsq_f32_e32 v154, v145
	v_fmamk_f32 v145, v164, 0x3a800000, v161
	v_rsq_f32_e32 v152, v145
	v_fmamk_f32 v145, v165, 0x3a800000, v161
	v_rsq_f32_e32 v150, v145
	v_fmamk_f32 v145, v163, 0x3a800000, v161
	v_pk_mul_f32 v[124:125], v[124:125], v[162:163] op_sel_hi:[1,0]
	v_rsq_f32_e32 v146, v145
	v_mul_f32_e32 v145, 0xbfb8aa3b, v124
	v_exp_f32_e32 v145, v145
	v_pk_mul_f32 v[116:117], v[116:117], v[162:163] op_sel_hi:[1,0]
	v_pk_mul_f32 v[118:119], v[118:119], v[162:163] op_sel_hi:[1,0]
	v_pk_mul_f32 v[120:121], v[120:121], v[162:163] op_sel_hi:[1,0]
	v_add_f32_e32 v145, 1.0, v145
	v_rcp_f32_e32 v164, v145
	v_mul_f32_e32 v145, 0xbfb8aa3b, v125
	v_exp_f32_e32 v145, v145
	v_pk_mul_f32 v[112:113], v[112:113], v[162:163] op_sel_hi:[1,0]
	v_ashrrev_i32_e32 v149, 31, v148
	v_pk_mul_f32 v[114:115], v[114:115], v[162:163] op_sel_hi:[1,0]
	v_add_f32_e32 v145, 1.0, v145
	v_rcp_f32_e32 v165, v145
	v_lshl_add_u64 v[148:149], v[148:149], 1, s[68:69]
	v_pk_mul_f32 v[108:109], v[108:109], v[160:161] op_sel_hi:[1,0]
	v_pk_mul_f32 v[104:105], v[104:105], v[160:161] op_sel_hi:[1,0]
	v_pk_mul_f32 v[124:125], v[124:125], v[164:165]
	v_pk_mul_f32 v[106:107], v[106:107], v[160:161] op_sel_hi:[1,0]
	v_pk_mul_f32 v[116:117], v[116:117], v[124:125]
	v_pk_mul_f32 v[124:125], v[126:127], v[162:163] op_sel_hi:[1,0]
	v_pk_mul_f32 v[100:101], v[100:101], v[160:161] op_sel_hi:[1,0]
	v_mul_f32_e32 v126, 0xbfb8aa3b, v124
	v_mul_f32_e32 v127, 0xbfb8aa3b, v125
	v_exp_f32_e32 v126, v126
	v_exp_f32_e32 v127, v127
	v_pk_mul_f32 v[96:97], v[96:97], v[160:161] op_sel_hi:[1,0]
	v_pk_mul_f32 v[98:99], v[98:99], v[160:161] op_sel_hi:[1,0]
	v_add_f32_e32 v126, 1.0, v126
	v_add_f32_e32 v127, 1.0, v127
	v_rcp_f32_e32 v126, v126
	v_rcp_f32_e32 v127, v127
	v_pk_mul_f32 v[92:93], v[92:93], v[158:159] op_sel_hi:[1,0]
	v_pk_mul_f32 v[88:89], v[88:89], v[158:159] op_sel_hi:[1,0]
	v_pk_mul_f32 v[90:91], v[90:91], v[158:159] op_sel_hi:[1,0]
	v_pk_mul_f32 v[124:125], v[124:125], v[126:127]
	v_pk_mul_f32 v[84:85], v[84:85], v[158:159] op_sel_hi:[1,0]
	v_pk_mul_f32 v[118:119], v[118:119], v[124:125]
	v_mul_f32_e32 v124, 0xbfb8aa3b, v120
	v_mul_f32_e32 v125, 0xbfb8aa3b, v121
	v_exp_f32_e32 v124, v124
	v_exp_f32_e32 v125, v125
	v_pk_mul_f32 v[80:81], v[80:81], v[158:159] op_sel_hi:[1,0]
	v_pk_mul_f32 v[82:83], v[82:83], v[158:159] op_sel_hi:[1,0]
	v_add_f32_e32 v124, 1.0, v124
	v_add_f32_e32 v125, 1.0, v125
	v_rcp_f32_e32 v124, v124
	v_rcp_f32_e32 v125, v125
	v_pk_mul_f32 v[76:77], v[76:77], v[156:157] op_sel_hi:[1,0]
	v_pk_mul_f32 v[72:73], v[72:73], v[156:157] op_sel_hi:[1,0]
	v_pk_mul_f32 v[74:75], v[74:75], v[156:157] op_sel_hi:[1,0]
	v_pk_mul_f32 v[120:121], v[120:121], v[124:125]
	v_pk_mul_f32 v[68:69], v[68:69], v[156:157] op_sel_hi:[1,0]
	v_pk_mul_f32 v[120:121], v[112:113], v[120:121]
	v_pk_mul_f32 v[112:113], v[122:123], v[162:163] op_sel_hi:[1,0]
	v_pk_mul_f32 v[64:65], v[64:65], v[156:157] op_sel_hi:[1,0]
	v_mul_f32_e32 v122, 0xbfb8aa3b, v112
	v_mul_f32_e32 v123, 0xbfb8aa3b, v113
	v_exp_f32_e32 v122, v122
	v_exp_f32_e32 v123, v123
	v_pk_mul_f32 v[66:67], v[66:67], v[156:157] op_sel_hi:[1,0]
	v_pk_mul_f32 v[60:61], v[60:61], v[154:155] op_sel_hi:[1,0]
	v_add_f32_e32 v122, 1.0, v122
	v_add_f32_e32 v123, 1.0, v123
	v_rcp_f32_e32 v122, v122
	v_rcp_f32_e32 v123, v123
	v_pk_mul_f32 v[56:57], v[56:57], v[154:155] op_sel_hi:[1,0]
	v_pk_mul_f32 v[58:59], v[58:59], v[154:155] op_sel_hi:[1,0]
	v_pk_mul_f32 v[52:53], v[52:53], v[154:155] op_sel_hi:[1,0]
	v_pk_mul_f32 v[112:113], v[112:113], v[122:123]
	v_pk_mul_f32 v[48:49], v[48:49], v[154:155] op_sel_hi:[1,0]
	v_pk_mul_f32 v[122:123], v[114:115], v[112:113]
	v_cvt_pk_bf16_f32 v112, v116, v117
	v_cvt_pk_bf16_f32 v113, v118, v119
	v_cvt_pk_bf16_f32 v114, v120, v121
	v_cvt_pk_bf16_f32 v115, v122, v123
	v_mad_i64_i32 v[116:117], s[6:7], v144, s75, v[148:149]
	global_store_dwordx4 v[116:117], v[112:115], off nt
	v_pk_mul_f32 v[50:51], v[50:51], v[154:155] op_sel_hi:[1,0]
	v_pk_mul_f32 v[44:45], v[44:45], v[152:153] op_sel_hi:[1,0]
	v_mul_f32_e32 v112, 0xbfb8aa3b, v108
	v_mul_f32_e32 v113, 0xbfb8aa3b, v109
	v_exp_f32_e32 v112, v112
	v_exp_f32_e32 v113, v113
	v_pk_mul_f32 v[40:41], v[40:41], v[152:153] op_sel_hi:[1,0]
	v_pk_mul_f32 v[42:43], v[42:43], v[152:153] op_sel_hi:[1,0]
	v_add_f32_e32 v112, 1.0, v112
	v_add_f32_e32 v113, 1.0, v113
	v_rcp_f32_e32 v112, v112
	v_rcp_f32_e32 v113, v113
	v_pk_mul_f32 v[36:37], v[36:37], v[152:153] op_sel_hi:[1,0]
	v_pk_mul_f32 v[32:33], v[32:33], v[152:153] op_sel_hi:[1,0]
	v_pk_mul_f32 v[34:35], v[34:35], v[152:153] op_sel_hi:[1,0]
	v_pk_mul_f32 v[108:109], v[108:109], v[112:113]
	v_pk_mul_f32 v[28:29], v[28:29], v[150:151] op_sel_hi:[1,0]
	v_pk_mul_f32 v[104:105], v[104:105], v[108:109]
	v_pk_mul_f32 v[108:109], v[110:111], v[160:161] op_sel_hi:[1,0]
	v_pk_mul_f32 v[24:25], v[24:25], v[150:151] op_sel_hi:[1,0]
	v_mul_f32_e32 v110, 0xbfb8aa3b, v108
	v_mul_f32_e32 v111, 0xbfb8aa3b, v109
	v_exp_f32_e32 v110, v110
	v_exp_f32_e32 v111, v111
	v_pk_mul_f32 v[26:27], v[26:27], v[150:151] op_sel_hi:[1,0]
	v_pk_mul_f32 v[20:21], v[20:21], v[150:151] op_sel_hi:[1,0]
	v_add_f32_e32 v110, 1.0, v110
	v_add_f32_e32 v111, 1.0, v111
	v_rcp_f32_e32 v110, v110
	v_rcp_f32_e32 v111, v111
	v_pk_mul_f32 v[16:17], v[16:17], v[150:151] op_sel_hi:[1,0]
	v_pk_mul_f32 v[18:19], v[18:19], v[150:151] op_sel_hi:[1,0]
	v_pk_mul_f32 v[12:13], v[12:13], v[146:147] op_sel_hi:[1,0]
	v_pk_mul_f32 v[108:109], v[108:109], v[110:111]
	v_pk_mul_f32 v[8:9], v[8:9], v[146:147] op_sel_hi:[1,0]
	v_pk_mul_f32 v[106:107], v[106:107], v[108:109]
	v_mul_f32_e32 v108, 0xbfb8aa3b, v100
	v_mul_f32_e32 v109, 0xbfb8aa3b, v101
	v_exp_f32_e32 v108, v108
	v_exp_f32_e32 v109, v109
	v_pk_mul_f32 v[10:11], v[10:11], v[146:147] op_sel_hi:[1,0]
	v_pk_mul_f32 v[4:5], v[4:5], v[146:147] op_sel_hi:[1,0]
	v_add_f32_e32 v108, 1.0, v108
	v_add_f32_e32 v109, 1.0, v109
	v_rcp_f32_e32 v108, v108
	v_rcp_f32_e32 v109, v109
	v_pk_mul_f32 v[0:1], v[0:1], v[146:147] op_sel_hi:[1,0]
	v_pk_mul_f32 v[2:3], v[2:3], v[146:147] op_sel_hi:[1,0]
	v_pk_mul_f32 v[100:101], v[100:101], v[108:109]
	s_nop 0
	v_pk_mul_f32 v[100:101], v[96:97], v[100:101]
	v_pk_mul_f32 v[96:97], v[102:103], v[160:161] op_sel_hi:[1,0]
	v_or_b32_e32 v108, 16, v144
	v_mul_f32_e32 v102, 0xbfb8aa3b, v96
	v_mul_f32_e32 v103, 0xbfb8aa3b, v97
	v_exp_f32_e32 v102, v102
	v_exp_f32_e32 v103, v103
	v_add_f32_e32 v102, 1.0, v102
	v_add_f32_e32 v103, 1.0, v103
	v_rcp_f32_e32 v102, v102
	v_rcp_f32_e32 v103, v103
	s_nop 0
	v_pk_mul_f32 v[96:97], v[96:97], v[102:103]
	s_nop 0
	v_pk_mul_f32 v[102:103], v[98:99], v[96:97]
	v_cvt_pk_bf16_f32 v96, v104, v105
	v_cvt_pk_bf16_f32 v97, v106, v107
	v_cvt_pk_bf16_f32 v98, v100, v101
	v_cvt_pk_bf16_f32 v99, v102, v103
	v_mad_i64_i32 v[100:101], s[6:7], v108, s75, v[148:149]
	global_store_dwordx4 v[100:101], v[96:99], off nt
	s_nop 1
	v_mul_f32_e32 v96, 0xbfb8aa3b, v92
	v_mul_f32_e32 v97, 0xbfb8aa3b, v93
	v_exp_f32_e32 v96, v96
	v_exp_f32_e32 v97, v97
	v_add_f32_e32 v96, 1.0, v96
	v_add_f32_e32 v97, 1.0, v97
	v_rcp_f32_e32 v96, v96
	v_rcp_f32_e32 v97, v97
	s_nop 0
	v_pk_mul_f32 v[92:93], v[92:93], v[96:97]
	s_nop 0
	v_pk_mul_f32 v[88:89], v[88:89], v[92:93]
	v_pk_mul_f32 v[92:93], v[94:95], v[158:159] op_sel_hi:[1,0]
	s_nop 0
	v_mul_f32_e32 v94, 0xbfb8aa3b, v92
	v_mul_f32_e32 v95, 0xbfb8aa3b, v93
	v_exp_f32_e32 v94, v94
	v_exp_f32_e32 v95, v95
	v_add_f32_e32 v94, 1.0, v94
	v_add_f32_e32 v95, 1.0, v95
	v_rcp_f32_e32 v94, v94
	v_rcp_f32_e32 v95, v95
	s_nop 0
	v_pk_mul_f32 v[92:93], v[92:93], v[94:95]
	s_nop 0
	v_pk_mul_f32 v[90:91], v[90:91], v[92:93]
	v_mul_f32_e32 v92, 0xbfb8aa3b, v84
	v_mul_f32_e32 v93, 0xbfb8aa3b, v85
	v_exp_f32_e32 v92, v92
	v_exp_f32_e32 v93, v93
	v_add_f32_e32 v92, 1.0, v92
	v_add_f32_e32 v93, 1.0, v93
	v_rcp_f32_e32 v92, v92
	v_rcp_f32_e32 v93, v93
	s_nop 0
	v_pk_mul_f32 v[84:85], v[84:85], v[92:93]
	s_nop 0
	v_pk_mul_f32 v[84:85], v[80:81], v[84:85]
	v_pk_mul_f32 v[80:81], v[86:87], v[158:159] op_sel_hi:[1,0]
	v_or_b32_e32 v92, 32, v144
	v_mul_f32_e32 v86, 0xbfb8aa3b, v80
	v_mul_f32_e32 v87, 0xbfb8aa3b, v81
	v_exp_f32_e32 v86, v86
	v_exp_f32_e32 v87, v87
	v_add_f32_e32 v86, 1.0, v86
	v_add_f32_e32 v87, 1.0, v87
	v_rcp_f32_e32 v86, v86
	v_rcp_f32_e32 v87, v87
	s_nop 0
	v_pk_mul_f32 v[80:81], v[80:81], v[86:87]
	s_nop 0
	v_pk_mul_f32 v[86:87], v[82:83], v[80:81]
	v_cvt_pk_bf16_f32 v80, v88, v89
	v_cvt_pk_bf16_f32 v81, v90, v91
	v_cvt_pk_bf16_f32 v82, v84, v85
	v_cvt_pk_bf16_f32 v83, v86, v87
	v_mad_i64_i32 v[84:85], s[6:7], v92, s75, v[148:149]
	global_store_dwordx4 v[84:85], v[80:83], off nt
	s_nop 1
	v_mul_f32_e32 v80, 0xbfb8aa3b, v76
	v_mul_f32_e32 v81, 0xbfb8aa3b, v77
	v_exp_f32_e32 v80, v80
	v_exp_f32_e32 v81, v81
	v_add_f32_e32 v80, 1.0, v80
	v_add_f32_e32 v81, 1.0, v81
	v_rcp_f32_e32 v80, v80
	v_rcp_f32_e32 v81, v81
	s_nop 0
	v_pk_mul_f32 v[76:77], v[76:77], v[80:81]
	s_nop 0
	v_pk_mul_f32 v[72:73], v[72:73], v[76:77]
	v_pk_mul_f32 v[76:77], v[78:79], v[156:157] op_sel_hi:[1,0]
	s_nop 0
	v_mul_f32_e32 v78, 0xbfb8aa3b, v76
	v_mul_f32_e32 v79, 0xbfb8aa3b, v77
	v_exp_f32_e32 v78, v78
	v_exp_f32_e32 v79, v79
	v_add_f32_e32 v78, 1.0, v78
	v_add_f32_e32 v79, 1.0, v79
	v_rcp_f32_e32 v78, v78
	v_rcp_f32_e32 v79, v79
	s_nop 0
	v_pk_mul_f32 v[76:77], v[76:77], v[78:79]
	s_nop 0
	v_pk_mul_f32 v[74:75], v[74:75], v[76:77]
	v_mul_f32_e32 v76, 0xbfb8aa3b, v68
	v_mul_f32_e32 v77, 0xbfb8aa3b, v69
	v_exp_f32_e32 v76, v76
	v_exp_f32_e32 v77, v77
	v_add_f32_e32 v76, 1.0, v76
	v_add_f32_e32 v77, 1.0, v77
	v_rcp_f32_e32 v76, v76
	v_rcp_f32_e32 v77, v77
	s_nop 0
	v_pk_mul_f32 v[68:69], v[68:69], v[76:77]
	s_nop 0
	v_pk_mul_f32 v[68:69], v[64:65], v[68:69]
	v_pk_mul_f32 v[64:65], v[70:71], v[156:157] op_sel_hi:[1,0]
	v_or_b32_e32 v76, 48, v144
	v_mul_f32_e32 v70, 0xbfb8aa3b, v64
	v_mul_f32_e32 v71, 0xbfb8aa3b, v65
	v_exp_f32_e32 v70, v70
	v_exp_f32_e32 v71, v71
	v_add_f32_e32 v70, 1.0, v70
	v_add_f32_e32 v71, 1.0, v71
	v_rcp_f32_e32 v70, v70
	v_rcp_f32_e32 v71, v71
	s_nop 0
	v_pk_mul_f32 v[64:65], v[64:65], v[70:71]
	s_nop 0
	v_pk_mul_f32 v[70:71], v[66:67], v[64:65]
	v_cvt_pk_bf16_f32 v64, v72, v73
	v_cvt_pk_bf16_f32 v65, v74, v75
	v_cvt_pk_bf16_f32 v66, v68, v69
	v_cvt_pk_bf16_f32 v67, v70, v71
	v_mad_i64_i32 v[68:69], s[6:7], v76, s75, v[148:149]
	global_store_dwordx4 v[68:69], v[64:67], off nt
	s_nop 1
	v_mul_f32_e32 v64, 0xbfb8aa3b, v60
	v_mul_f32_e32 v65, 0xbfb8aa3b, v61
	v_exp_f32_e32 v64, v64
	v_exp_f32_e32 v65, v65
	v_add_u32_e32 v66, 0x80, v144
	v_add_f32_e32 v64, 1.0, v64
	v_add_f32_e32 v65, 1.0, v65
	v_rcp_f32_e32 v64, v64
	v_rcp_f32_e32 v65, v65
	s_nop 0
	v_pk_mul_f32 v[60:61], v[60:61], v[64:65]
	s_nop 0
	v_pk_mul_f32 v[56:57], v[56:57], v[60:61]
	v_pk_mul_f32 v[60:61], v[62:63], v[154:155] op_sel_hi:[1,0]
	s_nop 0
	v_mul_f32_e32 v62, 0xbfb8aa3b, v60
	v_mul_f32_e32 v63, 0xbfb8aa3b, v61
	v_exp_f32_e32 v62, v62
	v_exp_f32_e32 v63, v63
	v_add_f32_e32 v62, 1.0, v62
	v_add_f32_e32 v63, 1.0, v63
	v_rcp_f32_e32 v62, v62
	v_rcp_f32_e32 v63, v63
	s_nop 0
	v_pk_mul_f32 v[60:61], v[60:61], v[62:63]
	s_nop 0
	v_pk_mul_f32 v[58:59], v[58:59], v[60:61]
	v_mul_f32_e32 v60, 0xbfb8aa3b, v52
	v_mul_f32_e32 v61, 0xbfb8aa3b, v53
	v_exp_f32_e32 v60, v60
	v_exp_f32_e32 v61, v61
	v_add_f32_e32 v60, 1.0, v60
	v_add_f32_e32 v61, 1.0, v61
	v_rcp_f32_e32 v60, v60
	v_rcp_f32_e32 v61, v61
	s_nop 0
	v_pk_mul_f32 v[52:53], v[52:53], v[60:61]
	s_nop 0
	v_pk_mul_f32 v[52:53], v[48:49], v[52:53]
	v_pk_mul_f32 v[48:49], v[54:55], v[154:155] op_sel_hi:[1,0]
	s_nop 0
	v_mul_f32_e32 v54, 0xbfb8aa3b, v48
	v_mul_f32_e32 v55, 0xbfb8aa3b, v49
	v_exp_f32_e32 v54, v54
	v_exp_f32_e32 v55, v55
	v_add_f32_e32 v54, 1.0, v54
	v_add_f32_e32 v55, 1.0, v55
	v_rcp_f32_e32 v54, v54
	v_rcp_f32_e32 v55, v55
	s_nop 0
	v_pk_mul_f32 v[48:49], v[48:49], v[54:55]
	s_nop 0
	v_pk_mul_f32 v[54:55], v[50:51], v[48:49]
	v_cvt_pk_bf16_f32 v48, v56, v57
	v_cvt_pk_bf16_f32 v49, v58, v59
	v_cvt_pk_bf16_f32 v50, v52, v53
	v_cvt_pk_bf16_f32 v51, v54, v55
	v_mad_i64_i32 v[52:53], s[6:7], v66, s75, v[148:149]
	global_store_dwordx4 v[52:53], v[48:51], off nt
	s_nop 1
	v_mul_f32_e32 v48, 0xbfb8aa3b, v44
	v_mul_f32_e32 v49, 0xbfb8aa3b, v45
	v_exp_f32_e32 v48, v48
	v_exp_f32_e32 v49, v49
	v_add_f32_e32 v48, 1.0, v48
	v_add_f32_e32 v49, 1.0, v49
	v_rcp_f32_e32 v48, v48
	v_rcp_f32_e32 v49, v49
	s_nop 0
	v_pk_mul_f32 v[44:45], v[44:45], v[48:49]
	s_nop 0
	v_pk_mul_f32 v[40:41], v[40:41], v[44:45]
	v_pk_mul_f32 v[44:45], v[46:47], v[152:153] op_sel_hi:[1,0]
	s_nop 0
	v_mul_f32_e32 v46, 0xbfb8aa3b, v44
	v_mul_f32_e32 v47, 0xbfb8aa3b, v45
	v_exp_f32_e32 v46, v46
	v_exp_f32_e32 v47, v47
	v_add_f32_e32 v46, 1.0, v46
	v_add_f32_e32 v47, 1.0, v47
	v_rcp_f32_e32 v46, v46
	v_rcp_f32_e32 v47, v47
	s_nop 0
	v_pk_mul_f32 v[44:45], v[44:45], v[46:47]
	s_nop 0
	v_pk_mul_f32 v[42:43], v[42:43], v[44:45]
	v_mul_f32_e32 v44, 0xbfb8aa3b, v36
	v_mul_f32_e32 v45, 0xbfb8aa3b, v37
	v_exp_f32_e32 v44, v44
	v_exp_f32_e32 v45, v45
	v_add_f32_e32 v44, 1.0, v44
	v_add_f32_e32 v45, 1.0, v45
	v_rcp_f32_e32 v44, v44
	v_rcp_f32_e32 v45, v45
	s_nop 0
	v_pk_mul_f32 v[36:37], v[36:37], v[44:45]
	s_nop 0
	v_pk_mul_f32 v[36:37], v[32:33], v[36:37]
	v_pk_mul_f32 v[32:33], v[38:39], v[152:153] op_sel_hi:[1,0]
	v_add_u32_e32 v44, 0x90, v144
	v_mul_f32_e32 v38, 0xbfb8aa3b, v32
	v_mul_f32_e32 v39, 0xbfb8aa3b, v33
	v_exp_f32_e32 v38, v38
	v_exp_f32_e32 v39, v39
	v_add_f32_e32 v38, 1.0, v38
	v_add_f32_e32 v39, 1.0, v39
	v_rcp_f32_e32 v38, v38
	v_rcp_f32_e32 v39, v39
	s_nop 0
	v_pk_mul_f32 v[32:33], v[32:33], v[38:39]
	s_nop 0
	v_pk_mul_f32 v[38:39], v[34:35], v[32:33]
	v_cvt_pk_bf16_f32 v32, v40, v41
	v_cvt_pk_bf16_f32 v33, v42, v43
	v_cvt_pk_bf16_f32 v34, v36, v37
	v_cvt_pk_bf16_f32 v35, v38, v39
	v_mad_i64_i32 v[36:37], s[6:7], v44, s75, v[148:149]
	global_store_dwordx4 v[36:37], v[32:35], off nt
	s_nop 1
	v_mul_f32_e32 v32, 0xbfb8aa3b, v28
	v_mul_f32_e32 v33, 0xbfb8aa3b, v29
	v_exp_f32_e32 v32, v32
	v_exp_f32_e32 v33, v33
	v_add_f32_e32 v32, 1.0, v32
	v_add_f32_e32 v33, 1.0, v33
	v_rcp_f32_e32 v32, v32
	v_rcp_f32_e32 v33, v33
	s_nop 0
	v_pk_mul_f32 v[28:29], v[28:29], v[32:33]
	s_nop 0
	v_pk_mul_f32 v[24:25], v[24:25], v[28:29]
	v_pk_mul_f32 v[28:29], v[30:31], v[150:151] op_sel_hi:[1,0]
	s_nop 0
	v_mul_f32_e32 v30, 0xbfb8aa3b, v28
	v_mul_f32_e32 v31, 0xbfb8aa3b, v29
	v_exp_f32_e32 v30, v30
	v_exp_f32_e32 v31, v31
	v_add_f32_e32 v30, 1.0, v30
	v_add_f32_e32 v31, 1.0, v31
	v_rcp_f32_e32 v30, v30
	v_rcp_f32_e32 v31, v31
	s_nop 0
	v_pk_mul_f32 v[28:29], v[28:29], v[30:31]
	s_nop 0
	v_pk_mul_f32 v[26:27], v[26:27], v[28:29]
	v_mul_f32_e32 v28, 0xbfb8aa3b, v20
	v_mul_f32_e32 v29, 0xbfb8aa3b, v21
	v_exp_f32_e32 v28, v28
	v_exp_f32_e32 v29, v29
	v_add_f32_e32 v28, 1.0, v28
	v_add_f32_e32 v29, 1.0, v29
	v_rcp_f32_e32 v28, v28
	v_rcp_f32_e32 v29, v29
	s_nop 0
	v_pk_mul_f32 v[20:21], v[20:21], v[28:29]
	s_nop 0
	v_pk_mul_f32 v[20:21], v[16:17], v[20:21]
	v_pk_mul_f32 v[16:17], v[22:23], v[150:151] op_sel_hi:[1,0]
	v_add_u32_e32 v28, 0xa0, v144
	v_mul_f32_e32 v22, 0xbfb8aa3b, v16
	v_mul_f32_e32 v23, 0xbfb8aa3b, v17
	v_exp_f32_e32 v22, v22
	v_exp_f32_e32 v23, v23
	v_add_f32_e32 v22, 1.0, v22
	v_add_f32_e32 v23, 1.0, v23
	v_rcp_f32_e32 v22, v22
	v_rcp_f32_e32 v23, v23
	s_nop 0
	v_pk_mul_f32 v[16:17], v[16:17], v[22:23]
	s_nop 0
	v_pk_mul_f32 v[22:23], v[18:19], v[16:17]
	v_cvt_pk_bf16_f32 v16, v24, v25
	v_cvt_pk_bf16_f32 v17, v26, v27
	v_cvt_pk_bf16_f32 v18, v20, v21
	v_cvt_pk_bf16_f32 v19, v22, v23
	v_mad_i64_i32 v[20:21], s[6:7], v28, s75, v[148:149]
	global_store_dwordx4 v[20:21], v[16:19], off nt
	s_nop 1
	v_mul_f32_e32 v16, 0xbfb8aa3b, v12
	v_mul_f32_e32 v17, 0xbfb8aa3b, v13
	v_exp_f32_e32 v16, v16
	v_exp_f32_e32 v17, v17
	v_add_f32_e32 v16, 1.0, v16
	v_add_f32_e32 v17, 1.0, v17
	v_rcp_f32_e32 v16, v16
	v_rcp_f32_e32 v17, v17
	s_nop 0
	v_pk_mul_f32 v[12:13], v[12:13], v[16:17]
	s_nop 0
	v_pk_mul_f32 v[8:9], v[8:9], v[12:13]
	v_pk_mul_f32 v[12:13], v[14:15], v[146:147] op_sel_hi:[1,0]
	s_nop 0
	v_mul_f32_e32 v14, 0xbfb8aa3b, v12
	v_mul_f32_e32 v15, 0xbfb8aa3b, v13
	v_exp_f32_e32 v14, v14
	v_exp_f32_e32 v15, v15
	v_add_f32_e32 v14, 1.0, v14
	v_add_f32_e32 v15, 1.0, v15
	v_rcp_f32_e32 v14, v14
	v_rcp_f32_e32 v15, v15
	s_nop 0
	v_pk_mul_f32 v[12:13], v[12:13], v[14:15]
	s_nop 0
	v_pk_mul_f32 v[10:11], v[10:11], v[12:13]
	v_mul_f32_e32 v12, 0xbfb8aa3b, v4
	v_mul_f32_e32 v13, 0xbfb8aa3b, v5
	v_exp_f32_e32 v12, v12
	v_exp_f32_e32 v13, v13
	v_add_f32_e32 v12, 1.0, v12
	v_add_f32_e32 v13, 1.0, v13
	v_rcp_f32_e32 v12, v12
	v_rcp_f32_e32 v13, v13
	s_nop 0
	v_pk_mul_f32 v[4:5], v[4:5], v[12:13]
	s_nop 0
	v_pk_mul_f32 v[4:5], v[0:1], v[4:5]
	v_pk_mul_f32 v[0:1], v[6:7], v[146:147] op_sel_hi:[1,0]
	v_add_u32_e32 v12, 0xb0, v144
	v_mul_f32_e32 v6, 0xbfb8aa3b, v0
	v_mul_f32_e32 v7, 0xbfb8aa3b, v1
	v_exp_f32_e32 v6, v6
	v_exp_f32_e32 v7, v7
	v_add_f32_e32 v6, 1.0, v6
	v_add_f32_e32 v7, 1.0, v7
	v_rcp_f32_e32 v6, v6
	v_rcp_f32_e32 v7, v7
	s_nop 0
	v_pk_mul_f32 v[0:1], v[0:1], v[6:7]
	s_nop 0
	v_pk_mul_f32 v[6:7], v[2:3], v[0:1]
	v_cvt_pk_bf16_f32 v2, v4, v5
	v_mad_i64_i32 v[4:5], s[6:7], v12, s75, v[148:149]
	v_cvt_pk_bf16_f32 v0, v8, v9
	v_cvt_pk_bf16_f32 v1, v10, v11
	v_cvt_pk_bf16_f32 v3, v6, v7
	s_mov_b64 s[6:7], -1
	global_store_dwordx4 v[4:5], v[0:3], off nt
	s_cbranch_vccnz .LBB0_107
	s_andn2_b64 vcc, exec, s[10:11]
	s_cbranch_vccnz .LBB0_106
	s_barrier
	s_branch .LBB0_106

.LBB0_546:
	ds_read_b128 v[144:147], v155
	ds_read_b128 v[148:151], v155 offset:1024
	ds_read_b128 v[160:163], v155 offset:2048
	ds_read_b128 v[164:167], v155 offset:3072
	ds_read_b128 v[168:171], v156
	ds_read_b128 v[172:175], v156 offset:1024
	ds_read_b128 v[176:179], v156 offset:2048
	ds_read_b128 v[180:183], v156 offset:3072
	s_add_u32 s19, s6, 0xfffc0080
	s_addc_u32 s20, s7, -1
	s_cmp_eq_u32 s18, 12
	s_cselect_b32 s89, s8, s20
	s_cselect_b32 s88, s9, s19
	s_cselect_b32 s43, s14, s17
	s_cselect_b32 s42, s15, s16
	s_add_i32 m0, s63, 0xc000
	ds_read_b128 v[186:189], v157
	ds_read_b128 v[190:193], v157 offset:1024
	ds_read_b128 v[194:197], v157 offset:2048
	ds_read_b128 v[198:201], v157 offset:3072
	ds_read_b128 v[202:205], v157 offset:4096
	ds_read_b128 v[206:209], v157 offset:5120
	ds_read_b128 v[210:213], v157 offset:6144
	ds_read_b128 v[214:217], v157 offset:7168
	global_load_lds_dwordx4 v136, s[6:7]
	s_add_i32 m0, s63, 0xe000
	s_nop 0
	global_load_lds_dwordx4 v138, s[6:7]
	s_waitcnt vmcnt(8)
	s_waitcnt lgkmcnt(0)
	s_barrier
	s_waitcnt lgkmcnt(0)
	v_mfma_f32_16x16x32_bf16 v[124:127], v[144:147], v[186:189], v[124:127]
	v_mfma_f32_16x16x32_bf16 v[120:123], v[160:163], v[186:189], v[120:123]
	v_mfma_f32_16x16x32_bf16 v[108:111], v[144:147], v[194:197], v[108:111]
	v_mfma_f32_16x16x32_bf16 v[104:107], v[160:163], v[194:197], v[104:107]
	v_mfma_f32_16x16x32_bf16 v[92:95], v[144:147], v[202:205], v[92:95]
	v_mfma_f32_16x16x32_bf16 v[88:91], v[160:163], v[202:205], v[88:91]
	v_mfma_f32_16x16x32_bf16 v[76:79], v[144:147], v[210:213], v[76:79]
	v_mfma_f32_16x16x32_bf16 v[72:75], v[160:163], v[210:213], v[72:75]
	v_mfma_f32_16x16x32_bf16 v[124:127], v[148:151], v[190:193], v[124:127]
	v_mfma_f32_16x16x32_bf16 v[120:123], v[164:167], v[190:193], v[120:123]
	v_mfma_f32_16x16x32_bf16 v[108:111], v[148:151], v[198:201], v[108:111]
	v_mfma_f32_16x16x32_bf16 v[104:107], v[164:167], v[198:201], v[104:107]
	v_mfma_f32_16x16x32_bf16 v[92:95], v[148:151], v[206:209], v[92:95]
	v_mfma_f32_16x16x32_bf16 v[88:91], v[164:167], v[206:209], v[88:91]
	v_mfma_f32_16x16x32_bf16 v[76:79], v[148:151], v[214:217], v[76:79]
	v_mfma_f32_16x16x32_bf16 v[72:75], v[164:167], v[214:217], v[72:75]
	v_mfma_f32_16x16x32_bf16 v[116:119], v[168:171], v[186:189], v[116:119]
	v_mfma_f32_16x16x32_bf16 v[112:115], v[176:179], v[186:189], v[112:115]
	v_mfma_f32_16x16x32_bf16 v[100:103], v[168:171], v[194:197], v[100:103]
	v_mfma_f32_16x16x32_bf16 v[96:99], v[176:179], v[194:197], v[96:99]
	v_mfma_f32_16x16x32_bf16 v[84:87], v[168:171], v[202:205], v[84:87]
	v_mfma_f32_16x16x32_bf16 v[80:83], v[176:179], v[202:205], v[80:83]
	v_mfma_f32_16x16x32_bf16 v[68:71], v[168:171], v[210:213], v[68:71]
	v_mfma_f32_16x16x32_bf16 v[64:67], v[176:179], v[210:213], v[64:67]
	v_mfma_f32_16x16x32_bf16 v[116:119], v[172:175], v[190:193], v[116:119]
	v_mfma_f32_16x16x32_bf16 v[112:115], v[180:183], v[190:193], v[112:115]
	v_mfma_f32_16x16x32_bf16 v[100:103], v[172:175], v[198:201], v[100:103]
	v_mfma_f32_16x16x32_bf16 v[96:99], v[180:183], v[198:201], v[96:99]
	v_mfma_f32_16x16x32_bf16 v[84:87], v[172:175], v[206:209], v[84:87]
	v_mfma_f32_16x16x32_bf16 v[80:83], v[180:183], v[206:209], v[80:83]
	v_mfma_f32_16x16x32_bf16 v[68:71], v[172:175], v[214:217], v[68:71]
	v_mfma_f32_16x16x32_bf16 v[64:67], v[180:183], v[214:217], v[64:67]
	s_barrier
	s_add_i32 s19, s72, s62
	s_mov_b32 m0, s19
	ds_read_b128 v[186:189], v157 offset:16384
	ds_read_b128 v[190:193], v157 offset:17408
	ds_read_b128 v[194:197], v157 offset:18432
	ds_read_b128 v[198:201], v157 offset:19456
	ds_read_b128 v[202:205], v157 offset:20480
	ds_read_b128 v[206:209], v157 offset:21504
	ds_read_b128 v[210:213], v157 offset:22528
	ds_read_b128 v[214:217], v157 offset:23552
	global_load_lds_dwordx4 v130, s[42:43]
	s_add_i32 m0, s19, 0x2000
	s_add_u32 s20, s42, 0x40000
	s_addc_u32 s21, s43, 0
	s_add_i32 s19, s73, s62
	global_load_lds_dwordx4 v134, s[42:43]
	s_mov_b32 m0, s19
	global_load_lds_dwordx4 v130, s[20:21]
	s_add_i32 m0, s19, 0x2000
	s_nop 0
	global_load_lds_dwordx4 v134, s[20:21]
	s_mov_b32 m0, s63
	s_nop 0
	global_load_lds_dwordx4 v128, s[88:89]
	s_mov_b32 m0, s64
	s_nop 0
	global_load_lds_dwordx4 v132, s[88:89]
	s_add_u32 s98, s42, s28
	s_addc_u32 s99, s43, s29
	s_add_u32 s100, s88, s28
	s_addc_u32 s101, s89, s29
	s_waitcnt vmcnt(8)
	s_waitcnt lgkmcnt(0)
	s_barrier
	s_waitcnt lgkmcnt(0)
	v_mfma_f32_16x16x32_bf16 v[60:63], v[144:147], v[186:189], v[60:63]
	v_mfma_f32_16x16x32_bf16 v[56:59], v[160:163], v[186:189], v[56:59]
	v_mfma_f32_16x16x32_bf16 v[44:47], v[144:147], v[194:197], v[44:47]
	v_mfma_f32_16x16x32_bf16 v[40:43], v[160:163], v[194:197], v[40:43]
	v_mfma_f32_16x16x32_bf16 v[28:31], v[144:147], v[202:205], v[28:31]
	v_mfma_f32_16x16x32_bf16 v[24:27], v[160:163], v[202:205], v[24:27]
	v_mfma_f32_16x16x32_bf16 v[12:15], v[144:147], v[210:213], v[12:15]
	v_mfma_f32_16x16x32_bf16 v[8:11], v[160:163], v[210:213], v[8:11]
	v_mfma_f32_16x16x32_bf16 v[60:63], v[148:151], v[190:193], v[60:63]
	v_mfma_f32_16x16x32_bf16 v[56:59], v[164:167], v[190:193], v[56:59]
	v_mfma_f32_16x16x32_bf16 v[44:47], v[148:151], v[198:201], v[44:47]
	v_mfma_f32_16x16x32_bf16 v[40:43], v[164:167], v[198:201], v[40:43]
	v_mfma_f32_16x16x32_bf16 v[28:31], v[148:151], v[206:209], v[28:31]
	v_mfma_f32_16x16x32_bf16 v[24:27], v[164:167], v[206:209], v[24:27]
	v_mfma_f32_16x16x32_bf16 v[12:15], v[148:151], v[214:217], v[12:15]
	v_mfma_f32_16x16x32_bf16 v[8:11], v[164:167], v[214:217], v[8:11]
	v_mfma_f32_16x16x32_bf16 v[52:55], v[168:171], v[186:189], v[52:55]
	v_mfma_f32_16x16x32_bf16 v[48:51], v[176:179], v[186:189], v[48:51]
	v_mfma_f32_16x16x32_bf16 v[36:39], v[168:171], v[194:197], v[36:39]
	v_mfma_f32_16x16x32_bf16 v[32:35], v[176:179], v[194:197], v[32:35]
	v_mfma_f32_16x16x32_bf16 v[20:23], v[168:171], v[202:205], v[20:23]
	v_mfma_f32_16x16x32_bf16 v[16:19], v[176:179], v[202:205], v[16:19]
	v_mfma_f32_16x16x32_bf16 v[4:7], v[168:171], v[210:213], v[4:7]
	v_mfma_f32_16x16x32_bf16 v[0:3], v[176:179], v[210:213], v[0:3]
	v_mfma_f32_16x16x32_bf16 v[52:55], v[172:175], v[190:193], v[52:55]
	v_mfma_f32_16x16x32_bf16 v[48:51], v[180:183], v[190:193], v[48:51]
	v_mfma_f32_16x16x32_bf16 v[36:39], v[172:175], v[198:201], v[36:39]
	v_mfma_f32_16x16x32_bf16 v[32:35], v[180:183], v[198:201], v[32:35]
	v_mfma_f32_16x16x32_bf16 v[20:23], v[172:175], v[206:209], v[20:23]
	v_mfma_f32_16x16x32_bf16 v[16:19], v[180:183], v[206:209], v[16:19]
	v_mfma_f32_16x16x32_bf16 v[4:7], v[172:175], v[214:217], v[4:7]
	v_mfma_f32_16x16x32_bf16 v[0:3], v[180:183], v[214:217], v[0:3]
	s_barrier
	s_add_i32 s19, 0, 0x18000
	v_add_u32_e32 v159, s19, v153
	s_add_i32 s22, 0, 0x1c000
	ds_read_b128 v[144:147], v159
	ds_read_b128 v[148:151], v159 offset:1024
	ds_read_b128 v[160:163], v159 offset:2048
	ds_read_b128 v[164:167], v159 offset:3072
	v_add_u32_e32 v159, s22, v153
	ds_read_b128 v[168:171], v159
	ds_read_b128 v[172:175], v159 offset:1024
	ds_read_b128 v[176:179], v159 offset:2048
	ds_read_b128 v[180:183], v159 offset:3072
	s_add_u32 s20, s88, 0x40000
	s_addc_u32 s21, s89, 0
	s_mov_b32 m0, s65
	ds_read_b128 v[186:189], v157 offset:32768
	ds_read_b128 v[190:193], v157 offset:33792
	ds_read_b128 v[194:197], v157 offset:34816
	ds_read_b128 v[198:201], v157 offset:35840
	ds_read_b128 v[202:205], v157 offset:36864
	ds_read_b128 v[206:209], v157 offset:37888
	ds_read_b128 v[210:213], v157 offset:38912
	ds_read_b128 v[214:217], v157 offset:39936
	global_load_lds_dwordx4 v128, s[20:21]
	s_mov_b32 m0, s66
	s_nop 0
	global_load_lds_dwordx4 v132, s[20:21]
	s_waitcnt vmcnt(8)
	s_waitcnt lgkmcnt(0)
	s_barrier
	s_waitcnt lgkmcnt(0)
	v_mfma_f32_16x16x32_bf16 v[124:127], v[144:147], v[186:189], v[124:127]
	v_mfma_f32_16x16x32_bf16 v[120:123], v[160:163], v[186:189], v[120:123]
	v_mfma_f32_16x16x32_bf16 v[108:111], v[144:147], v[194:197], v[108:111]
	v_mfma_f32_16x16x32_bf16 v[104:107], v[160:163], v[194:197], v[104:107]
	v_mfma_f32_16x16x32_bf16 v[92:95], v[144:147], v[202:205], v[92:95]
	v_mfma_f32_16x16x32_bf16 v[88:91], v[160:163], v[202:205], v[88:91]
	v_mfma_f32_16x16x32_bf16 v[76:79], v[144:147], v[210:213], v[76:79]
	v_mfma_f32_16x16x32_bf16 v[72:75], v[160:163], v[210:213], v[72:75]
	v_mfma_f32_16x16x32_bf16 v[124:127], v[148:151], v[190:193], v[124:127]
	v_mfma_f32_16x16x32_bf16 v[120:123], v[164:167], v[190:193], v[120:123]
	v_mfma_f32_16x16x32_bf16 v[108:111], v[148:151], v[198:201], v[108:111]
	v_mfma_f32_16x16x32_bf16 v[104:107], v[164:167], v[198:201], v[104:107]
	v_mfma_f32_16x16x32_bf16 v[92:95], v[148:151], v[206:209], v[92:95]
	v_mfma_f32_16x16x32_bf16 v[88:91], v[164:167], v[206:209], v[88:91]
	v_mfma_f32_16x16x32_bf16 v[76:79], v[148:151], v[214:217], v[76:79]
	v_mfma_f32_16x16x32_bf16 v[72:75], v[164:167], v[214:217], v[72:75]
	v_mfma_f32_16x16x32_bf16 v[116:119], v[168:171], v[186:189], v[116:119]
	v_mfma_f32_16x16x32_bf16 v[112:115], v[176:179], v[186:189], v[112:115]
	v_mfma_f32_16x16x32_bf16 v[100:103], v[168:171], v[194:197], v[100:103]
	v_mfma_f32_16x16x32_bf16 v[96:99], v[176:179], v[194:197], v[96:99]
	v_mfma_f32_16x16x32_bf16 v[84:87], v[168:171], v[202:205], v[84:87]
	v_mfma_f32_16x16x32_bf16 v[80:83], v[176:179], v[202:205], v[80:83]
	v_mfma_f32_16x16x32_bf16 v[68:71], v[168:171], v[210:213], v[68:71]
	v_mfma_f32_16x16x32_bf16 v[64:67], v[176:179], v[210:213], v[64:67]
	v_mfma_f32_16x16x32_bf16 v[116:119], v[172:175], v[190:193], v[116:119]
	v_mfma_f32_16x16x32_bf16 v[112:115], v[180:183], v[190:193], v[112:115]
	v_mfma_f32_16x16x32_bf16 v[100:103], v[172:175], v[198:201], v[100:103]
	v_mfma_f32_16x16x32_bf16 v[96:99], v[180:183], v[198:201], v[96:99]
	v_mfma_f32_16x16x32_bf16 v[84:87], v[172:175], v[206:209], v[84:87]
	v_mfma_f32_16x16x32_bf16 v[80:83], v[180:183], v[206:209], v[80:83]
	v_mfma_f32_16x16x32_bf16 v[68:71], v[172:175], v[214:217], v[68:71]
	v_mfma_f32_16x16x32_bf16 v[64:67], v[180:183], v[214:217], v[64:67]
	s_barrier
	s_add_i32 s19, s19, s62
	s_mov_b32 m0, s19
	ds_read_b128 v[186:189], v157 offset:49152
	ds_read_b128 v[190:193], v157 offset:50176
	ds_read_b128 v[194:197], v157 offset:51200
	ds_read_b128 v[198:201], v157 offset:52224
	ds_read_b128 v[202:205], v157 offset:53248
	ds_read_b128 v[206:209], v157 offset:54272
	ds_read_b128 v[210:213], v157 offset:55296
	ds_read_b128 v[214:217], v157 offset:56320
	global_load_lds_dwordx4 v130, s[98:99]
	s_add_i32 m0, s19, 0x2000
	s_add_u32 s20, s42, 0x40080
	s_addc_u32 s21, s43, 0
	s_add_i32 s19, s22, s62
	global_load_lds_dwordx4 v134, s[98:99]
	s_mov_b32 m0, s19
	s_nop 0
	global_load_lds_dwordx4 v130, s[20:21]
	s_add_i32 m0, s19, 0x2000
	s_nop 0
	global_load_lds_dwordx4 v134, s[20:21]
	s_mov_b32 m0, s70
	s_nop 0
	global_load_lds_dwordx4 v128, s[100:101]
	s_mov_b32 m0, s71
	s_nop 0
	global_load_lds_dwordx4 v132, s[100:101]
	s_waitcnt vmcnt(8)
	s_waitcnt lgkmcnt(0)
	s_barrier
	s_waitcnt lgkmcnt(0)
	v_mfma_f32_16x16x32_bf16 v[60:63], v[144:147], v[186:189], v[60:63]
	v_mfma_f32_16x16x32_bf16 v[56:59], v[160:163], v[186:189], v[56:59]
	s_cmp_eq_u32 s18, 12
	s_cbranch_scc0 .Lrs_skip_546
	v_lshl_add_u32 v252, s80, 8, v152
	v_ashrrev_i32_e32 v253, 31, v252
	v_lshl_add_u64 v[254:255], v[252:253], 2, s[12:13]
	global_load_dword v243, v[254:255], off
	global_load_dword v244, v[254:255], off offset:64
	global_load_dword v245, v[254:255], off offset:128
	global_load_dword v246, v[254:255], off offset:192
	global_load_dword v247, v[254:255], off offset:512
	global_load_dword v248, v[254:255], off offset:576
	global_load_dword v249, v[254:255], off offset:640
	global_load_dword v250, v[254:255], off offset:704
.Lrs_skip_546:
	v_mfma_f32_16x16x32_bf16 v[44:47], v[144:147], v[194:197], v[44:47]
	v_mfma_f32_16x16x32_bf16 v[40:43], v[160:163], v[194:197], v[40:43]
	v_mfma_f32_16x16x32_bf16 v[28:31], v[144:147], v[202:205], v[28:31]
	v_mfma_f32_16x16x32_bf16 v[24:27], v[160:163], v[202:205], v[24:27]
	v_mfma_f32_16x16x32_bf16 v[12:15], v[144:147], v[210:213], v[12:15]
	v_mfma_f32_16x16x32_bf16 v[8:11], v[160:163], v[210:213], v[8:11]
	v_mfma_f32_16x16x32_bf16 v[60:63], v[148:151], v[190:193], v[60:63]
	v_mfma_f32_16x16x32_bf16 v[56:59], v[164:167], v[190:193], v[56:59]
	v_mfma_f32_16x16x32_bf16 v[44:47], v[148:151], v[198:201], v[44:47]
	v_mfma_f32_16x16x32_bf16 v[40:43], v[164:167], v[198:201], v[40:43]
	v_mfma_f32_16x16x32_bf16 v[28:31], v[148:151], v[206:209], v[28:31]
	v_mfma_f32_16x16x32_bf16 v[24:27], v[164:167], v[206:209], v[24:27]
	v_mfma_f32_16x16x32_bf16 v[12:15], v[148:151], v[214:217], v[12:15]
	v_mfma_f32_16x16x32_bf16 v[8:11], v[164:167], v[214:217], v[8:11]
	v_mfma_f32_16x16x32_bf16 v[52:55], v[168:171], v[186:189], v[52:55]
	v_mfma_f32_16x16x32_bf16 v[48:51], v[176:179], v[186:189], v[48:51]
	v_mfma_f32_16x16x32_bf16 v[36:39], v[168:171], v[194:197], v[36:39]
	v_mfma_f32_16x16x32_bf16 v[32:35], v[176:179], v[194:197], v[32:35]
	v_mfma_f32_16x16x32_bf16 v[20:23], v[168:171], v[202:205], v[20:23]
	v_mfma_f32_16x16x32_bf16 v[16:19], v[176:179], v[202:205], v[16:19]
	v_mfma_f32_16x16x32_bf16 v[4:7], v[168:171], v[210:213], v[4:7]
	v_mfma_f32_16x16x32_bf16 v[0:3], v[176:179], v[210:213], v[0:3]
	v_mfma_f32_16x16x32_bf16 v[52:55], v[172:175], v[190:193], v[52:55]
	v_mfma_f32_16x16x32_bf16 v[48:51], v[180:183], v[190:193], v[48:51]
	v_mfma_f32_16x16x32_bf16 v[36:39], v[172:175], v[198:201], v[36:39]
	v_mfma_f32_16x16x32_bf16 v[32:35], v[180:183], v[198:201], v[32:35]
	v_mfma_f32_16x16x32_bf16 v[20:23], v[172:175], v[206:209], v[20:23]
	v_mfma_f32_16x16x32_bf16 v[16:19], v[180:183], v[206:209], v[16:19]
	v_mfma_f32_16x16x32_bf16 v[4:7], v[172:175], v[214:217], v[4:7]
	v_mfma_f32_16x16x32_bf16 v[0:3], v[180:183], v[214:217], v[0:3]
	s_barrier
	s_add_i32 s18, s18, 2
	s_add_u32 s6, s6, 0x100
	s_addc_u32 s7, s7, 0
	s_add_u32 s16, s16, 0x100
	s_addc_u32 s17, s17, 0
	s_cmp_gt_u32 s18, 13
	s_cbranch_scc0 .LBB0_546
	s_and_b64 vcc, exec, s[30:31]
	s_cbranch_vccz .LBB0_549
	s_barrier
.LBB0_549:
	v_lshl_add_u32 v144, s80, 8, v152
	v_ashrrev_i32_e32 v145, 31, v144
	v_lshl_add_u64 v[146:147], v[144:145], 2, s[12:13]
	s_waitcnt vmcnt(0)
	v_mov_b32_e32 v148, v243
	v_mov_b32_e32 v165, v244
	v_mov_b32_e32 v164, v245
	v_mov_b32_e32 v163, v246
	v_mov_b32_e32 v162, v247
	v_mov_b32_e32 v161, v248
	v_mov_b32_e32 v160, v249
	v_mov_b32_e32 v159, v250
	s_cmp_gt_i32 s40, 3
	s_cselect_b64 s[42:43], -1, 0
	s_mov_b64 s[6:7], -1
	s_and_b64 vcc, exec, s[42:43]
	s_waitcnt vmcnt(0)
	v_fmamk_f32 v146, v148, 0x3a800000, v158
	v_rsq_f32_e32 v146, v146
	s_nop 0
	v_pk_mul_f32 v[148:149], v[126:127], v[146:147] op_sel_hi:[1,0]
	v_pk_mul_f32 v[150:151], v[124:125], v[146:147] op_sel_hi:[1,0]
	v_pk_mul_f32 v[124:125], v[122:123], v[146:147] op_sel_hi:[1,0]
	v_pk_mul_f32 v[126:127], v[120:121], v[146:147] op_sel_hi:[1,0]
	s_cbranch_vccz .LBB0_551
	v_cvt_pk_bf16_f32 v120, v150, v151
	v_cvt_pk_bf16_f32 v121, v148, v149
	v_cvt_pk_bf16_f32 v122, v126, v127
	s_mov_b64 s[6:7], 0

.LBB0_1115:
	ds_read_b128 v[144:147], v155
	ds_read_b128 v[160:163], v155 offset:1024
	ds_read_b128 v[164:167], v155 offset:2048
	ds_read_b128 v[168:171], v155 offset:3072
	ds_read_b128 v[172:175], v157
	ds_read_b128 v[176:179], v157 offset:1024
	ds_read_b128 v[180:183], v157 offset:2048
	ds_read_b128 v[186:189], v157 offset:3072
	s_add_u32 s40, s38, 0xfffc0080
	s_addc_u32 s41, s39, -1
	s_cmp_eq_u32 s70, 12
	s_cselect_b32 s43, s27, s41
	s_cselect_b32 s42, s64, s40
	s_cselect_b32 s41, s29, s67
	s_cselect_b32 s40, s65, s66
	s_add_i32 m0, s16, 0xc000
	ds_read_b128 v[190:193], v158
	ds_read_b128 v[194:197], v158 offset:1024
	ds_read_b128 v[198:201], v158 offset:2048
	ds_read_b128 v[202:205], v158 offset:3072
	ds_read_b128 v[206:209], v158 offset:4096
	ds_read_b128 v[210:213], v158 offset:5120
	ds_read_b128 v[214:217], v158 offset:6144
	ds_read_b128 v[218:221], v158 offset:7168
	global_load_lds_dwordx4 v136, s[38:39]
	s_add_i32 m0, s16, 0xe000
	s_nop 0
	global_load_lds_dwordx4 v138, s[38:39]
	s_waitcnt vmcnt(8)
	s_waitcnt lgkmcnt(0)
	s_barrier
	s_waitcnt lgkmcnt(0)
	v_mfma_f32_16x16x32_bf16 v[124:127], v[144:147], v[190:193], v[124:127]
	v_mfma_f32_16x16x32_bf16 v[120:123], v[164:167], v[190:193], v[120:123]
	v_mfma_f32_16x16x32_bf16 v[116:119], v[144:147], v[198:201], v[116:119]
	v_mfma_f32_16x16x32_bf16 v[104:107], v[164:167], v[198:201], v[104:107]
	v_mfma_f32_16x16x32_bf16 v[92:95], v[144:147], v[206:209], v[92:95]
	v_mfma_f32_16x16x32_bf16 v[88:91], v[164:167], v[206:209], v[88:91]
	v_mfma_f32_16x16x32_bf16 v[76:79], v[144:147], v[214:217], v[76:79]
	v_mfma_f32_16x16x32_bf16 v[72:75], v[164:167], v[214:217], v[72:75]
	v_mfma_f32_16x16x32_bf16 v[124:127], v[160:163], v[194:197], v[124:127]
	v_mfma_f32_16x16x32_bf16 v[120:123], v[168:171], v[194:197], v[120:123]
	v_mfma_f32_16x16x32_bf16 v[116:119], v[160:163], v[202:205], v[116:119]
	v_mfma_f32_16x16x32_bf16 v[104:107], v[168:171], v[202:205], v[104:107]
	v_mfma_f32_16x16x32_bf16 v[92:95], v[160:163], v[210:213], v[92:95]
	v_mfma_f32_16x16x32_bf16 v[88:91], v[168:171], v[210:213], v[88:91]
	v_mfma_f32_16x16x32_bf16 v[76:79], v[160:163], v[218:221], v[76:79]
	v_mfma_f32_16x16x32_bf16 v[72:75], v[168:171], v[218:221], v[72:75]
	v_mfma_f32_16x16x32_bf16 v[112:115], v[172:175], v[190:193], v[112:115]
	v_mfma_f32_16x16x32_bf16 v[108:111], v[180:183], v[190:193], v[108:111]
	v_mfma_f32_16x16x32_bf16 v[100:103], v[172:175], v[198:201], v[100:103]
	v_mfma_f32_16x16x32_bf16 v[96:99], v[180:183], v[198:201], v[96:99]
	v_mfma_f32_16x16x32_bf16 v[84:87], v[172:175], v[206:209], v[84:87]
	v_mfma_f32_16x16x32_bf16 v[80:83], v[180:183], v[206:209], v[80:83]
	v_mfma_f32_16x16x32_bf16 v[68:71], v[172:175], v[214:217], v[68:71]
	v_mfma_f32_16x16x32_bf16 v[64:67], v[180:183], v[214:217], v[64:67]
	v_mfma_f32_16x16x32_bf16 v[112:115], v[176:179], v[194:197], v[112:115]
	v_mfma_f32_16x16x32_bf16 v[108:111], v[186:189], v[194:197], v[108:111]
	v_mfma_f32_16x16x32_bf16 v[100:103], v[176:179], v[202:205], v[100:103]
	v_mfma_f32_16x16x32_bf16 v[96:99], v[186:189], v[202:205], v[96:99]
	v_mfma_f32_16x16x32_bf16 v[84:87], v[176:179], v[210:213], v[84:87]
	v_mfma_f32_16x16x32_bf16 v[80:83], v[186:189], v[210:213], v[80:83]
	v_mfma_f32_16x16x32_bf16 v[68:71], v[176:179], v[218:221], v[68:71]
	v_mfma_f32_16x16x32_bf16 v[64:67], v[186:189], v[218:221], v[64:67]
	s_barrier
	s_add_i32 s71, s60, s3
	s_mov_b32 m0, s71
	ds_read_b128 v[190:193], v158 offset:16384
	ds_read_b128 v[194:197], v158 offset:17408
	ds_read_b128 v[198:201], v158 offset:18432
	ds_read_b128 v[202:205], v158 offset:19456
	ds_read_b128 v[206:209], v158 offset:20480
	ds_read_b128 v[210:213], v158 offset:21504
	ds_read_b128 v[214:217], v158 offset:22528
	ds_read_b128 v[218:221], v158 offset:23552
	global_load_lds_dwordx4 v132, s[40:41]
	s_add_i32 m0, s71, 0x2000
	s_add_u32 s72, s40, 0x40000
	s_addc_u32 s73, s41, 0
	s_add_i32 s71, s61, s3
	global_load_lds_dwordx4 v128, s[40:41]
	s_mov_b32 m0, s71
	global_load_lds_dwordx4 v132, s[72:73]
	s_add_i32 m0, s71, 0x2000
	s_nop 0
	global_load_lds_dwordx4 v128, s[72:73]
	s_mov_b32 m0, s16
	s_nop 0
	global_load_lds_dwordx4 v134, s[42:43]
	s_mov_b32 m0, s17
	s_nop 0
	global_load_lds_dwordx4 v130, s[42:43]
	s_add_u32 s98, s40, s12
	s_addc_u32 s99, s41, s13
	s_add_u32 s100, s42, s12
	s_addc_u32 s101, s43, s13
	s_waitcnt vmcnt(8)
	s_waitcnt lgkmcnt(0)
	s_barrier
	s_waitcnt lgkmcnt(0)
	v_mfma_f32_16x16x32_bf16 v[60:63], v[144:147], v[190:193], v[60:63]
	v_mfma_f32_16x16x32_bf16 v[56:59], v[164:167], v[190:193], v[56:59]
	v_mfma_f32_16x16x32_bf16 v[44:47], v[144:147], v[198:201], v[44:47]
	v_mfma_f32_16x16x32_bf16 v[40:43], v[164:167], v[198:201], v[40:43]
	v_mfma_f32_16x16x32_bf16 v[28:31], v[144:147], v[206:209], v[28:31]
	v_mfma_f32_16x16x32_bf16 v[24:27], v[164:167], v[206:209], v[24:27]
	v_mfma_f32_16x16x32_bf16 v[12:15], v[144:147], v[214:217], v[12:15]
	v_mfma_f32_16x16x32_bf16 v[8:11], v[164:167], v[214:217], v[8:11]
	v_mfma_f32_16x16x32_bf16 v[60:63], v[160:163], v[194:197], v[60:63]
	v_mfma_f32_16x16x32_bf16 v[56:59], v[168:171], v[194:197], v[56:59]
	v_mfma_f32_16x16x32_bf16 v[44:47], v[160:163], v[202:205], v[44:47]
	v_mfma_f32_16x16x32_bf16 v[40:43], v[168:171], v[202:205], v[40:43]
	v_mfma_f32_16x16x32_bf16 v[28:31], v[160:163], v[210:213], v[28:31]
	v_mfma_f32_16x16x32_bf16 v[24:27], v[168:171], v[210:213], v[24:27]
	v_mfma_f32_16x16x32_bf16 v[12:15], v[160:163], v[218:221], v[12:15]
	v_mfma_f32_16x16x32_bf16 v[8:11], v[168:171], v[218:221], v[8:11]
	v_mfma_f32_16x16x32_bf16 v[52:55], v[172:175], v[190:193], v[52:55]
	v_mfma_f32_16x16x32_bf16 v[48:51], v[180:183], v[190:193], v[48:51]
	v_mfma_f32_16x16x32_bf16 v[36:39], v[172:175], v[198:201], v[36:39]
	v_mfma_f32_16x16x32_bf16 v[32:35], v[180:183], v[198:201], v[32:35]
	v_mfma_f32_16x16x32_bf16 v[20:23], v[172:175], v[206:209], v[20:23]
	v_mfma_f32_16x16x32_bf16 v[16:19], v[180:183], v[206:209], v[16:19]
	v_mfma_f32_16x16x32_bf16 v[4:7], v[172:175], v[214:217], v[4:7]
	v_mfma_f32_16x16x32_bf16 v[0:3], v[180:183], v[214:217], v[0:3]
	v_mfma_f32_16x16x32_bf16 v[52:55], v[176:179], v[194:197], v[52:55]
	v_mfma_f32_16x16x32_bf16 v[48:51], v[186:189], v[194:197], v[48:51]
	v_mfma_f32_16x16x32_bf16 v[36:39], v[176:179], v[202:205], v[36:39]
	v_mfma_f32_16x16x32_bf16 v[32:35], v[186:189], v[202:205], v[32:35]
	v_mfma_f32_16x16x32_bf16 v[20:23], v[176:179], v[210:213], v[20:23]
	v_mfma_f32_16x16x32_bf16 v[16:19], v[186:189], v[210:213], v[16:19]
	v_mfma_f32_16x16x32_bf16 v[4:7], v[176:179], v[218:221], v[4:7]
	v_mfma_f32_16x16x32_bf16 v[0:3], v[186:189], v[218:221], v[0:3]
	s_barrier
	s_add_i32 s71, 0, 0x18000
	v_add_u32_e32 v148, s71, v151
	s_add_i32 s72, 0, 0x1c000
	ds_read_b128 v[144:147], v148
	ds_read_b128 v[160:163], v148 offset:1024
	ds_read_b128 v[164:167], v148 offset:2048
	ds_read_b128 v[168:171], v148 offset:3072
	v_add_u32_e32 v148, s72, v151
	ds_read_b128 v[172:175], v148
	ds_read_b128 v[176:179], v148 offset:1024
	ds_read_b128 v[180:183], v148 offset:2048
	ds_read_b128 v[186:189], v148 offset:3072
	s_add_u32 s42, s42, 0x40000
	s_addc_u32 s43, s43, 0
	s_mov_b32 m0, s18
	ds_read_b128 v[190:193], v158 offset:32768
	ds_read_b128 v[194:197], v158 offset:33792
	ds_read_b128 v[198:201], v158 offset:34816
	ds_read_b128 v[202:205], v158 offset:35840
	ds_read_b128 v[206:209], v158 offset:36864
	ds_read_b128 v[210:213], v158 offset:37888
	ds_read_b128 v[214:217], v158 offset:38912
	ds_read_b128 v[218:221], v158 offset:39936
	global_load_lds_dwordx4 v134, s[42:43]
	s_mov_b32 m0, s19
	s_nop 0
	global_load_lds_dwordx4 v130, s[42:43]
	s_waitcnt vmcnt(8)
	s_waitcnt lgkmcnt(0)
	s_barrier
	s_waitcnt lgkmcnt(0)
	v_mfma_f32_16x16x32_bf16 v[124:127], v[144:147], v[190:193], v[124:127]
	v_mfma_f32_16x16x32_bf16 v[120:123], v[164:167], v[190:193], v[120:123]
	v_mfma_f32_16x16x32_bf16 v[116:119], v[144:147], v[198:201], v[116:119]
	v_mfma_f32_16x16x32_bf16 v[104:107], v[164:167], v[198:201], v[104:107]
	v_mfma_f32_16x16x32_bf16 v[92:95], v[144:147], v[206:209], v[92:95]
	v_mfma_f32_16x16x32_bf16 v[88:91], v[164:167], v[206:209], v[88:91]
	v_mfma_f32_16x16x32_bf16 v[76:79], v[144:147], v[214:217], v[76:79]
	v_mfma_f32_16x16x32_bf16 v[72:75], v[164:167], v[214:217], v[72:75]
	v_mfma_f32_16x16x32_bf16 v[124:127], v[160:163], v[194:197], v[124:127]
	v_mfma_f32_16x16x32_bf16 v[120:123], v[168:171], v[194:197], v[120:123]
	v_mfma_f32_16x16x32_bf16 v[116:119], v[160:163], v[202:205], v[116:119]
	v_mfma_f32_16x16x32_bf16 v[104:107], v[168:171], v[202:205], v[104:107]
	v_mfma_f32_16x16x32_bf16 v[92:95], v[160:163], v[210:213], v[92:95]
	v_mfma_f32_16x16x32_bf16 v[88:91], v[168:171], v[210:213], v[88:91]
	v_mfma_f32_16x16x32_bf16 v[76:79], v[160:163], v[218:221], v[76:79]
	v_mfma_f32_16x16x32_bf16 v[72:75], v[168:171], v[218:221], v[72:75]
	v_mfma_f32_16x16x32_bf16 v[112:115], v[172:175], v[190:193], v[112:115]
	v_mfma_f32_16x16x32_bf16 v[108:111], v[180:183], v[190:193], v[108:111]
	v_mfma_f32_16x16x32_bf16 v[100:103], v[172:175], v[198:201], v[100:103]
	v_mfma_f32_16x16x32_bf16 v[96:99], v[180:183], v[198:201], v[96:99]
	v_mfma_f32_16x16x32_bf16 v[84:87], v[172:175], v[206:209], v[84:87]
	v_mfma_f32_16x16x32_bf16 v[80:83], v[180:183], v[206:209], v[80:83]
	v_mfma_f32_16x16x32_bf16 v[68:71], v[172:175], v[214:217], v[68:71]
	v_mfma_f32_16x16x32_bf16 v[64:67], v[180:183], v[214:217], v[64:67]
	v_mfma_f32_16x16x32_bf16 v[112:115], v[176:179], v[194:197], v[112:115]
	v_mfma_f32_16x16x32_bf16 v[108:111], v[186:189], v[194:197], v[108:111]
	v_mfma_f32_16x16x32_bf16 v[100:103], v[176:179], v[202:205], v[100:103]
	v_mfma_f32_16x16x32_bf16 v[96:99], v[186:189], v[202:205], v[96:99]
	v_mfma_f32_16x16x32_bf16 v[84:87], v[176:179], v[210:213], v[84:87]
	v_mfma_f32_16x16x32_bf16 v[80:83], v[186:189], v[210:213], v[80:83]
	v_mfma_f32_16x16x32_bf16 v[68:71], v[176:179], v[218:221], v[68:71]
	v_mfma_f32_16x16x32_bf16 v[64:67], v[186:189], v[218:221], v[64:67]
	s_barrier
	s_add_i32 s42, s71, s3
	s_mov_b32 m0, s42
	ds_read_b128 v[190:193], v158 offset:49152
	ds_read_b128 v[194:197], v158 offset:50176
	ds_read_b128 v[198:201], v158 offset:51200
	ds_read_b128 v[202:205], v158 offset:52224
	ds_read_b128 v[206:209], v158 offset:53248
	ds_read_b128 v[210:213], v158 offset:54272
	ds_read_b128 v[214:217], v158 offset:55296
	ds_read_b128 v[218:221], v158 offset:56320
	global_load_lds_dwordx4 v132, s[98:99]
	s_add_i32 m0, s42, 0x2000
	s_add_u32 s40, s40, 0x40080
	s_addc_u32 s41, s41, 0
	s_add_i32 s42, s72, s3
	global_load_lds_dwordx4 v128, s[98:99]
	s_mov_b32 m0, s42
	s_nop 0
	global_load_lds_dwordx4 v132, s[40:41]
	s_add_i32 m0, s42, 0x2000
	s_nop 0
	global_load_lds_dwordx4 v128, s[40:41]
	s_mov_b32 m0, s21
	s_nop 0
	global_load_lds_dwordx4 v134, s[100:101]
	s_mov_b32 m0, s22
	s_nop 0
	global_load_lds_dwordx4 v130, s[100:101]
	s_waitcnt vmcnt(8)
	s_waitcnt lgkmcnt(0)
	s_barrier
	s_waitcnt lgkmcnt(0)
	v_mfma_f32_16x16x32_bf16 v[60:63], v[144:147], v[190:193], v[60:63]
	v_mfma_f32_16x16x32_bf16 v[56:59], v[164:167], v[190:193], v[56:59]
	s_cmp_eq_u32 s70, 12
	s_cbranch_scc0 .Lrs_skip_1115
	v_lshl_add_u32 v252, s36, 8, v149
	v_ashrrev_i32_e32 v253, 31, v252
	v_lshl_add_u64 v[254:255], v[252:253], 2, s[10:11]
	global_load_dword v243, v[254:255], off
	global_load_dword v244, v[254:255], off offset:64
	global_load_dword v245, v[254:255], off offset:128
	global_load_dword v246, v[254:255], off offset:192
	global_load_dword v247, v[254:255], off offset:512
	global_load_dword v248, v[254:255], off offset:576
	global_load_dword v249, v[254:255], off offset:640
	global_load_dword v250, v[254:255], off offset:704
.Lrs_skip_1115:
	v_mfma_f32_16x16x32_bf16 v[44:47], v[144:147], v[198:201], v[44:47]
	v_mfma_f32_16x16x32_bf16 v[40:43], v[164:167], v[198:201], v[40:43]
	v_mfma_f32_16x16x32_bf16 v[28:31], v[144:147], v[206:209], v[28:31]
	v_mfma_f32_16x16x32_bf16 v[24:27], v[164:167], v[206:209], v[24:27]
	v_mfma_f32_16x16x32_bf16 v[12:15], v[144:147], v[214:217], v[12:15]
	v_mfma_f32_16x16x32_bf16 v[8:11], v[164:167], v[214:217], v[8:11]
	v_mfma_f32_16x16x32_bf16 v[60:63], v[160:163], v[194:197], v[60:63]
	v_mfma_f32_16x16x32_bf16 v[56:59], v[168:171], v[194:197], v[56:59]
	v_mfma_f32_16x16x32_bf16 v[44:47], v[160:163], v[202:205], v[44:47]
	v_mfma_f32_16x16x32_bf16 v[40:43], v[168:171], v[202:205], v[40:43]
	v_mfma_f32_16x16x32_bf16 v[28:31], v[160:163], v[210:213], v[28:31]
	v_mfma_f32_16x16x32_bf16 v[24:27], v[168:171], v[210:213], v[24:27]
	v_mfma_f32_16x16x32_bf16 v[12:15], v[160:163], v[218:221], v[12:15]
	v_mfma_f32_16x16x32_bf16 v[8:11], v[168:171], v[218:221], v[8:11]
	v_mfma_f32_16x16x32_bf16 v[52:55], v[172:175], v[190:193], v[52:55]
	v_mfma_f32_16x16x32_bf16 v[48:51], v[180:183], v[190:193], v[48:51]
	v_mfma_f32_16x16x32_bf16 v[36:39], v[172:175], v[198:201], v[36:39]
	v_mfma_f32_16x16x32_bf16 v[32:35], v[180:183], v[198:201], v[32:35]
	v_mfma_f32_16x16x32_bf16 v[20:23], v[172:175], v[206:209], v[20:23]
	v_mfma_f32_16x16x32_bf16 v[16:19], v[180:183], v[206:209], v[16:19]
	v_mfma_f32_16x16x32_bf16 v[4:7], v[172:175], v[214:217], v[4:7]
	v_mfma_f32_16x16x32_bf16 v[0:3], v[180:183], v[214:217], v[0:3]
	v_mfma_f32_16x16x32_bf16 v[52:55], v[176:179], v[194:197], v[52:55]
	v_mfma_f32_16x16x32_bf16 v[48:51], v[186:189], v[194:197], v[48:51]
	v_mfma_f32_16x16x32_bf16 v[36:39], v[176:179], v[202:205], v[36:39]
	v_mfma_f32_16x16x32_bf16 v[32:35], v[186:189], v[202:205], v[32:35]
	v_mfma_f32_16x16x32_bf16 v[20:23], v[176:179], v[210:213], v[20:23]
	v_mfma_f32_16x16x32_bf16 v[16:19], v[186:189], v[210:213], v[16:19]
	v_mfma_f32_16x16x32_bf16 v[4:7], v[176:179], v[218:221], v[4:7]
	v_mfma_f32_16x16x32_bf16 v[0:3], v[186:189], v[218:221], v[0:3]
	s_barrier
	s_add_i32 s70, s70, 2
	s_add_u32 s38, s38, 0x100
	s_addc_u32 s39, s39, 0
	s_add_u32 s66, s66, 0x100
	s_addc_u32 s67, s67, 0
	s_cmp_gt_u32 s70, 13
	s_cbranch_scc0 .LBB0_1115
	s_and_b64 vcc, exec, s[24:25]
	s_cbranch_vccz .LBB0_1118
	s_barrier
.LBB0_1118:
	v_lshl_add_u32 v144, s36, 8, v149
	v_ashrrev_i32_e32 v145, 31, v144
	v_lshl_add_u64 v[146:147], v[144:145], 2, s[10:11]
	s_waitcnt vmcnt(0)
	v_mov_b32_e32 v145, v243
	v_mov_b32_e32 v148, v244
	v_mov_b32_e32 v150, v245
	v_mov_b32_e32 v152, v246
	v_mov_b32_e32 v154, v247
	v_mov_b32_e32 v156, v248
	v_mov_b32_e32 v162, v249
	v_mov_b32_e32 v163, v250
	v_lshl_or_b32 v146, s63, 7, v153
	v_ashrrev_i32_e32 v147, 31, v146
	v_lshl_add_u64 v[146:147], v[146:147], 1, s[68:69]
	v_mad_i64_i32 v[160:161], s[38:39], v144, s62, v[146:147]
	s_andn2_b64 vcc, exec, s[4:5]
	s_mov_b64 s[4:5], -1
	s_waitcnt vmcnt(0)
	v_fmamk_f32 v145, v145, 0x3a800000, v159
	v_fmamk_f32 v148, v148, 0x3a800000, v159
	v_rsq_f32_e32 v164, v148
	v_fmamk_f32 v150, v150, 0x3a800000, v159
	v_fmamk_f32 v152, v152, 0x3a800000, v159
	v_fmamk_f32 v165, v156, 0x3a800000, v159
	v_fmamk_f32 v167, v162, 0x3a800000, v159
	v_rsq_f32_e32 v162, v145
	v_fmamk_f32 v163, v163, 0x3a800000, v159
	v_rsq_f32_e32 v166, v150
	v_rsq_f32_e32 v156, v152
	v_pk_mul_f32 v[124:125], v[124:125], v[162:163] op_sel_hi:[1,0]
	v_pk_mul_f32 v[126:127], v[126:127], v[162:163] op_sel_hi:[1,0]
	v_pk_mul_f32 v[120:121], v[120:121], v[162:163] op_sel_hi:[1,0]
	v_pk_mul_f32 v[122:123], v[122:123], v[162:163] op_sel_hi:[1,0]
	v_rsq_f32_e32 v152, v165
	v_rsq_f32_e32 v150, v167
	v_rsq_f32_e32 v148, v163
	v_pk_mul_f32 v[112:113], v[112:113], v[162:163] op_sel_hi:[1,0]
	v_pk_mul_f32 v[114:115], v[114:115], v[162:163] op_sel_hi:[1,0]
	v_pk_mul_f32 v[108:109], v[108:109], v[162:163] op_sel_hi:[1,0]
	v_pk_mul_f32 v[110:111], v[110:111], v[162:163] op_sel_hi:[1,0]
	v_pk_mul_f32 v[116:117], v[116:117], v[164:165] op_sel_hi:[1,0]
	v_pk_mul_f32 v[100:101], v[100:101], v[164:165] op_sel_hi:[1,0]
	v_pk_mul_f32 v[118:119], v[118:119], v[164:165] op_sel_hi:[1,0]
	v_mul_f32_e32 v145, 0xbfb8aa3b, v124
	v_mul_f32_e32 v162, 0xbfb8aa3b, v125
	v_mul_f32_e32 v163, 0xbfb8aa3b, v126
	v_mul_f32_e32 v165, 0xbfb8aa3b, v127
	v_mul_f32_e32 v167, 0xbfb8aa3b, v120
	v_mul_f32_e32 v168, 0xbfb8aa3b, v121
	v_mul_f32_e32 v169, 0xbfb8aa3b, v122
	v_mul_f32_e32 v170, 0xbfb8aa3b, v123
	v_mul_f32_e32 v171, 0xbfb8aa3b, v116
	v_mul_f32_e32 v172, 0xbfb8aa3b, v117
	v_mul_f32_e32 v173, 0xbfb8aa3b, v118
	v_exp_f32_e32 v145, v145
	v_exp_f32_e32 v162, v162
	v_exp_f32_e32 v163, v163
	v_exp_f32_e32 v165, v165
	v_exp_f32_e32 v167, v167
	v_exp_f32_e32 v168, v168
	v_exp_f32_e32 v169, v169
	v_exp_f32_e32 v170, v170
	v_exp_f32_e32 v171, v171
	v_exp_f32_e32 v172, v172
	v_exp_f32_e32 v173, v173
	v_add_f32_e32 v145, 1.0, v145
	v_add_f32_e32 v175, 1.0, v162
	v_add_f32_e32 v176, 1.0, v163
	v_add_f32_e32 v165, 1.0, v165
	v_add_f32_e32 v167, 1.0, v167
	v_add_f32_e32 v177, 1.0, v168
	v_add_f32_e32 v178, 1.0, v169
	v_add_f32_e32 v179, 1.0, v170
	v_mul_f32_e32 v174, 0xbfb8aa3b, v119
	v_add_f32_e32 v180, 1.0, v171
	v_add_f32_e32 v181, 1.0, v172
	v_add_f32_e32 v182, 1.0, v173
	v_rcp_f32_e32 v162, v145
	v_rcp_f32_e32 v163, v175
	v_rcp_f32_e32 v168, v176
	v_rcp_f32_e32 v169, v165
	v_rcp_f32_e32 v170, v167
	v_rcp_f32_e32 v171, v177
	v_rcp_f32_e32 v172, v178
	v_rcp_f32_e32 v173, v179
	v_exp_f32_e32 v174, v174
	v_pk_mul_f32 v[124:125], v[124:125], v[162:163]
	v_pk_mul_f32 v[126:127], v[126:127], v[168:169]
	v_pk_mul_f32 v[120:121], v[120:121], v[170:171]
	v_pk_mul_f32 v[122:123], v[122:123], v[172:173]
	v_add_f32_e32 v183, 1.0, v174
	v_rcp_f32_e32 v174, v180
	v_rcp_f32_e32 v175, v181
	v_pk_mul_f32 v[112:113], v[112:113], v[124:125]
	v_pk_mul_f32 v[114:115], v[114:115], v[126:127]
	v_pk_mul_f32 v[120:121], v[108:109], v[120:121]
	v_pk_mul_f32 v[122:123], v[110:111], v[122:123]
	v_rcp_f32_e32 v176, v182
	v_cvt_pk_bf16_f32 v108, v112, v113
	v_cvt_pk_bf16_f32 v109, v114, v115
	v_cvt_pk_bf16_f32 v110, v120, v121
	v_cvt_pk_bf16_f32 v111, v122, v123
	v_rcp_f32_e32 v177, v183
	v_pk_mul_f32 v[104:105], v[104:105], v[164:165] op_sel_hi:[1,0]
	global_store_dwordx4 v[160:161], v[108:111], off nt
	v_pk_mul_f32 v[102:103], v[102:103], v[164:165] op_sel_hi:[1,0]
	v_pk_mul_f32 v[106:107], v[106:107], v[164:165] op_sel_hi:[1,0]
	v_mul_f32_e32 v110, 0xbfb8aa3b, v104
	v_exp_f32_e32 v110, v110
	v_pk_mul_f32 v[108:109], v[116:117], v[174:175]
	v_mul_f32_e32 v111, 0xbfb8aa3b, v107
	v_pk_mul_f32 v[100:101], v[100:101], v[108:109]
	v_pk_mul_f32 v[108:109], v[118:119], v[176:177]
	v_exp_f32_e32 v111, v111
	v_pk_mul_f32 v[102:103], v[102:103], v[108:109]
	v_mul_f32_e32 v108, 0xbfb8aa3b, v105
	v_exp_f32_e32 v109, v108
	v_add_f32_e32 v108, 1.0, v110
	v_mul_f32_e32 v110, 0xbfb8aa3b, v106
	v_exp_f32_e32 v110, v110
	v_add_f32_e32 v109, 1.0, v109
	v_rcp_f32_e32 v108, v108
	v_rcp_f32_e32 v109, v109
	v_add_f32_e32 v110, 1.0, v110
	v_add_f32_e32 v111, 1.0, v111
	v_rcp_f32_e32 v110, v110
	v_rcp_f32_e32 v111, v111
	v_pk_mul_f32 v[96:97], v[96:97], v[164:165] op_sel_hi:[1,0]
	v_pk_mul_f32 v[104:105], v[104:105], v[108:109]
	v_or_b32_e32 v108, 16, v144
	v_pk_mul_f32 v[104:105], v[96:97], v[104:105]
	v_pk_mul_f32 v[96:97], v[98:99], v[164:165] op_sel_hi:[1,0]
	v_pk_mul_f32 v[98:99], v[106:107], v[110:111]
	v_pk_mul_f32 v[92:93], v[92:93], v[166:167] op_sel_hi:[1,0]
	v_pk_mul_f32 v[106:107], v[96:97], v[98:99]
	v_cvt_pk_bf16_f32 v96, v100, v101
	v_cvt_pk_bf16_f32 v97, v102, v103
	v_cvt_pk_bf16_f32 v98, v104, v105
	v_cvt_pk_bf16_f32 v99, v106, v107
	v_mad_i64_i32 v[100:101], s[38:39], v108, s62, v[146:147]
	v_mul_f32_e32 v102, 0xbfb8aa3b, v92
	global_store_dwordx4 v[100:101], v[96:99], off nt
	v_pk_mul_f32 v[94:95], v[94:95], v[166:167] op_sel_hi:[1,0]
	v_exp_f32_e32 v102, v102
	v_mul_f32_e32 v96, 0xbfb8aa3b, v93
	v_exp_f32_e32 v97, v96
	v_mul_f32_e32 v98, 0xbfb8aa3b, v94
	v_mul_f32_e32 v99, 0xbfb8aa3b, v95
	v_exp_f32_e32 v98, v98
	v_exp_f32_e32 v99, v99
	v_add_f32_e32 v96, 1.0, v102
	v_add_f32_e32 v97, 1.0, v97
	v_rcp_f32_e32 v96, v96
	v_rcp_f32_e32 v97, v97
	v_add_f32_e32 v98, 1.0, v98
	v_add_f32_e32 v99, 1.0, v99
	v_rcp_f32_e32 v98, v98
	v_rcp_f32_e32 v99, v99
	v_pk_mul_f32 v[84:85], v[84:85], v[166:167] op_sel_hi:[1,0]
	v_pk_mul_f32 v[92:93], v[92:93], v[96:97]
	v_pk_mul_f32 v[88:89], v[88:89], v[166:167] op_sel_hi:[1,0]
	v_pk_mul_f32 v[84:85], v[84:85], v[92:93]
	v_pk_mul_f32 v[92:93], v[94:95], v[98:99]
	v_mul_f32_e32 v94, 0xbfb8aa3b, v88
	v_exp_f32_e32 v94, v94
	v_pk_mul_f32 v[86:87], v[86:87], v[166:167] op_sel_hi:[1,0]
	v_pk_mul_f32 v[90:91], v[90:91], v[166:167] op_sel_hi:[1,0]
	v_pk_mul_f32 v[86:87], v[86:87], v[92:93]
	v_mul_f32_e32 v92, 0xbfb8aa3b, v89
	v_exp_f32_e32 v93, v92
	v_add_f32_e32 v92, 1.0, v94
	v_mul_f32_e32 v94, 0xbfb8aa3b, v90
	v_mul_f32_e32 v95, 0xbfb8aa3b, v91
	v_exp_f32_e32 v94, v94
	v_exp_f32_e32 v95, v95
	v_add_f32_e32 v93, 1.0, v93
	v_rcp_f32_e32 v92, v92
	v_rcp_f32_e32 v93, v93
	v_add_f32_e32 v94, 1.0, v94
	v_add_f32_e32 v95, 1.0, v95
	v_rcp_f32_e32 v94, v94
	v_rcp_f32_e32 v95, v95
	v_pk_mul_f32 v[80:81], v[80:81], v[166:167] op_sel_hi:[1,0]
	v_pk_mul_f32 v[88:89], v[88:89], v[92:93]
	v_or_b32_e32 v92, 32, v144
	v_pk_mul_f32 v[88:89], v[80:81], v[88:89]
	v_pk_mul_f32 v[80:81], v[82:83], v[166:167] op_sel_hi:[1,0]
	v_pk_mul_f32 v[82:83], v[90:91], v[94:95]
	v_pk_mul_f32 v[76:77], v[76:77], v[156:157] op_sel_hi:[1,0]
	v_pk_mul_f32 v[90:91], v[80:81], v[82:83]
	v_cvt_pk_bf16_f32 v80, v84, v85
	v_cvt_pk_bf16_f32 v81, v86, v87
	v_cvt_pk_bf16_f32 v82, v88, v89
	v_cvt_pk_bf16_f32 v83, v90, v91
	v_mad_i64_i32 v[84:85], s[38:39], v92, s62, v[146:147]
	v_mul_f32_e32 v86, 0xbfb8aa3b, v76
	global_store_dwordx4 v[84:85], v[80:83], off nt
	v_pk_mul_f32 v[78:79], v[78:79], v[156:157] op_sel_hi:[1,0]
	v_exp_f32_e32 v86, v86
	v_mul_f32_e32 v80, 0xbfb8aa3b, v77
	v_exp_f32_e32 v81, v80
	v_mul_f32_e32 v82, 0xbfb8aa3b, v78
	v_mul_f32_e32 v83, 0xbfb8aa3b, v79
	v_exp_f32_e32 v82, v82
	v_exp_f32_e32 v83, v83
	v_add_f32_e32 v80, 1.0, v86
	v_add_f32_e32 v81, 1.0, v81
	v_rcp_f32_e32 v80, v80
	v_rcp_f32_e32 v81, v81
	v_add_f32_e32 v82, 1.0, v82
	v_add_f32_e32 v83, 1.0, v83
	v_rcp_f32_e32 v82, v82
	v_rcp_f32_e32 v83, v83
	v_pk_mul_f32 v[68:69], v[68:69], v[156:157] op_sel_hi:[1,0]
	v_pk_mul_f32 v[76:77], v[76:77], v[80:81]
	v_pk_mul_f32 v[72:73], v[72:73], v[156:157] op_sel_hi:[1,0]
	v_pk_mul_f32 v[68:69], v[68:69], v[76:77]
	v_pk_mul_f32 v[76:77], v[78:79], v[82:83]
	v_mul_f32_e32 v78, 0xbfb8aa3b, v72
	v_exp_f32_e32 v78, v78
	v_pk_mul_f32 v[70:71], v[70:71], v[156:157] op_sel_hi:[1,0]
	v_pk_mul_f32 v[74:75], v[74:75], v[156:157] op_sel_hi:[1,0]
	v_pk_mul_f32 v[70:71], v[70:71], v[76:77]
	v_mul_f32_e32 v76, 0xbfb8aa3b, v73
	v_exp_f32_e32 v77, v76
	v_add_f32_e32 v76, 1.0, v78
	v_mul_f32_e32 v78, 0xbfb8aa3b, v74
	v_mul_f32_e32 v79, 0xbfb8aa3b, v75
	v_exp_f32_e32 v78, v78
	v_exp_f32_e32 v79, v79
	v_add_f32_e32 v77, 1.0, v77
	v_rcp_f32_e32 v76, v76
	v_rcp_f32_e32 v77, v77
	v_add_f32_e32 v78, 1.0, v78
	v_add_f32_e32 v79, 1.0, v79
	v_rcp_f32_e32 v78, v78
	v_rcp_f32_e32 v79, v79
	v_fmamk_f32 v154, v154, 0x3a800000, v159
	v_rsq_f32_e32 v154, v154
	v_pk_mul_f32 v[64:65], v[64:65], v[156:157] op_sel_hi:[1,0]
	v_pk_mul_f32 v[72:73], v[72:73], v[76:77]
	v_or_b32_e32 v76, 48, v144
	v_pk_mul_f32 v[72:73], v[64:65], v[72:73]
	v_pk_mul_f32 v[64:65], v[66:67], v[156:157] op_sel_hi:[1,0]
	v_pk_mul_f32 v[66:67], v[74:75], v[78:79]
	v_pk_mul_f32 v[60:61], v[60:61], v[154:155] op_sel_hi:[1,0]
	v_pk_mul_f32 v[74:75], v[64:65], v[66:67]
	v_cvt_pk_bf16_f32 v64, v68, v69
	v_cvt_pk_bf16_f32 v65, v70, v71
	v_cvt_pk_bf16_f32 v66, v72, v73
	v_cvt_pk_bf16_f32 v67, v74, v75
	v_mad_i64_i32 v[68:69], s[38:39], v76, s62, v[146:147]
	global_store_dwordx4 v[68:69], v[64:67], off nt
	v_pk_mul_f32 v[62:63], v[62:63], v[154:155] op_sel_hi:[1,0]
	v_pk_mul_f32 v[52:53], v[52:53], v[154:155] op_sel_hi:[1,0]
	v_mul_f32_e32 v64, 0xbfb8aa3b, v60
	v_mul_f32_e32 v65, 0xbfb8aa3b, v61
	v_exp_f32_e32 v64, v64
	v_exp_f32_e32 v65, v65
	v_mul_f32_e32 v66, 0xbfb8aa3b, v62
	v_mul_f32_e32 v67, 0xbfb8aa3b, v63
	v_exp_f32_e32 v66, v66
	v_exp_f32_e32 v67, v67
	v_add_f32_e32 v64, 1.0, v64
	v_add_f32_e32 v65, 1.0, v65
	v_rcp_f32_e32 v64, v64
	v_rcp_f32_e32 v65, v65
	v_add_f32_e32 v66, 1.0, v66
	v_add_f32_e32 v67, 1.0, v67
	v_rcp_f32_e32 v66, v66
	v_rcp_f32_e32 v67, v67
	v_pk_mul_f32 v[60:61], v[60:61], v[64:65]
	v_pk_mul_f32 v[56:57], v[56:57], v[154:155] op_sel_hi:[1,0]
	v_pk_mul_f32 v[52:53], v[52:53], v[60:61]
	v_pk_mul_f32 v[60:61], v[62:63], v[66:67]
	v_mul_f32_e32 v62, 0xbfb8aa3b, v56
	v_exp_f32_e32 v62, v62
	v_pk_mul_f32 v[54:55], v[54:55], v[154:155] op_sel_hi:[1,0]
	v_pk_mul_f32 v[58:59], v[58:59], v[154:155] op_sel_hi:[1,0]
	v_pk_mul_f32 v[54:55], v[54:55], v[60:61]
	v_mul_f32_e32 v60, 0xbfb8aa3b, v57
	v_exp_f32_e32 v61, v60
	v_add_f32_e32 v60, 1.0, v62
	v_mul_f32_e32 v62, 0xbfb8aa3b, v58
	v_mul_f32_e32 v63, 0xbfb8aa3b, v59
	v_exp_f32_e32 v62, v62
	v_exp_f32_e32 v63, v63
	v_add_f32_e32 v61, 1.0, v61
	v_rcp_f32_e32 v60, v60
	v_rcp_f32_e32 v61, v61
	v_add_f32_e32 v62, 1.0, v62
	v_add_f32_e32 v63, 1.0, v63
	v_rcp_f32_e32 v62, v62
	v_rcp_f32_e32 v63, v63
	v_pk_mul_f32 v[48:49], v[48:49], v[154:155] op_sel_hi:[1,0]
	v_pk_mul_f32 v[56:57], v[56:57], v[60:61]
	v_add_u32_e32 v68, 0x80, v144
	v_pk_mul_f32 v[56:57], v[48:49], v[56:57]
	v_pk_mul_f32 v[48:49], v[50:51], v[154:155] op_sel_hi:[1,0]
	v_pk_mul_f32 v[50:51], v[58:59], v[62:63]
	v_pk_mul_f32 v[44:45], v[44:45], v[152:153] op_sel_hi:[1,0]
	v_pk_mul_f32 v[58:59], v[48:49], v[50:51]
	v_cvt_pk_bf16_f32 v48, v52, v53
	v_cvt_pk_bf16_f32 v49, v54, v55
	v_cvt_pk_bf16_f32 v50, v56, v57
	v_cvt_pk_bf16_f32 v51, v58, v59
	v_mad_i64_i32 v[52:53], s[38:39], v68, s62, v[146:147]
	v_mul_f32_e32 v54, 0xbfb8aa3b, v44
	global_store_dwordx4 v[52:53], v[48:51], off nt
	v_pk_mul_f32 v[46:47], v[46:47], v[152:153] op_sel_hi:[1,0]
	v_exp_f32_e32 v54, v54
	v_mul_f32_e32 v48, 0xbfb8aa3b, v45
	v_exp_f32_e32 v49, v48
	v_mul_f32_e32 v50, 0xbfb8aa3b, v46
	v_mul_f32_e32 v51, 0xbfb8aa3b, v47
	v_exp_f32_e32 v50, v50
	v_exp_f32_e32 v51, v51
	v_add_f32_e32 v48, 1.0, v54
	v_add_f32_e32 v49, 1.0, v49
	v_rcp_f32_e32 v48, v48
	v_rcp_f32_e32 v49, v49
	v_add_f32_e32 v50, 1.0, v50
	v_add_f32_e32 v51, 1.0, v51
	v_rcp_f32_e32 v50, v50
	v_rcp_f32_e32 v51, v51
	v_pk_mul_f32 v[36:37], v[36:37], v[152:153] op_sel_hi:[1,0]
	v_pk_mul_f32 v[44:45], v[44:45], v[48:49]
	v_pk_mul_f32 v[40:41], v[40:41], v[152:153] op_sel_hi:[1,0]
	v_pk_mul_f32 v[36:37], v[36:37], v[44:45]
	v_pk_mul_f32 v[44:45], v[46:47], v[50:51]
	v_mul_f32_e32 v46, 0xbfb8aa3b, v40
	v_exp_f32_e32 v46, v46
	v_pk_mul_f32 v[38:39], v[38:39], v[152:153] op_sel_hi:[1,0]
	v_pk_mul_f32 v[42:43], v[42:43], v[152:153] op_sel_hi:[1,0]
	v_pk_mul_f32 v[38:39], v[38:39], v[44:45]
	v_mul_f32_e32 v44, 0xbfb8aa3b, v41
	v_exp_f32_e32 v45, v44
	v_add_f32_e32 v44, 1.0, v46
	v_mul_f32_e32 v46, 0xbfb8aa3b, v42
	v_mul_f32_e32 v47, 0xbfb8aa3b, v43
	v_exp_f32_e32 v46, v46
	v_exp_f32_e32 v47, v47
	v_add_f32_e32 v45, 1.0, v45
	v_rcp_f32_e32 v44, v44
	v_rcp_f32_e32 v45, v45
	v_add_f32_e32 v46, 1.0, v46
	v_add_f32_e32 v47, 1.0, v47
	v_rcp_f32_e32 v46, v46
	v_rcp_f32_e32 v47, v47
	v_pk_mul_f32 v[32:33], v[32:33], v[152:153] op_sel_hi:[1,0]
	v_pk_mul_f32 v[40:41], v[40:41], v[44:45]
	v_add_u32_e32 v44, 0x90, v144
	v_pk_mul_f32 v[40:41], v[32:33], v[40:41]
	v_pk_mul_f32 v[32:33], v[34:35], v[152:153] op_sel_hi:[1,0]
	v_pk_mul_f32 v[34:35], v[42:43], v[46:47]
	v_pk_mul_f32 v[28:29], v[28:29], v[150:151] op_sel_hi:[1,0]
	v_pk_mul_f32 v[42:43], v[32:33], v[34:35]
	v_cvt_pk_bf16_f32 v32, v36, v37
	v_cvt_pk_bf16_f32 v33, v38, v39
	v_cvt_pk_bf16_f32 v34, v40, v41
	v_cvt_pk_bf16_f32 v35, v42, v43
	v_mad_i64_i32 v[36:37], s[38:39], v44, s62, v[146:147]
	v_mul_f32_e32 v38, 0xbfb8aa3b, v28
	global_store_dwordx4 v[36:37], v[32:35], off nt
	v_pk_mul_f32 v[30:31], v[30:31], v[150:151] op_sel_hi:[1,0]
	v_exp_f32_e32 v38, v38
	v_mul_f32_e32 v32, 0xbfb8aa3b, v29
	v_exp_f32_e32 v33, v32
	v_mul_f32_e32 v34, 0xbfb8aa3b, v30
	v_mul_f32_e32 v35, 0xbfb8aa3b, v31
	v_exp_f32_e32 v34, v34
	v_exp_f32_e32 v35, v35
	v_add_f32_e32 v32, 1.0, v38
	v_add_f32_e32 v33, 1.0, v33
	v_rcp_f32_e32 v32, v32
	v_rcp_f32_e32 v33, v33
	v_add_f32_e32 v34, 1.0, v34
	v_add_f32_e32 v35, 1.0, v35
	v_rcp_f32_e32 v34, v34
	v_rcp_f32_e32 v35, v35
	v_pk_mul_f32 v[20:21], v[20:21], v[150:151] op_sel_hi:[1,0]
	v_pk_mul_f32 v[28:29], v[28:29], v[32:33]
	v_pk_mul_f32 v[24:25], v[24:25], v[150:151] op_sel_hi:[1,0]
	v_pk_mul_f32 v[20:21], v[20:21], v[28:29]
	v_pk_mul_f32 v[28:29], v[30:31], v[34:35]
	v_mul_f32_e32 v30, 0xbfb8aa3b, v24
	v_exp_f32_e32 v30, v30
	v_pk_mul_f32 v[22:23], v[22:23], v[150:151] op_sel_hi:[1,0]
	v_pk_mul_f32 v[26:27], v[26:27], v[150:151] op_sel_hi:[1,0]
	v_pk_mul_f32 v[22:23], v[22:23], v[28:29]
	v_mul_f32_e32 v28, 0xbfb8aa3b, v25
	v_exp_f32_e32 v29, v28
	v_add_f32_e32 v28, 1.0, v30
	v_mul_f32_e32 v30, 0xbfb8aa3b, v26
	v_mul_f32_e32 v31, 0xbfb8aa3b, v27
	v_exp_f32_e32 v30, v30
	v_exp_f32_e32 v31, v31
	v_add_f32_e32 v29, 1.0, v29
	v_rcp_f32_e32 v28, v28
	v_rcp_f32_e32 v29, v29
	v_add_f32_e32 v30, 1.0, v30
	v_add_f32_e32 v31, 1.0, v31
	v_rcp_f32_e32 v30, v30
	v_rcp_f32_e32 v31, v31
	v_pk_mul_f32 v[16:17], v[16:17], v[150:151] op_sel_hi:[1,0]
	v_pk_mul_f32 v[24:25], v[24:25], v[28:29]
	v_add_u32_e32 v28, 0xa0, v144
	v_pk_mul_f32 v[24:25], v[16:17], v[24:25]
	v_pk_mul_f32 v[16:17], v[18:19], v[150:151] op_sel_hi:[1,0]
	v_pk_mul_f32 v[18:19], v[26:27], v[30:31]
	v_pk_mul_f32 v[12:13], v[12:13], v[148:149] op_sel_hi:[1,0]
	v_pk_mul_f32 v[26:27], v[16:17], v[18:19]
	v_cvt_pk_bf16_f32 v16, v20, v21
	v_cvt_pk_bf16_f32 v17, v22, v23
	v_cvt_pk_bf16_f32 v18, v24, v25
	v_cvt_pk_bf16_f32 v19, v26, v27
	v_mad_i64_i32 v[20:21], s[38:39], v28, s62, v[146:147]
	v_mul_f32_e32 v22, 0xbfb8aa3b, v12
	global_store_dwordx4 v[20:21], v[16:19], off nt
	v_pk_mul_f32 v[14:15], v[14:15], v[148:149] op_sel_hi:[1,0]
	v_exp_f32_e32 v22, v22
	v_mul_f32_e32 v16, 0xbfb8aa3b, v13
	v_exp_f32_e32 v17, v16
	v_mul_f32_e32 v18, 0xbfb8aa3b, v14
	v_mul_f32_e32 v19, 0xbfb8aa3b, v15
	v_exp_f32_e32 v18, v18
	v_exp_f32_e32 v19, v19
	v_add_f32_e32 v16, 1.0, v22
	v_add_f32_e32 v17, 1.0, v17
	v_rcp_f32_e32 v16, v16
	v_rcp_f32_e32 v17, v17
	v_add_f32_e32 v18, 1.0, v18
	v_add_f32_e32 v19, 1.0, v19
	v_rcp_f32_e32 v18, v18
	v_rcp_f32_e32 v19, v19
	v_pk_mul_f32 v[4:5], v[4:5], v[148:149] op_sel_hi:[1,0]
	v_pk_mul_f32 v[12:13], v[12:13], v[16:17]
	v_pk_mul_f32 v[8:9], v[8:9], v[148:149] op_sel_hi:[1,0]
	v_pk_mul_f32 v[4:5], v[4:5], v[12:13]
	v_pk_mul_f32 v[12:13], v[14:15], v[18:19]
	v_mul_f32_e32 v14, 0xbfb8aa3b, v8
	v_exp_f32_e32 v14, v14
	v_pk_mul_f32 v[6:7], v[6:7], v[148:149] op_sel_hi:[1,0]
	v_pk_mul_f32 v[10:11], v[10:11], v[148:149] op_sel_hi:[1,0]
	v_pk_mul_f32 v[6:7], v[6:7], v[12:13]
	v_mul_f32_e32 v12, 0xbfb8aa3b, v9
	v_exp_f32_e32 v13, v12
	v_add_f32_e32 v12, 1.0, v14
	v_mul_f32_e32 v14, 0xbfb8aa3b, v10
	v_mul_f32_e32 v15, 0xbfb8aa3b, v11
	v_exp_f32_e32 v14, v14
	v_exp_f32_e32 v15, v15
	v_add_f32_e32 v13, 1.0, v13
	v_rcp_f32_e32 v12, v12
	v_rcp_f32_e32 v13, v13
	v_add_f32_e32 v14, 1.0, v14
	v_add_f32_e32 v15, 1.0, v15
	v_rcp_f32_e32 v14, v14
	v_rcp_f32_e32 v15, v15
	v_pk_mul_f32 v[0:1], v[0:1], v[148:149] op_sel_hi:[1,0]
	v_pk_mul_f32 v[8:9], v[8:9], v[12:13]
	v_add_u32_e32 v12, 0xb0, v144
	v_pk_mul_f32 v[8:9], v[0:1], v[8:9]
	v_pk_mul_f32 v[0:1], v[2:3], v[148:149] op_sel_hi:[1,0]
	v_pk_mul_f32 v[2:3], v[10:11], v[14:15]
	s_nop 0
	v_pk_mul_f32 v[10:11], v[0:1], v[2:3]
	v_cvt_pk_bf16_f32 v0, v4, v5
	v_cvt_pk_bf16_f32 v1, v6, v7
	v_cvt_pk_bf16_f32 v2, v8, v9
	v_cvt_pk_bf16_f32 v3, v10, v11
	v_mad_i64_i32 v[4:5], s[38:39], v12, s62, v[146:147]
	global_store_dwordx4 v[4:5], v[0:3], off nt
	s_cbranch_vccnz .LBB0_1111
	s_andn2_b64 vcc, exec, s[8:9]
	s_cbranch_vccnz .LBB0_1110
	s_barrier
	s_branch .LBB0_1110

.LBB0_1413:
	ds_read_b128 v[128:131], v171
	ds_read_b128 v[132:135], v171 offset:1024
	ds_read_b128 v[178:181], v171 offset:2048
	ds_read_b128 v[186:189], v171 offset:3072
	ds_read_b128 v[190:193], v173
	ds_read_b128 v[194:197], v173 offset:1024
	ds_read_b128 v[198:201], v173 offset:2048
	ds_read_b128 v[202:205], v173 offset:3072
	s_add_u32 s21, s38, 0xfffc0080
	s_addc_u32 s22, s39, -1
	s_cmp_eq_u32 s20, 12
	s_cselect_b32 s43, s14, s22
	s_cselect_b32 s42, s15, s21
	s_cselect_b32 s41, s16, s19
	s_cselect_b32 s40, s17, s18
	s_add_i32 m0, s37, 0xc000
	ds_read_b128 v[206:209], v175
	ds_read_b128 v[210:213], v175 offset:1024
	ds_read_b128 v[214:217], v175 offset:2048
	ds_read_b128 v[218:221], v175 offset:3072
	ds_read_b128 v[222:225], v175 offset:4096
	ds_read_b128 v[226:229], v175 offset:5120
	ds_read_b128 v[230:233], v175 offset:6144
	ds_read_b128 v[234:237], v175 offset:7168
	global_load_lds_dwordx4 v152, s[38:39]
	s_add_i32 m0, s37, 0xe000
	s_nop 0
	global_load_lds_dwordx4 v154, s[38:39]
	s_waitcnt vmcnt(8)
	s_waitcnt lgkmcnt(0)
	s_barrier
	s_waitcnt lgkmcnt(0)
	v_mfma_f32_16x16x32_bf16 v[124:127], v[128:131], v[206:209], v[124:127]
	v_mfma_f32_16x16x32_bf16 v[120:123], v[178:181], v[206:209], v[120:123]
	v_mfma_f32_16x16x32_bf16 v[108:111], v[128:131], v[214:217], v[108:111]
	v_mfma_f32_16x16x32_bf16 v[100:103], v[178:181], v[214:217], v[100:103]
	v_mfma_f32_16x16x32_bf16 v[92:95], v[128:131], v[222:225], v[92:95]
	v_mfma_f32_16x16x32_bf16 v[84:87], v[178:181], v[222:225], v[84:87]
	v_mfma_f32_16x16x32_bf16 v[76:79], v[128:131], v[230:233], v[76:79]
	v_mfma_f32_16x16x32_bf16 v[68:71], v[178:181], v[230:233], v[68:71]
	v_mfma_f32_16x16x32_bf16 v[124:127], v[132:135], v[210:213], v[124:127]
	v_mfma_f32_16x16x32_bf16 v[120:123], v[186:189], v[210:213], v[120:123]
	v_mfma_f32_16x16x32_bf16 v[108:111], v[132:135], v[218:221], v[108:111]
	v_mfma_f32_16x16x32_bf16 v[100:103], v[186:189], v[218:221], v[100:103]
	v_mfma_f32_16x16x32_bf16 v[92:95], v[132:135], v[226:229], v[92:95]
	v_mfma_f32_16x16x32_bf16 v[84:87], v[186:189], v[226:229], v[84:87]
	v_mfma_f32_16x16x32_bf16 v[76:79], v[132:135], v[234:237], v[76:79]
	v_mfma_f32_16x16x32_bf16 v[68:71], v[186:189], v[234:237], v[68:71]
	v_mfma_f32_16x16x32_bf16 v[116:119], v[190:193], v[206:209], v[116:119]
	v_mfma_f32_16x16x32_bf16 v[112:115], v[198:201], v[206:209], v[112:115]
	v_mfma_f32_16x16x32_bf16 v[104:107], v[190:193], v[214:217], v[104:107]
	v_mfma_f32_16x16x32_bf16 v[96:99], v[198:201], v[214:217], v[96:99]
	v_mfma_f32_16x16x32_bf16 v[88:91], v[190:193], v[222:225], v[88:91]
	v_mfma_f32_16x16x32_bf16 v[80:83], v[198:201], v[222:225], v[80:83]
	v_mfma_f32_16x16x32_bf16 v[72:75], v[190:193], v[230:233], v[72:75]
	v_mfma_f32_16x16x32_bf16 v[64:67], v[198:201], v[230:233], v[64:67]
	v_mfma_f32_16x16x32_bf16 v[116:119], v[194:197], v[210:213], v[116:119]
	v_mfma_f32_16x16x32_bf16 v[112:115], v[202:205], v[210:213], v[112:115]
	v_mfma_f32_16x16x32_bf16 v[104:107], v[194:197], v[218:221], v[104:107]
	v_mfma_f32_16x16x32_bf16 v[96:99], v[202:205], v[218:221], v[96:99]
	v_mfma_f32_16x16x32_bf16 v[88:91], v[194:197], v[226:229], v[88:91]
	v_mfma_f32_16x16x32_bf16 v[80:83], v[202:205], v[226:229], v[80:83]
	v_mfma_f32_16x16x32_bf16 v[72:75], v[194:197], v[234:237], v[72:75]
	v_mfma_f32_16x16x32_bf16 v[64:67], v[202:205], v[234:237], v[64:67]
	s_barrier
	s_add_i32 s21, s44, s60
	s_mov_b32 m0, s21
	ds_read_b128 v[206:209], v175 offset:16384
	ds_read_b128 v[210:213], v175 offset:17408
	ds_read_b128 v[214:217], v175 offset:18432
	ds_read_b128 v[218:221], v175 offset:19456
	ds_read_b128 v[222:225], v175 offset:20480
	ds_read_b128 v[226:229], v175 offset:21504
	ds_read_b128 v[230:233], v175 offset:22528
	ds_read_b128 v[234:237], v175 offset:23552
	global_load_lds_dwordx4 v140, s[40:41]
	s_add_i32 m0, s21, 0x2000
	s_add_u32 s22, s40, 0x40000
	s_addc_u32 s23, s41, 0
	s_add_i32 s21, s45, s60
	global_load_lds_dwordx4 v136, s[40:41]
	s_mov_b32 m0, s21
	global_load_lds_dwordx4 v140, s[22:23]
	s_add_i32 m0, s21, 0x2000
	s_nop 0
	global_load_lds_dwordx4 v136, s[22:23]
	s_mov_b32 m0, s37
	s_nop 0
	global_load_lds_dwordx4 v142, s[42:43]
	s_mov_b32 m0, s63
	s_nop 0
	global_load_lds_dwordx4 v138, s[42:43]
	s_add_u32 s98, s40, s12
	s_addc_u32 s99, s41, s13
	s_add_u32 s100, s42, s12
	s_addc_u32 s101, s43, s13
	s_waitcnt vmcnt(8)
	s_waitcnt lgkmcnt(0)
	s_barrier
	s_waitcnt lgkmcnt(0)
	v_mfma_f32_16x16x32_bf16 v[60:63], v[128:131], v[206:209], v[60:63]
	v_mfma_f32_16x16x32_bf16 v[52:55], v[178:181], v[206:209], v[52:55]
	v_mfma_f32_16x16x32_bf16 v[44:47], v[128:131], v[214:217], v[44:47]
	v_mfma_f32_16x16x32_bf16 v[36:39], v[178:181], v[214:217], v[36:39]
	v_mfma_f32_16x16x32_bf16 v[28:31], v[128:131], v[222:225], v[28:31]
	v_mfma_f32_16x16x32_bf16 v[20:23], v[178:181], v[222:225], v[20:23]
	v_mfma_f32_16x16x32_bf16 v[12:15], v[128:131], v[230:233], v[12:15]
	v_mfma_f32_16x16x32_bf16 v[4:7], v[178:181], v[230:233], v[4:7]
	v_mfma_f32_16x16x32_bf16 v[60:63], v[132:135], v[210:213], v[60:63]
	v_mfma_f32_16x16x32_bf16 v[52:55], v[186:189], v[210:213], v[52:55]
	v_mfma_f32_16x16x32_bf16 v[44:47], v[132:135], v[218:221], v[44:47]
	v_mfma_f32_16x16x32_bf16 v[36:39], v[186:189], v[218:221], v[36:39]
	v_mfma_f32_16x16x32_bf16 v[28:31], v[132:135], v[226:229], v[28:31]
	v_mfma_f32_16x16x32_bf16 v[20:23], v[186:189], v[226:229], v[20:23]
	v_mfma_f32_16x16x32_bf16 v[12:15], v[132:135], v[234:237], v[12:15]
	v_mfma_f32_16x16x32_bf16 v[4:7], v[186:189], v[234:237], v[4:7]
	v_mfma_f32_16x16x32_bf16 v[56:59], v[190:193], v[206:209], v[56:59]
	v_mfma_f32_16x16x32_bf16 v[48:51], v[198:201], v[206:209], v[48:51]
	v_mfma_f32_16x16x32_bf16 v[40:43], v[190:193], v[214:217], v[40:43]
	v_mfma_f32_16x16x32_bf16 v[32:35], v[198:201], v[214:217], v[32:35]
	v_mfma_f32_16x16x32_bf16 v[24:27], v[190:193], v[222:225], v[24:27]
	v_mfma_f32_16x16x32_bf16 v[16:19], v[198:201], v[222:225], v[16:19]
	v_mfma_f32_16x16x32_bf16 v[8:11], v[190:193], v[230:233], v[8:11]
	v_mfma_f32_16x16x32_bf16 v[0:3], v[198:201], v[230:233], v[0:3]
	v_mfma_f32_16x16x32_bf16 v[56:59], v[194:197], v[210:213], v[56:59]
	v_mfma_f32_16x16x32_bf16 v[48:51], v[202:205], v[210:213], v[48:51]
	v_mfma_f32_16x16x32_bf16 v[40:43], v[194:197], v[218:221], v[40:43]
	v_mfma_f32_16x16x32_bf16 v[32:35], v[202:205], v[218:221], v[32:35]
	v_mfma_f32_16x16x32_bf16 v[24:27], v[194:197], v[226:229], v[24:27]
	v_mfma_f32_16x16x32_bf16 v[16:19], v[202:205], v[226:229], v[16:19]
	v_mfma_f32_16x16x32_bf16 v[8:11], v[194:197], v[234:237], v[8:11]
	v_mfma_f32_16x16x32_bf16 v[0:3], v[202:205], v[234:237], v[0:3]
	s_barrier
	s_add_i32 s21, 0, 0x18000
	v_add_u32_e32 v144, s21, v165
	s_add_i32 s27, 0, 0x1c000
	ds_read_b128 v[128:131], v144
	ds_read_b128 v[132:135], v144 offset:1024
	ds_read_b128 v[178:181], v144 offset:2048
	ds_read_b128 v[186:189], v144 offset:3072
	v_add_u32_e32 v144, s27, v165
	ds_read_b128 v[190:193], v144
	ds_read_b128 v[194:197], v144 offset:1024
	ds_read_b128 v[198:201], v144 offset:2048
	ds_read_b128 v[202:205], v144 offset:3072
	s_add_u32 s22, s42, 0x40000
	s_addc_u32 s23, s43, 0
	s_mov_b32 m0, s64
	ds_read_b128 v[206:209], v175 offset:32768
	ds_read_b128 v[210:213], v175 offset:33792
	ds_read_b128 v[214:217], v175 offset:34816
	ds_read_b128 v[218:221], v175 offset:35840
	ds_read_b128 v[222:225], v175 offset:36864
	ds_read_b128 v[226:229], v175 offset:37888
	ds_read_b128 v[230:233], v175 offset:38912
	ds_read_b128 v[234:237], v175 offset:39936
	global_load_lds_dwordx4 v142, s[22:23]
	s_mov_b32 m0, s65
	s_nop 0
	global_load_lds_dwordx4 v138, s[22:23]
	s_waitcnt vmcnt(8)
	s_waitcnt lgkmcnt(0)
	s_barrier
	s_waitcnt lgkmcnt(0)
	v_mfma_f32_16x16x32_bf16 v[124:127], v[128:131], v[206:209], v[124:127]
	v_mfma_f32_16x16x32_bf16 v[120:123], v[178:181], v[206:209], v[120:123]
	v_mfma_f32_16x16x32_bf16 v[108:111], v[128:131], v[214:217], v[108:111]
	v_mfma_f32_16x16x32_bf16 v[100:103], v[178:181], v[214:217], v[100:103]
	v_mfma_f32_16x16x32_bf16 v[92:95], v[128:131], v[222:225], v[92:95]
	v_mfma_f32_16x16x32_bf16 v[84:87], v[178:181], v[222:225], v[84:87]
	v_mfma_f32_16x16x32_bf16 v[76:79], v[128:131], v[230:233], v[76:79]
	v_mfma_f32_16x16x32_bf16 v[68:71], v[178:181], v[230:233], v[68:71]
	v_mfma_f32_16x16x32_bf16 v[124:127], v[132:135], v[210:213], v[124:127]
	v_mfma_f32_16x16x32_bf16 v[120:123], v[186:189], v[210:213], v[120:123]
	v_mfma_f32_16x16x32_bf16 v[108:111], v[132:135], v[218:221], v[108:111]
	v_mfma_f32_16x16x32_bf16 v[100:103], v[186:189], v[218:221], v[100:103]
	v_mfma_f32_16x16x32_bf16 v[92:95], v[132:135], v[226:229], v[92:95]
	v_mfma_f32_16x16x32_bf16 v[84:87], v[186:189], v[226:229], v[84:87]
	v_mfma_f32_16x16x32_bf16 v[76:79], v[132:135], v[234:237], v[76:79]
	v_mfma_f32_16x16x32_bf16 v[68:71], v[186:189], v[234:237], v[68:71]
	v_mfma_f32_16x16x32_bf16 v[116:119], v[190:193], v[206:209], v[116:119]
	v_mfma_f32_16x16x32_bf16 v[112:115], v[198:201], v[206:209], v[112:115]
	v_mfma_f32_16x16x32_bf16 v[104:107], v[190:193], v[214:217], v[104:107]
	v_mfma_f32_16x16x32_bf16 v[96:99], v[198:201], v[214:217], v[96:99]
	v_mfma_f32_16x16x32_bf16 v[88:91], v[190:193], v[222:225], v[88:91]
	v_mfma_f32_16x16x32_bf16 v[80:83], v[198:201], v[222:225], v[80:83]
	v_mfma_f32_16x16x32_bf16 v[72:75], v[190:193], v[230:233], v[72:75]
	v_mfma_f32_16x16x32_bf16 v[64:67], v[198:201], v[230:233], v[64:67]
	v_mfma_f32_16x16x32_bf16 v[116:119], v[194:197], v[210:213], v[116:119]
	v_mfma_f32_16x16x32_bf16 v[112:115], v[202:205], v[210:213], v[112:115]
	v_mfma_f32_16x16x32_bf16 v[104:107], v[194:197], v[218:221], v[104:107]
	v_mfma_f32_16x16x32_bf16 v[96:99], v[202:205], v[218:221], v[96:99]
	v_mfma_f32_16x16x32_bf16 v[88:91], v[194:197], v[226:229], v[88:91]
	v_mfma_f32_16x16x32_bf16 v[80:83], v[202:205], v[226:229], v[80:83]
	v_mfma_f32_16x16x32_bf16 v[72:75], v[194:197], v[234:237], v[72:75]
	v_mfma_f32_16x16x32_bf16 v[64:67], v[202:205], v[234:237], v[64:67]
	s_barrier
	s_add_i32 s21, s21, s60
	s_mov_b32 m0, s21
	ds_read_b128 v[206:209], v175 offset:49152
	ds_read_b128 v[210:213], v175 offset:50176
	ds_read_b128 v[214:217], v175 offset:51200
	ds_read_b128 v[218:221], v175 offset:52224
	ds_read_b128 v[222:225], v175 offset:53248
	ds_read_b128 v[226:229], v175 offset:54272
	ds_read_b128 v[230:233], v175 offset:55296
	ds_read_b128 v[234:237], v175 offset:56320
	global_load_lds_dwordx4 v140, s[98:99]
	s_add_i32 m0, s21, 0x2000
	s_add_u32 s22, s40, 0x40080
	s_addc_u32 s23, s41, 0
	s_add_i32 s21, s27, s60
	global_load_lds_dwordx4 v136, s[98:99]
	s_mov_b32 m0, s21
	s_nop 0
	global_load_lds_dwordx4 v140, s[22:23]
	s_add_i32 m0, s21, 0x2000
	s_nop 0
	global_load_lds_dwordx4 v136, s[22:23]
	s_mov_b32 m0, s67
	s_nop 0
	global_load_lds_dwordx4 v142, s[100:101]
	s_mov_b32 m0, s70
	s_nop 0
	global_load_lds_dwordx4 v138, s[100:101]
	s_waitcnt vmcnt(8)
	s_waitcnt lgkmcnt(0)
	s_barrier
	s_waitcnt lgkmcnt(0)
	v_mfma_f32_16x16x32_bf16 v[60:63], v[128:131], v[206:209], v[60:63]
	v_mfma_f32_16x16x32_bf16 v[52:55], v[178:181], v[206:209], v[52:55]
	s_cmp_eq_u32 s20, 12
	s_cbranch_scc0 .Lrs_skip_1413
	v_lshl_add_u32 v252, s36, 8, v163
	v_ashrrev_i32_e32 v253, 31, v252
	v_lshl_add_u64 v[254:255], v[252:253], 2, s[10:11]
	global_load_dword v243, v[254:255], off
	global_load_dword v244, v[254:255], off offset:64
	global_load_dword v245, v[254:255], off offset:128
	global_load_dword v246, v[254:255], off offset:192
	global_load_dword v247, v[254:255], off offset:512
	global_load_dword v248, v[254:255], off offset:576
	global_load_dword v249, v[254:255], off offset:640
	global_load_dword v250, v[254:255], off offset:704
.Lrs_skip_1413:
	v_mfma_f32_16x16x32_bf16 v[44:47], v[128:131], v[214:217], v[44:47]
	v_mfma_f32_16x16x32_bf16 v[36:39], v[178:181], v[214:217], v[36:39]
	v_mfma_f32_16x16x32_bf16 v[28:31], v[128:131], v[222:225], v[28:31]
	v_mfma_f32_16x16x32_bf16 v[20:23], v[178:181], v[222:225], v[20:23]
	v_mfma_f32_16x16x32_bf16 v[12:15], v[128:131], v[230:233], v[12:15]
	v_mfma_f32_16x16x32_bf16 v[4:7], v[178:181], v[230:233], v[4:7]
	v_mfma_f32_16x16x32_bf16 v[60:63], v[132:135], v[210:213], v[60:63]
	v_mfma_f32_16x16x32_bf16 v[52:55], v[186:189], v[210:213], v[52:55]
	v_mfma_f32_16x16x32_bf16 v[44:47], v[132:135], v[218:221], v[44:47]
	v_mfma_f32_16x16x32_bf16 v[36:39], v[186:189], v[218:221], v[36:39]
	v_mfma_f32_16x16x32_bf16 v[28:31], v[132:135], v[226:229], v[28:31]
	v_mfma_f32_16x16x32_bf16 v[20:23], v[186:189], v[226:229], v[20:23]
	v_mfma_f32_16x16x32_bf16 v[12:15], v[132:135], v[234:237], v[12:15]
	v_mfma_f32_16x16x32_bf16 v[4:7], v[186:189], v[234:237], v[4:7]
	v_mfma_f32_16x16x32_bf16 v[56:59], v[190:193], v[206:209], v[56:59]
	v_mfma_f32_16x16x32_bf16 v[48:51], v[198:201], v[206:209], v[48:51]
	v_mfma_f32_16x16x32_bf16 v[40:43], v[190:193], v[214:217], v[40:43]
	v_mfma_f32_16x16x32_bf16 v[32:35], v[198:201], v[214:217], v[32:35]
	v_mfma_f32_16x16x32_bf16 v[24:27], v[190:193], v[222:225], v[24:27]
	v_mfma_f32_16x16x32_bf16 v[16:19], v[198:201], v[222:225], v[16:19]
	v_mfma_f32_16x16x32_bf16 v[8:11], v[190:193], v[230:233], v[8:11]
	v_mfma_f32_16x16x32_bf16 v[0:3], v[198:201], v[230:233], v[0:3]
	v_mfma_f32_16x16x32_bf16 v[56:59], v[194:197], v[210:213], v[56:59]
	v_mfma_f32_16x16x32_bf16 v[48:51], v[202:205], v[210:213], v[48:51]
	v_mfma_f32_16x16x32_bf16 v[40:43], v[194:197], v[218:221], v[40:43]
	v_mfma_f32_16x16x32_bf16 v[32:35], v[202:205], v[218:221], v[32:35]
	v_mfma_f32_16x16x32_bf16 v[24:27], v[194:197], v[226:229], v[24:27]
	v_mfma_f32_16x16x32_bf16 v[16:19], v[202:205], v[226:229], v[16:19]
	v_mfma_f32_16x16x32_bf16 v[8:11], v[194:197], v[234:237], v[8:11]
	v_mfma_f32_16x16x32_bf16 v[0:3], v[202:205], v[234:237], v[0:3]
	s_barrier
	s_add_i32 s20, s20, 2
	s_add_u32 s38, s38, 0x100
	s_addc_u32 s39, s39, 0
	s_add_u32 s18, s18, 0x100
	s_addc_u32 s19, s19, 0
	s_cmp_gt_u32 s20, 13
	s_cbranch_scc0 .LBB0_1413
	s_and_b64 vcc, exec, s[24:25]
	s_cbranch_vccz .LBB0_1418
	s_barrier
	s_cmp_lt_i32 s80, 8
	s_mov_b64 s[38:39], -1
	s_cbranch_scc1 .LBB0_1419

.LBB0_1417:
	s_nop 0
	v_lshl_add_u32 v128, s36, 8, v163
	v_ashrrev_i32_e32 v129, 31, v128
	v_lshl_add_u64 v[130:131], v[128:129], 2, s[10:11]
	s_waitcnt vmcnt(0)
	v_mov_b32_e32 v129, v243
	v_mov_b32_e32 v132, v244
	v_mov_b32_e32 v133, v245
	v_mov_b32_e32 v134, v246
	v_mov_b32_e32 v135, v247
	v_mov_b32_e32 v160, v248
	v_mov_b32_e32 v161, v249
	v_mov_b32_e32 v162, v250
	v_lshl_add_u32 v144, s80, 7, v167
	v_lshl_add_u64 v[130:131], v[144:145], 1, s[68:69]
	v_mad_i64_i32 v[168:169], s[14:15], v128, s75, v[130:131]
	s_waitcnt vmcnt(0)
	v_fmamk_f32 v129, v129, 0x3a800000, v176
	v_fmamk_f32 v132, v132, 0x3a800000, v176
	v_rsq_f32_e32 v170, v129
	v_rsq_f32_e32 v166, v132
	v_fmamk_f32 v133, v133, 0x3a800000, v176
	v_fmamk_f32 v134, v134, 0x3a800000, v176
	v_fmamk_f32 v135, v135, 0x3a800000, v176
	v_fmamk_f32 v161, v161, 0x3a800000, v176
	v_fmamk_f32 v172, v162, 0x3a800000, v176
	v_pk_mul_f32 v[124:125], v[124:125], v[170:171] op_sel_hi:[1,0]
	v_pk_mul_f32 v[126:127], v[126:127], v[170:171] op_sel_hi:[1,0]
	v_pk_mul_f32 v[120:121], v[120:121], v[170:171] op_sel_hi:[1,0]
	v_pk_mul_f32 v[122:123], v[122:123], v[170:171] op_sel_hi:[1,0]
	v_fmamk_f32 v144, v160, 0x3a800000, v176
	v_rsq_f32_e32 v164, v133
	v_rsq_f32_e32 v162, v134
	v_rsq_f32_e32 v160, v135
	v_rsq_f32_e32 v134, v161
	v_rsq_f32_e32 v132, v172
	v_pk_mul_f32 v[116:117], v[116:117], v[170:171] op_sel_hi:[1,0]
	v_pk_mul_f32 v[118:119], v[118:119], v[170:171] op_sel_hi:[1,0]
	v_pk_mul_f32 v[112:113], v[112:113], v[170:171] op_sel_hi:[1,0]
	v_pk_mul_f32 v[114:115], v[114:115], v[170:171] op_sel_hi:[1,0]
	v_pk_mul_f32 v[108:109], v[108:109], v[166:167] op_sel_hi:[1,0]
	v_pk_mul_f32 v[178:179], v[104:105], v[166:167] op_sel_hi:[1,0]
	v_pk_mul_f32 v[104:105], v[110:111], v[166:167] op_sel_hi:[1,0]
	v_mul_f32_e32 v110, 0xbfb8aa3b, v124
	v_mul_f32_e32 v111, 0xbfb8aa3b, v125
	v_mul_f32_e32 v129, 0xbfb8aa3b, v126
	v_mul_f32_e32 v133, 0xbfb8aa3b, v127
	v_mul_f32_e32 v135, 0xbfb8aa3b, v120
	v_mul_f32_e32 v161, 0xbfb8aa3b, v121
	v_mul_f32_e32 v170, 0xbfb8aa3b, v122
	v_mul_f32_e32 v172, 0xbfb8aa3b, v123
	v_mul_f32_e32 v180, 0xbfb8aa3b, v109
	v_mul_f32_e32 v181, 0xbfb8aa3b, v104
	v_mul_f32_e32 v182, 0xbfb8aa3b, v105
	v_exp_f32_e32 v110, v110
	v_exp_f32_e32 v111, v111
	v_exp_f32_e32 v129, v129
	v_exp_f32_e32 v133, v133
	v_exp_f32_e32 v135, v135
	v_exp_f32_e32 v161, v161
	v_exp_f32_e32 v170, v170
	v_exp_f32_e32 v172, v172
	v_exp_f32_e32 v180, v180
	v_exp_f32_e32 v181, v181
	v_exp_f32_e32 v182, v182
	v_add_f32_e32 v110, 1.0, v110
	v_add_f32_e32 v111, 1.0, v111
	v_add_f32_e32 v129, 1.0, v129
	v_add_f32_e32 v133, 1.0, v133
	v_add_f32_e32 v135, 1.0, v135
	v_add_f32_e32 v161, 1.0, v161
	v_add_f32_e32 v170, 1.0, v170
	v_add_f32_e32 v172, 1.0, v172
	v_add_f32_e32 v189, 1.0, v180
	v_add_f32_e32 v190, 1.0, v181
	v_add_f32_e32 v191, 1.0, v182
	v_rcp_f32_e32 v110, v110
	v_rcp_f32_e32 v111, v111
	v_rcp_f32_e32 v180, v129
	v_rcp_f32_e32 v181, v133
	v_rcp_f32_e32 v182, v135
	v_rcp_f32_e32 v183, v161
	v_rcp_f32_e32 v186, v170
	v_rcp_f32_e32 v187, v172
	v_pk_mul_f32 v[110:111], v[124:125], v[110:111]
	v_pk_mul_f32 v[124:125], v[126:127], v[180:181]
	v_pk_mul_f32 v[120:121], v[120:121], v[182:183]
	v_pk_mul_f32 v[122:123], v[122:123], v[186:187]
	v_pk_mul_f32 v[110:111], v[116:117], v[110:111]
	v_pk_mul_f32 v[116:117], v[118:119], v[124:125]
	v_pk_mul_f32 v[112:113], v[112:113], v[120:121]
	v_pk_mul_f32 v[114:115], v[114:115], v[122:123]
	v_rcp_f32_e32 v190, v190
	v_rcp_f32_e32 v191, v191
	v_cvt_pk_bf16_f32 v110, v110, v111
	v_cvt_pk_bf16_f32 v111, v116, v117
	v_cvt_pk_bf16_f32 v112, v112, v113
	v_cvt_pk_bf16_f32 v113, v114, v115
	v_pk_mul_f32 v[100:101], v[100:101], v[166:167] op_sel_hi:[1,0]
	global_store_dwordx4 v[168:169], v[110:113], off nt
	v_pk_mul_f32 v[106:107], v[106:107], v[166:167] op_sel_hi:[1,0]
	v_pk_mul_f32 v[104:105], v[104:105], v[190:191]
	v_mul_f32_e32 v110, 0xbfb8aa3b, v100
	v_exp_f32_e32 v110, v110
	v_pk_mul_f32 v[104:105], v[106:107], v[104:105]
	v_mul_f32_e32 v106, 0xbfb8aa3b, v101
	v_pk_mul_f32 v[102:103], v[102:103], v[166:167] op_sel_hi:[1,0]
	v_mul_f32_e32 v174, 0xbfb8aa3b, v108
	v_exp_f32_e32 v107, v106
	v_add_f32_e32 v106, 1.0, v110
	v_mul_f32_e32 v110, 0xbfb8aa3b, v102
	v_mul_f32_e32 v111, 0xbfb8aa3b, v103
	v_exp_f32_e32 v174, v174
	v_exp_f32_e32 v110, v110
	v_exp_f32_e32 v111, v111
	v_add_f32_e32 v107, 1.0, v107
	v_add_f32_e32 v174, 1.0, v174
	v_rcp_f32_e32 v106, v106
	v_rcp_f32_e32 v107, v107
	v_add_f32_e32 v110, 1.0, v110
	v_add_f32_e32 v111, 1.0, v111
	v_rcp_f32_e32 v188, v174
	v_rcp_f32_e32 v189, v189
	v_rcp_f32_e32 v110, v110
	v_rcp_f32_e32 v111, v111
	v_pk_mul_f32 v[96:97], v[96:97], v[166:167] op_sel_hi:[1,0]
	v_pk_mul_f32 v[100:101], v[100:101], v[106:107]
	v_pk_mul_f32 v[108:109], v[108:109], v[188:189]
	v_pk_mul_f32 v[100:101], v[96:97], v[100:101]
	v_pk_mul_f32 v[96:97], v[98:99], v[166:167] op_sel_hi:[1,0]
	v_pk_mul_f32 v[98:99], v[102:103], v[110:111]
	v_pk_mul_f32 v[108:109], v[178:179], v[108:109]
	v_pk_mul_f32 v[102:103], v[96:97], v[98:99]
	v_or_b32_e32 v106, 16, v128
	v_cvt_pk_bf16_f32 v96, v108, v109
	v_cvt_pk_bf16_f32 v97, v104, v105
	v_cvt_pk_bf16_f32 v98, v100, v101
	v_cvt_pk_bf16_f32 v99, v102, v103
	v_mad_i64_i32 v[100:101], s[14:15], v106, s75, v[130:131]
	v_pk_mul_f32 v[92:93], v[92:93], v[164:165] op_sel_hi:[1,0]
	global_store_dwordx4 v[100:101], v[96:99], off nt
	v_mul_f32_e32 v102, 0xbfb8aa3b, v92
	v_pk_mul_f32 v[94:95], v[94:95], v[164:165] op_sel_hi:[1,0]
	v_mul_f32_e32 v96, 0xbfb8aa3b, v93
	v_exp_f32_e32 v102, v102
	v_exp_f32_e32 v97, v96
	v_mul_f32_e32 v98, 0xbfb8aa3b, v94
	v_mul_f32_e32 v99, 0xbfb8aa3b, v95
	v_exp_f32_e32 v98, v98
	v_exp_f32_e32 v99, v99
	v_add_f32_e32 v96, 1.0, v102
	v_add_f32_e32 v97, 1.0, v97
	v_rcp_f32_e32 v96, v96
	v_rcp_f32_e32 v97, v97
	v_add_f32_e32 v98, 1.0, v98
	v_add_f32_e32 v99, 1.0, v99
	v_rcp_f32_e32 v98, v98
	v_rcp_f32_e32 v99, v99
	v_pk_mul_f32 v[88:89], v[88:89], v[164:165] op_sel_hi:[1,0]
	v_pk_mul_f32 v[92:93], v[92:93], v[96:97]
	v_pk_mul_f32 v[84:85], v[84:85], v[164:165] op_sel_hi:[1,0]
	v_pk_mul_f32 v[88:89], v[88:89], v[92:93]
	v_pk_mul_f32 v[92:93], v[94:95], v[98:99]
	v_mul_f32_e32 v94, 0xbfb8aa3b, v84
	v_exp_f32_e32 v94, v94
	v_pk_mul_f32 v[90:91], v[90:91], v[164:165] op_sel_hi:[1,0]
	v_pk_mul_f32 v[86:87], v[86:87], v[164:165] op_sel_hi:[1,0]
	v_pk_mul_f32 v[90:91], v[90:91], v[92:93]
	v_mul_f32_e32 v92, 0xbfb8aa3b, v85
	v_exp_f32_e32 v93, v92
	v_add_f32_e32 v92, 1.0, v94
	v_mul_f32_e32 v94, 0xbfb8aa3b, v86
	v_mul_f32_e32 v95, 0xbfb8aa3b, v87
	v_exp_f32_e32 v94, v94
	v_exp_f32_e32 v95, v95
	v_add_f32_e32 v93, 1.0, v93
	v_rcp_f32_e32 v92, v92
	v_rcp_f32_e32 v93, v93
	v_add_f32_e32 v94, 1.0, v94
	v_add_f32_e32 v95, 1.0, v95
	v_rcp_f32_e32 v94, v94
	v_rcp_f32_e32 v95, v95
	v_pk_mul_f32 v[80:81], v[80:81], v[164:165] op_sel_hi:[1,0]
	v_pk_mul_f32 v[84:85], v[84:85], v[92:93]
	v_or_b32_e32 v92, 32, v128
	v_pk_mul_f32 v[84:85], v[80:81], v[84:85]
	v_pk_mul_f32 v[80:81], v[82:83], v[164:165] op_sel_hi:[1,0]
	v_pk_mul_f32 v[82:83], v[86:87], v[94:95]
	v_pk_mul_f32 v[76:77], v[76:77], v[162:163] op_sel_hi:[1,0]
	v_pk_mul_f32 v[86:87], v[80:81], v[82:83]
	v_cvt_pk_bf16_f32 v80, v88, v89
	v_cvt_pk_bf16_f32 v81, v90, v91
	v_cvt_pk_bf16_f32 v82, v84, v85
	v_cvt_pk_bf16_f32 v83, v86, v87
	v_mad_i64_i32 v[84:85], s[14:15], v92, s75, v[130:131]
	v_mul_f32_e32 v86, 0xbfb8aa3b, v76
	global_store_dwordx4 v[84:85], v[80:83], off nt
	v_pk_mul_f32 v[78:79], v[78:79], v[162:163] op_sel_hi:[1,0]
	v_exp_f32_e32 v86, v86
	v_mul_f32_e32 v80, 0xbfb8aa3b, v77
	v_exp_f32_e32 v81, v80
	v_mul_f32_e32 v82, 0xbfb8aa3b, v78
	v_mul_f32_e32 v83, 0xbfb8aa3b, v79
	v_exp_f32_e32 v82, v82
	v_exp_f32_e32 v83, v83
	v_add_f32_e32 v80, 1.0, v86
	v_add_f32_e32 v81, 1.0, v81
	v_rcp_f32_e32 v80, v80
	v_rcp_f32_e32 v81, v81
	v_add_f32_e32 v82, 1.0, v82
	v_add_f32_e32 v83, 1.0, v83
	v_rcp_f32_e32 v82, v82
	v_rcp_f32_e32 v83, v83
	v_pk_mul_f32 v[72:73], v[72:73], v[162:163] op_sel_hi:[1,0]
	v_pk_mul_f32 v[76:77], v[76:77], v[80:81]
	v_pk_mul_f32 v[68:69], v[68:69], v[162:163] op_sel_hi:[1,0]
	v_pk_mul_f32 v[72:73], v[72:73], v[76:77]
	v_pk_mul_f32 v[76:77], v[78:79], v[82:83]
	v_mul_f32_e32 v78, 0xbfb8aa3b, v68
	v_exp_f32_e32 v78, v78
	v_pk_mul_f32 v[74:75], v[74:75], v[162:163] op_sel_hi:[1,0]
	v_pk_mul_f32 v[70:71], v[70:71], v[162:163] op_sel_hi:[1,0]
	v_pk_mul_f32 v[74:75], v[74:75], v[76:77]
	v_mul_f32_e32 v76, 0xbfb8aa3b, v69
	v_exp_f32_e32 v77, v76
	v_add_f32_e32 v76, 1.0, v78
	v_mul_f32_e32 v78, 0xbfb8aa3b, v70
	v_mul_f32_e32 v79, 0xbfb8aa3b, v71
	v_exp_f32_e32 v78, v78
	v_exp_f32_e32 v79, v79
	v_add_f32_e32 v77, 1.0, v77
	v_rcp_f32_e32 v76, v76
	v_rcp_f32_e32 v77, v77
	v_add_f32_e32 v78, 1.0, v78
	v_add_f32_e32 v79, 1.0, v79
	v_rcp_f32_e32 v78, v78
	v_rcp_f32_e32 v79, v79
	v_pk_mul_f32 v[64:65], v[64:65], v[162:163] op_sel_hi:[1,0]
	v_pk_mul_f32 v[68:69], v[68:69], v[76:77]
	v_or_b32_e32 v76, 48, v128
	v_pk_mul_f32 v[68:69], v[64:65], v[68:69]
	v_pk_mul_f32 v[64:65], v[66:67], v[162:163] op_sel_hi:[1,0]
	v_pk_mul_f32 v[66:67], v[70:71], v[78:79]
	v_pk_mul_f32 v[60:61], v[60:61], v[160:161] op_sel_hi:[1,0]
	v_pk_mul_f32 v[70:71], v[64:65], v[66:67]
	v_cvt_pk_bf16_f32 v64, v72, v73
	v_cvt_pk_bf16_f32 v65, v74, v75
	v_cvt_pk_bf16_f32 v66, v68, v69
	v_cvt_pk_bf16_f32 v67, v70, v71
	v_mad_i64_i32 v[68:69], s[14:15], v76, s75, v[130:131]
	global_store_dwordx4 v[68:69], v[64:67], off nt
	v_pk_mul_f32 v[62:63], v[62:63], v[160:161] op_sel_hi:[1,0]
	v_pk_mul_f32 v[56:57], v[56:57], v[160:161] op_sel_hi:[1,0]
	v_mul_f32_e32 v64, 0xbfb8aa3b, v60
	v_mul_f32_e32 v65, 0xbfb8aa3b, v61
	v_exp_f32_e32 v64, v64
	v_exp_f32_e32 v65, v65
	v_mul_f32_e32 v66, 0xbfb8aa3b, v62
	v_mul_f32_e32 v67, 0xbfb8aa3b, v63
	v_exp_f32_e32 v66, v66
	v_exp_f32_e32 v67, v67
	v_add_f32_e32 v64, 1.0, v64
	v_add_f32_e32 v65, 1.0, v65
	v_rcp_f32_e32 v64, v64
	v_rcp_f32_e32 v65, v65
	v_add_f32_e32 v66, 1.0, v66
	v_add_f32_e32 v67, 1.0, v67
	v_rcp_f32_e32 v66, v66
	v_rcp_f32_e32 v67, v67
	v_pk_mul_f32 v[60:61], v[60:61], v[64:65]
	v_pk_mul_f32 v[52:53], v[52:53], v[160:161] op_sel_hi:[1,0]
	v_pk_mul_f32 v[56:57], v[56:57], v[60:61]
	v_pk_mul_f32 v[60:61], v[62:63], v[66:67]
	v_mul_f32_e32 v62, 0xbfb8aa3b, v52
	v_exp_f32_e32 v62, v62
	v_pk_mul_f32 v[58:59], v[58:59], v[160:161] op_sel_hi:[1,0]
	v_pk_mul_f32 v[54:55], v[54:55], v[160:161] op_sel_hi:[1,0]
	v_pk_mul_f32 v[58:59], v[58:59], v[60:61]
	v_mul_f32_e32 v60, 0xbfb8aa3b, v53
	v_exp_f32_e32 v61, v60
	v_add_f32_e32 v60, 1.0, v62
	v_mul_f32_e32 v62, 0xbfb8aa3b, v54
	v_mul_f32_e32 v63, 0xbfb8aa3b, v55
	v_exp_f32_e32 v62, v62
	v_exp_f32_e32 v63, v63
	v_add_f32_e32 v61, 1.0, v61
	v_rcp_f32_e32 v60, v60
	v_rcp_f32_e32 v61, v61
	v_add_f32_e32 v62, 1.0, v62
	v_add_f32_e32 v63, 1.0, v63
	v_rcp_f32_e32 v62, v62
	v_rcp_f32_e32 v63, v63
	v_rsq_f32_e32 v144, v144
	v_pk_mul_f32 v[48:49], v[48:49], v[160:161] op_sel_hi:[1,0]
	v_pk_mul_f32 v[52:53], v[52:53], v[60:61]
	v_add_u32_e32 v68, 0x80, v128
	v_pk_mul_f32 v[52:53], v[48:49], v[52:53]
	v_pk_mul_f32 v[48:49], v[50:51], v[160:161] op_sel_hi:[1,0]
	v_pk_mul_f32 v[50:51], v[54:55], v[62:63]
	v_pk_mul_f32 v[44:45], v[44:45], v[144:145] op_sel_hi:[1,0]
	v_pk_mul_f32 v[54:55], v[48:49], v[50:51]
	v_cvt_pk_bf16_f32 v48, v56, v57
	v_cvt_pk_bf16_f32 v49, v58, v59
	v_cvt_pk_bf16_f32 v50, v52, v53
	v_cvt_pk_bf16_f32 v51, v54, v55
	v_mad_i64_i32 v[52:53], s[14:15], v68, s75, v[130:131]
	v_mul_f32_e32 v54, 0xbfb8aa3b, v44
	global_store_dwordx4 v[52:53], v[48:51], off nt
	v_pk_mul_f32 v[46:47], v[46:47], v[144:145] op_sel_hi:[1,0]
	v_exp_f32_e32 v54, v54
	v_mul_f32_e32 v48, 0xbfb8aa3b, v45
	v_exp_f32_e32 v49, v48
	v_mul_f32_e32 v50, 0xbfb8aa3b, v46
	v_mul_f32_e32 v51, 0xbfb8aa3b, v47
	v_exp_f32_e32 v50, v50
	v_exp_f32_e32 v51, v51
	v_add_f32_e32 v48, 1.0, v54
	v_add_f32_e32 v49, 1.0, v49
	v_rcp_f32_e32 v48, v48
	v_rcp_f32_e32 v49, v49
	v_add_f32_e32 v50, 1.0, v50
	v_add_f32_e32 v51, 1.0, v51
	v_rcp_f32_e32 v50, v50
	v_rcp_f32_e32 v51, v51
	v_pk_mul_f32 v[40:41], v[40:41], v[144:145] op_sel_hi:[1,0]
	v_pk_mul_f32 v[44:45], v[44:45], v[48:49]
	v_pk_mul_f32 v[36:37], v[36:37], v[144:145] op_sel_hi:[1,0]
	v_pk_mul_f32 v[40:41], v[40:41], v[44:45]
	v_pk_mul_f32 v[44:45], v[46:47], v[50:51]
	v_mul_f32_e32 v46, 0xbfb8aa3b, v36
	v_exp_f32_e32 v46, v46
	v_pk_mul_f32 v[42:43], v[42:43], v[144:145] op_sel_hi:[1,0]
	v_pk_mul_f32 v[38:39], v[38:39], v[144:145] op_sel_hi:[1,0]
	v_pk_mul_f32 v[42:43], v[42:43], v[44:45]
	v_mul_f32_e32 v44, 0xbfb8aa3b, v37
	v_exp_f32_e32 v45, v44
	v_add_f32_e32 v44, 1.0, v46
	v_mul_f32_e32 v46, 0xbfb8aa3b, v38
	v_mul_f32_e32 v47, 0xbfb8aa3b, v39
	v_exp_f32_e32 v46, v46
	v_exp_f32_e32 v47, v47
	v_add_f32_e32 v45, 1.0, v45
	v_rcp_f32_e32 v44, v44
	v_rcp_f32_e32 v45, v45
	v_add_f32_e32 v46, 1.0, v46
	v_add_f32_e32 v47, 1.0, v47
	v_rcp_f32_e32 v46, v46
	v_rcp_f32_e32 v47, v47
	v_pk_mul_f32 v[32:33], v[32:33], v[144:145] op_sel_hi:[1,0]
	v_pk_mul_f32 v[36:37], v[36:37], v[44:45]
	v_add_u32_e32 v44, 0x90, v128
	v_pk_mul_f32 v[36:37], v[32:33], v[36:37]
	v_pk_mul_f32 v[32:33], v[34:35], v[144:145] op_sel_hi:[1,0]
	v_pk_mul_f32 v[34:35], v[38:39], v[46:47]
	v_pk_mul_f32 v[28:29], v[28:29], v[134:135] op_sel_hi:[1,0]
	v_pk_mul_f32 v[38:39], v[32:33], v[34:35]
	v_cvt_pk_bf16_f32 v32, v40, v41
	v_cvt_pk_bf16_f32 v33, v42, v43
	v_cvt_pk_bf16_f32 v34, v36, v37
	v_cvt_pk_bf16_f32 v35, v38, v39
	v_mad_i64_i32 v[36:37], s[14:15], v44, s75, v[130:131]
	v_mul_f32_e32 v38, 0xbfb8aa3b, v28
	global_store_dwordx4 v[36:37], v[32:35], off nt
	v_pk_mul_f32 v[30:31], v[30:31], v[134:135] op_sel_hi:[1,0]
	v_exp_f32_e32 v38, v38
	v_mul_f32_e32 v32, 0xbfb8aa3b, v29
	v_exp_f32_e32 v33, v32
	v_mul_f32_e32 v34, 0xbfb8aa3b, v30
	v_mul_f32_e32 v35, 0xbfb8aa3b, v31
	v_exp_f32_e32 v34, v34
	v_exp_f32_e32 v35, v35
	v_add_f32_e32 v32, 1.0, v38
	v_add_f32_e32 v33, 1.0, v33
	v_rcp_f32_e32 v32, v32
	v_rcp_f32_e32 v33, v33
	v_add_f32_e32 v34, 1.0, v34
	v_add_f32_e32 v35, 1.0, v35
	v_rcp_f32_e32 v34, v34
	v_rcp_f32_e32 v35, v35
	v_pk_mul_f32 v[24:25], v[24:25], v[134:135] op_sel_hi:[1,0]
	v_pk_mul_f32 v[28:29], v[28:29], v[32:33]
	v_pk_mul_f32 v[20:21], v[20:21], v[134:135] op_sel_hi:[1,0]
	v_pk_mul_f32 v[24:25], v[24:25], v[28:29]
	v_pk_mul_f32 v[28:29], v[30:31], v[34:35]
	v_mul_f32_e32 v30, 0xbfb8aa3b, v20
	v_exp_f32_e32 v30, v30
	v_pk_mul_f32 v[26:27], v[26:27], v[134:135] op_sel_hi:[1,0]
	v_pk_mul_f32 v[22:23], v[22:23], v[134:135] op_sel_hi:[1,0]
	v_pk_mul_f32 v[26:27], v[26:27], v[28:29]
	v_mul_f32_e32 v28, 0xbfb8aa3b, v21
	v_exp_f32_e32 v29, v28
	v_add_f32_e32 v28, 1.0, v30
	v_mul_f32_e32 v30, 0xbfb8aa3b, v22
	v_mul_f32_e32 v31, 0xbfb8aa3b, v23
	v_exp_f32_e32 v30, v30
	v_exp_f32_e32 v31, v31
	v_add_f32_e32 v29, 1.0, v29
	v_rcp_f32_e32 v28, v28
	v_rcp_f32_e32 v29, v29
	v_add_f32_e32 v30, 1.0, v30
	v_add_f32_e32 v31, 1.0, v31
	v_rcp_f32_e32 v30, v30
	v_rcp_f32_e32 v31, v31
	v_pk_mul_f32 v[16:17], v[16:17], v[134:135] op_sel_hi:[1,0]
	v_pk_mul_f32 v[20:21], v[20:21], v[28:29]
	v_add_u32_e32 v28, 0xa0, v128
	v_pk_mul_f32 v[20:21], v[16:17], v[20:21]
	v_pk_mul_f32 v[16:17], v[18:19], v[134:135] op_sel_hi:[1,0]
	v_pk_mul_f32 v[18:19], v[22:23], v[30:31]
	v_pk_mul_f32 v[12:13], v[12:13], v[132:133] op_sel_hi:[1,0]
	v_pk_mul_f32 v[22:23], v[16:17], v[18:19]
	v_cvt_pk_bf16_f32 v16, v24, v25
	v_cvt_pk_bf16_f32 v17, v26, v27
	v_cvt_pk_bf16_f32 v18, v20, v21
	v_cvt_pk_bf16_f32 v19, v22, v23
	v_mad_i64_i32 v[20:21], s[14:15], v28, s75, v[130:131]
	v_mul_f32_e32 v22, 0xbfb8aa3b, v12
	global_store_dwordx4 v[20:21], v[16:19], off nt
	v_pk_mul_f32 v[14:15], v[14:15], v[132:133] op_sel_hi:[1,0]
	v_exp_f32_e32 v22, v22
	v_mul_f32_e32 v16, 0xbfb8aa3b, v13
	v_exp_f32_e32 v17, v16
	v_mul_f32_e32 v18, 0xbfb8aa3b, v14
	v_mul_f32_e32 v19, 0xbfb8aa3b, v15
	v_exp_f32_e32 v18, v18
	v_exp_f32_e32 v19, v19
	v_add_f32_e32 v16, 1.0, v22
	v_add_f32_e32 v17, 1.0, v17
	v_rcp_f32_e32 v16, v16
	v_rcp_f32_e32 v17, v17
	v_add_f32_e32 v18, 1.0, v18
	v_add_f32_e32 v19, 1.0, v19
	v_rcp_f32_e32 v18, v18
	v_rcp_f32_e32 v19, v19
	v_pk_mul_f32 v[8:9], v[8:9], v[132:133] op_sel_hi:[1,0]
	v_pk_mul_f32 v[12:13], v[12:13], v[16:17]
	v_pk_mul_f32 v[4:5], v[4:5], v[132:133] op_sel_hi:[1,0]
	v_pk_mul_f32 v[8:9], v[8:9], v[12:13]
	v_pk_mul_f32 v[12:13], v[14:15], v[18:19]
	v_mul_f32_e32 v14, 0xbfb8aa3b, v4
	v_exp_f32_e32 v14, v14
	v_pk_mul_f32 v[10:11], v[10:11], v[132:133] op_sel_hi:[1,0]
	v_pk_mul_f32 v[6:7], v[6:7], v[132:133] op_sel_hi:[1,0]
	v_pk_mul_f32 v[10:11], v[10:11], v[12:13]
	v_mul_f32_e32 v12, 0xbfb8aa3b, v5
	v_exp_f32_e32 v13, v12
	v_add_f32_e32 v12, 1.0, v14
	v_mul_f32_e32 v14, 0xbfb8aa3b, v6
	v_mul_f32_e32 v15, 0xbfb8aa3b, v7
	v_exp_f32_e32 v14, v14
	v_exp_f32_e32 v15, v15
	v_add_f32_e32 v13, 1.0, v13
	v_rcp_f32_e32 v12, v12
	v_rcp_f32_e32 v13, v13
	v_add_f32_e32 v14, 1.0, v14
	v_add_f32_e32 v15, 1.0, v15
	v_rcp_f32_e32 v14, v14
	v_rcp_f32_e32 v15, v15
	v_pk_mul_f32 v[0:1], v[0:1], v[132:133] op_sel_hi:[1,0]
	v_pk_mul_f32 v[4:5], v[4:5], v[12:13]
	v_add_u32_e32 v12, 0xb0, v128
	v_pk_mul_f32 v[4:5], v[0:1], v[4:5]
	v_pk_mul_f32 v[0:1], v[2:3], v[132:133] op_sel_hi:[1,0]
	v_pk_mul_f32 v[2:3], v[6:7], v[14:15]
	s_nop 0
	v_pk_mul_f32 v[6:7], v[0:1], v[2:3]
	v_cvt_pk_bf16_f32 v0, v8, v9
	v_cvt_pk_bf16_f32 v1, v10, v11
	v_cvt_pk_bf16_f32 v2, v4, v5
	v_cvt_pk_bf16_f32 v3, v6, v7
	v_mad_i64_i32 v[4:5], s[14:15], v12, s75, v[130:131]
	global_store_dwordx4 v[4:5], v[0:3], off nt
	s_andn2_b64 vcc, exec, s[4:5]
	s_mov_b64 s[4:5], -1
	s_cbranch_vccnz .LBB0_1409
	s_branch .LBB0_1425

.LBB0_1419:
	s_cmp_gt_i32 s80, 3
	s_cbranch_scc0 .LBB0_1421
	v_lshl_add_u32 v128, s36, 8, v163
	v_ashrrev_i32_e32 v129, 31, v128
	v_lshl_add_u64 v[130:131], v[128:129], 2, s[10:11]
	s_waitcnt vmcnt(0)
	v_mov_b32_e32 v132, v243
	v_mov_b32_e32 v133, v244
	v_mov_b32_e32 v134, v245
	v_mov_b32_e32 v135, v246
	v_mov_b32_e32 v164, v247
	v_mov_b32_e32 v166, v248
	v_mov_b32_e32 v168, v249
	s_nop 0
	v_mov_b32_e32 v130, v250
	v_lshrrev_b32_e32 v129, 20, v129
	v_add_u32_e32 v129, v128, v129
	s_lshl_b32 s14, s80, 2
	v_ashrrev_i32_e32 v129, 12, v129
	s_add_i32 s14, s71, s14
	s_mov_b64 s[38:39], 0
	s_waitcnt vmcnt(0)
	v_fmamk_f32 v131, v132, 0x3a800000, v176
	v_rsq_f32_e32 v162, v131
	v_fmamk_f32 v131, v133, 0x3a800000, v176
	v_rsq_f32_e32 v161, v131
	v_fmamk_f32 v131, v134, 0x3a800000, v176
	v_rsq_f32_e32 v160, v131
	v_fmamk_f32 v131, v135, 0x3a800000, v176
	v_rsq_f32_e32 v144, v131
	v_fmamk_f32 v131, v164, 0x3a800000, v176
	v_fmamk_f32 v130, v130, 0x3a800000, v176
	v_rsq_f32_e32 v135, v131
	v_fmamk_f32 v131, v166, 0x3a800000, v176
	v_rsq_f32_e32 v132, v130
	v_mul_i32_i24_e32 v130, 0x1000, v129
	v_rsq_f32_e32 v134, v131
	v_fmamk_f32 v131, v168, 0x3a800000, v176
	v_sub_u32_e32 v128, v128, v130
	v_lshl_add_u32 v130, v129, 4, s14
	v_rsq_f32_e32 v133, v131
	v_ashrrev_i32_e32 v131, 31, v130
	v_lshlrev_b64 v[130:131], 19, v[130:131]
	v_lshl_add_u64 v[130:131], v[146:147], 0, v[130:131]
	v_ashrrev_i32_e32 v129, 31, v128
	v_lshl_add_u64 v[128:129], v[128:129], 1, v[130:131]
	v_mul_f32_e32 v130, v124, v162
	v_cvt_pk_bf16_f32 v130, v130, s0
	global_store_short v[128:129], v130, off
	v_mul_f32_e32 v130, v108, v161
	v_cvt_pk_bf16_f32 v130, v130, s0
	global_store_short v[128:129], v130, off offset:32
	v_mul_f32_e32 v130, v92, v160
	v_cvt_pk_bf16_f32 v130, v130, s0
	global_store_short v[128:129], v130, off offset:64
	v_mul_f32_e32 v130, v76, v144
	v_cvt_pk_bf16_f32 v130, v130, s0
	global_store_short v[128:129], v130, off offset:96
	v_mul_f32_e32 v130, v60, v135
	v_cvt_pk_bf16_f32 v130, v130, s0
	global_store_short v[128:129], v130, off offset:256
	v_mul_f32_e32 v130, v44, v134
	v_cvt_pk_bf16_f32 v130, v130, s0
	global_store_short v[128:129], v130, off offset:288
	v_mul_f32_e32 v130, v28, v133
	v_cvt_pk_bf16_f32 v130, v130, s0
	global_store_short v[128:129], v130, off offset:320
	v_mul_f32_e32 v130, v12, v132
	v_cvt_pk_bf16_f32 v130, v130, s0
	global_store_short v[128:129], v130, off offset:352
	v_mul_f32_e32 v130, v125, v162
	s_movk_i32 s14, 0x2000
	v_cvt_pk_bf16_f32 v164, v130, s0
	v_add_co_u32_e32 v130, vcc, s14, v128
	s_movk_i32 s14, 0x4000
	s_nop 0
	v_addc_co_u32_e32 v131, vcc, 0, v129, vcc
	global_store_short v[130:131], v164, off
	v_mul_f32_e32 v164, v109, v161
	v_cvt_pk_bf16_f32 v164, v164, s0
	global_store_short v[130:131], v164, off offset:32
	v_mul_f32_e32 v164, v93, v160
	v_cvt_pk_bf16_f32 v164, v164, s0
	global_store_short v[130:131], v164, off offset:64
	v_mul_f32_e32 v164, v77, v144
	v_cvt_pk_bf16_f32 v164, v164, s0
	global_store_short v[130:131], v164, off offset:96
	v_mul_f32_e32 v164, v61, v135
	v_cvt_pk_bf16_f32 v164, v164, s0
	global_store_short v[130:131], v164, off offset:256
	v_mul_f32_e32 v164, v45, v134
	v_cvt_pk_bf16_f32 v164, v164, s0
	global_store_short v[130:131], v164, off offset:288
	v_mul_f32_e32 v164, v29, v133
	v_cvt_pk_bf16_f32 v164, v164, s0
	global_store_short v[130:131], v164, off offset:320
	v_mul_f32_e32 v164, v13, v132
	v_cvt_pk_bf16_f32 v164, v164, s0
	global_store_short v[130:131], v164, off offset:352
	v_mul_f32_e32 v130, v126, v162
	v_cvt_pk_bf16_f32 v164, v130, s0
	v_add_co_u32_e32 v130, vcc, s14, v128
	s_movk_i32 s14, 0x6000
	s_nop 0
	v_addc_co_u32_e32 v131, vcc, 0, v129, vcc
	global_store_short v[130:131], v164, off
	v_mul_f32_e32 v164, v110, v161
	v_cvt_pk_bf16_f32 v164, v164, s0
	global_store_short v[130:131], v164, off offset:32
	v_mul_f32_e32 v164, v94, v160
	v_cvt_pk_bf16_f32 v164, v164, s0
	global_store_short v[130:131], v164, off offset:64
	v_mul_f32_e32 v164, v78, v144
	v_cvt_pk_bf16_f32 v164, v164, s0
	global_store_short v[130:131], v164, off offset:96
	v_mul_f32_e32 v164, v62, v135
	v_cvt_pk_bf16_f32 v164, v164, s0
	global_store_short v[130:131], v164, off offset:256
	v_mul_f32_e32 v164, v46, v134
	v_cvt_pk_bf16_f32 v164, v164, s0
	global_store_short v[130:131], v164, off offset:288
	v_mul_f32_e32 v164, v30, v133
	v_cvt_pk_bf16_f32 v164, v164, s0
	global_store_short v[130:131], v164, off offset:320
	v_mul_f32_e32 v164, v14, v132
	v_cvt_pk_bf16_f32 v164, v164, s0
	global_store_short v[130:131], v164, off offset:352
	v_mul_f32_e32 v130, v127, v162
	v_cvt_pk_bf16_f32 v164, v130, s0
	v_add_co_u32_e32 v130, vcc, s14, v128
	s_mov_b32 s14, 0x8000
	s_nop 0
	v_addc_co_u32_e32 v131, vcc, 0, v129, vcc
	global_store_short v[130:131], v164, off
	v_mul_f32_e32 v164, v111, v161
	v_cvt_pk_bf16_f32 v164, v164, s0
	global_store_short v[130:131], v164, off offset:32
	v_mul_f32_e32 v164, v95, v160
	v_cvt_pk_bf16_f32 v164, v164, s0
	global_store_short v[130:131], v164, off offset:64
	v_mul_f32_e32 v164, v79, v144
	v_cvt_pk_bf16_f32 v164, v164, s0
	global_store_short v[130:131], v164, off offset:96
	v_mul_f32_e32 v164, v63, v135
	v_cvt_pk_bf16_f32 v164, v164, s0
	global_store_short v[130:131], v164, off offset:256
	v_mul_f32_e32 v164, v47, v134
	v_cvt_pk_bf16_f32 v164, v164, s0
	global_store_short v[130:131], v164, off offset:288
	v_mul_f32_e32 v164, v31, v133
	v_cvt_pk_bf16_f32 v164, v164, s0
	global_store_short v[130:131], v164, off offset:320
	v_mul_f32_e32 v164, v15, v132
	v_cvt_pk_bf16_f32 v164, v164, s0
	global_store_short v[130:131], v164, off offset:352
	v_mul_f32_e32 v130, v120, v162
	v_cvt_pk_bf16_f32 v164, v130, s0
	v_add_co_u32_e32 v130, vcc, s14, v128
	s_mov_b32 s14, 0xa000
	s_nop 0
	v_addc_co_u32_e32 v131, vcc, 0, v129, vcc
	global_store_short v[130:131], v164, off
	v_mul_f32_e32 v164, v100, v161
	v_cvt_pk_bf16_f32 v164, v164, s0
	global_store_short v[130:131], v164, off offset:32
	v_mul_f32_e32 v164, v84, v160
	v_cvt_pk_bf16_f32 v164, v164, s0
	global_store_short v[130:131], v164, off offset:64
	v_mul_f32_e32 v164, v68, v144
	v_cvt_pk_bf16_f32 v164, v164, s0
	global_store_short v[130:131], v164, off offset:96
	v_mul_f32_e32 v164, v52, v135
	v_cvt_pk_bf16_f32 v164, v164, s0
	global_store_short v[130:131], v164, off offset:256
	v_mul_f32_e32 v164, v36, v134
	v_cvt_pk_bf16_f32 v164, v164, s0
	global_store_short v[130:131], v164, off offset:288
	v_mul_f32_e32 v164, v20, v133
	v_cvt_pk_bf16_f32 v164, v164, s0
	global_store_short v[130:131], v164, off offset:320
	v_mul_f32_e32 v164, v4, v132
	v_cvt_pk_bf16_f32 v164, v164, s0
	global_store_short v[130:131], v164, off offset:352
	v_mul_f32_e32 v130, v121, v162
	v_cvt_pk_bf16_f32 v164, v130, s0
	v_add_co_u32_e32 v130, vcc, s14, v128
	s_mov_b32 s14, 0xc000
	s_nop 0
	v_addc_co_u32_e32 v131, vcc, 0, v129, vcc
	global_store_short v[130:131], v164, off
	v_mul_f32_e32 v164, v101, v161
	v_cvt_pk_bf16_f32 v164, v164, s0
	global_store_short v[130:131], v164, off offset:32
	v_mul_f32_e32 v164, v85, v160
	v_cvt_pk_bf16_f32 v164, v164, s0
	global_store_short v[130:131], v164, off offset:64
	v_mul_f32_e32 v164, v69, v144
	v_cvt_pk_bf16_f32 v164, v164, s0
	global_store_short v[130:131], v164, off offset:96
	v_mul_f32_e32 v164, v53, v135
	v_cvt_pk_bf16_f32 v164, v164, s0
	global_store_short v[130:131], v164, off offset:256
	v_mul_f32_e32 v164, v37, v134
	v_cvt_pk_bf16_f32 v164, v164, s0
	global_store_short v[130:131], v164, off offset:288
	v_mul_f32_e32 v164, v21, v133
	v_cvt_pk_bf16_f32 v164, v164, s0
	global_store_short v[130:131], v164, off offset:320
	v_mul_f32_e32 v164, v5, v132
	v_cvt_pk_bf16_f32 v164, v164, s0
	global_store_short v[130:131], v164, off offset:352
	v_mul_f32_e32 v130, v122, v162
	v_cvt_pk_bf16_f32 v164, v130, s0
	v_add_co_u32_e32 v130, vcc, s14, v128
	s_mov_b32 s14, 0xe000
	s_nop 0
	v_addc_co_u32_e32 v131, vcc, 0, v129, vcc
	global_store_short v[130:131], v164, off
	v_mul_f32_e32 v164, v102, v161
	v_cvt_pk_bf16_f32 v164, v164, s0
	global_store_short v[130:131], v164, off offset:32
	v_mul_f32_e32 v164, v86, v160
	v_cvt_pk_bf16_f32 v164, v164, s0
	global_store_short v[130:131], v164, off offset:64
	v_mul_f32_e32 v164, v70, v144
	v_cvt_pk_bf16_f32 v164, v164, s0
	global_store_short v[130:131], v164, off offset:96
	v_mul_f32_e32 v164, v54, v135
	v_cvt_pk_bf16_f32 v164, v164, s0
	global_store_short v[130:131], v164, off offset:256
	v_mul_f32_e32 v164, v38, v134
	v_cvt_pk_bf16_f32 v164, v164, s0
	global_store_short v[130:131], v164, off offset:288
	v_mul_f32_e32 v164, v22, v133
	v_cvt_pk_bf16_f32 v164, v164, s0
	global_store_short v[130:131], v164, off offset:320
	v_mul_f32_e32 v164, v6, v132
	v_cvt_pk_bf16_f32 v164, v164, s0
	global_store_short v[130:131], v164, off offset:352
	v_mul_f32_e32 v130, v123, v162
	v_cvt_pk_bf16_f32 v164, v130, s0
	v_add_co_u32_e32 v130, vcc, s14, v128
	s_mov_b32 s14, 0x40000
	s_nop 0
	v_addc_co_u32_e32 v131, vcc, 0, v129, vcc
	global_store_short v[130:131], v164, off
	v_mul_f32_e32 v164, v103, v161
	v_cvt_pk_bf16_f32 v164, v164, s0
	global_store_short v[130:131], v164, off offset:32
	v_mul_f32_e32 v164, v87, v160
	v_cvt_pk_bf16_f32 v164, v164, s0
	global_store_short v[130:131], v164, off offset:64
	v_mul_f32_e32 v164, v71, v144
	v_cvt_pk_bf16_f32 v164, v164, s0
	global_store_short v[130:131], v164, off offset:96
	v_mul_f32_e32 v164, v55, v135
	v_cvt_pk_bf16_f32 v164, v164, s0
	global_store_short v[130:131], v164, off offset:256
	v_mul_f32_e32 v164, v39, v134
	v_cvt_pk_bf16_f32 v164, v164, s0
	global_store_short v[130:131], v164, off offset:288
	v_mul_f32_e32 v164, v23, v133
	v_cvt_pk_bf16_f32 v164, v164, s0
	global_store_short v[130:131], v164, off offset:320
	v_mul_f32_e32 v164, v7, v132
	v_cvt_pk_bf16_f32 v164, v164, s0
	global_store_short v[130:131], v164, off offset:352
	v_mul_f32_e32 v130, v116, v162
	v_cvt_pk_bf16_f32 v164, v130, s0
	v_add_co_u32_e32 v130, vcc, s14, v128
	s_mov_b32 s14, 0x42000
	s_nop 0
	v_addc_co_u32_e32 v131, vcc, 0, v129, vcc
	global_store_short v[130:131], v164, off
	v_mul_f32_e32 v164, v104, v161
	v_cvt_pk_bf16_f32 v164, v164, s0
	global_store_short v[130:131], v164, off offset:32
	v_mul_f32_e32 v164, v88, v160
	v_cvt_pk_bf16_f32 v164, v164, s0
	global_store_short v[130:131], v164, off offset:64
	v_mul_f32_e32 v164, v72, v144
	v_cvt_pk_bf16_f32 v164, v164, s0
	global_store_short v[130:131], v164, off offset:96
	v_mul_f32_e32 v164, v56, v135
	v_cvt_pk_bf16_f32 v164, v164, s0
	global_store_short v[130:131], v164, off offset:256
	v_mul_f32_e32 v164, v40, v134
	v_cvt_pk_bf16_f32 v164, v164, s0
	global_store_short v[130:131], v164, off offset:288
	v_mul_f32_e32 v164, v24, v133
	v_cvt_pk_bf16_f32 v164, v164, s0
	global_store_short v[130:131], v164, off offset:320
	v_mul_f32_e32 v164, v8, v132
	v_cvt_pk_bf16_f32 v164, v164, s0
	global_store_short v[130:131], v164, off offset:352
	v_mul_f32_e32 v130, v117, v162
	v_cvt_pk_bf16_f32 v164, v130, s0
	v_add_co_u32_e32 v130, vcc, s14, v128
	s_mov_b32 s14, 0x44000
	s_nop 0
	v_addc_co_u32_e32 v131, vcc, 0, v129, vcc
	global_store_short v[130:131], v164, off
	v_mul_f32_e32 v164, v105, v161
	v_cvt_pk_bf16_f32 v164, v164, s0
	global_store_short v[130:131], v164, off offset:32
	v_mul_f32_e32 v164, v89, v160
	v_cvt_pk_bf16_f32 v164, v164, s0
	global_store_short v[130:131], v164, off offset:64
	v_mul_f32_e32 v164, v73, v144
	v_cvt_pk_bf16_f32 v164, v164, s0
	global_store_short v[130:131], v164, off offset:96
	v_mul_f32_e32 v164, v57, v135
	v_cvt_pk_bf16_f32 v164, v164, s0
	global_store_short v[130:131], v164, off offset:256
	v_mul_f32_e32 v164, v41, v134
	v_cvt_pk_bf16_f32 v164, v164, s0
	global_store_short v[130:131], v164, off offset:288
	v_mul_f32_e32 v164, v25, v133
	v_cvt_pk_bf16_f32 v164, v164, s0
	global_store_short v[130:131], v164, off offset:320
	v_mul_f32_e32 v164, v9, v132
	v_cvt_pk_bf16_f32 v164, v164, s0
	global_store_short v[130:131], v164, off offset:352
	v_mul_f32_e32 v130, v118, v162
	v_cvt_pk_bf16_f32 v164, v130, s0
	v_add_co_u32_e32 v130, vcc, s14, v128
	s_mov_b32 s14, 0x46000
	s_nop 0
	v_addc_co_u32_e32 v131, vcc, 0, v129, vcc
	global_store_short v[130:131], v164, off
	v_mul_f32_e32 v164, v106, v161
	v_cvt_pk_bf16_f32 v164, v164, s0
	global_store_short v[130:131], v164, off offset:32
	v_mul_f32_e32 v164, v90, v160
	v_cvt_pk_bf16_f32 v164, v164, s0
	global_store_short v[130:131], v164, off offset:64
	v_mul_f32_e32 v164, v74, v144
	v_cvt_pk_bf16_f32 v164, v164, s0
	global_store_short v[130:131], v164, off offset:96
	v_mul_f32_e32 v164, v58, v135
	v_cvt_pk_bf16_f32 v164, v164, s0
	global_store_short v[130:131], v164, off offset:256
	v_mul_f32_e32 v164, v42, v134
	v_cvt_pk_bf16_f32 v164, v164, s0
	global_store_short v[130:131], v164, off offset:288
	v_mul_f32_e32 v164, v26, v133
	v_cvt_pk_bf16_f32 v164, v164, s0
	global_store_short v[130:131], v164, off offset:320
	v_mul_f32_e32 v164, v10, v132
	v_cvt_pk_bf16_f32 v164, v164, s0
	global_store_short v[130:131], v164, off offset:352
	v_mul_f32_e32 v130, v119, v162
	v_cvt_pk_bf16_f32 v164, v130, s0
	v_add_co_u32_e32 v130, vcc, s14, v128
	s_mov_b32 s14, 0x48000
	s_nop 0
	v_addc_co_u32_e32 v131, vcc, 0, v129, vcc
	global_store_short v[130:131], v164, off
	v_mul_f32_e32 v164, v107, v161
	v_cvt_pk_bf16_f32 v164, v164, s0
	global_store_short v[130:131], v164, off offset:32
	v_mul_f32_e32 v164, v91, v160
	v_cvt_pk_bf16_f32 v164, v164, s0
	global_store_short v[130:131], v164, off offset:64
	v_mul_f32_e32 v164, v75, v144
	v_cvt_pk_bf16_f32 v164, v164, s0
	global_store_short v[130:131], v164, off offset:96
	v_mul_f32_e32 v164, v59, v135
	v_cvt_pk_bf16_f32 v164, v164, s0
	global_store_short v[130:131], v164, off offset:256
	v_mul_f32_e32 v164, v43, v134
	v_cvt_pk_bf16_f32 v164, v164, s0
	global_store_short v[130:131], v164, off offset:288
	v_mul_f32_e32 v164, v27, v133
	v_cvt_pk_bf16_f32 v164, v164, s0
	global_store_short v[130:131], v164, off offset:320
	v_mul_f32_e32 v164, v11, v132
	v_cvt_pk_bf16_f32 v164, v164, s0
	global_store_short v[130:131], v164, off offset:352
	v_mul_f32_e32 v130, v112, v162
	v_cvt_pk_bf16_f32 v164, v130, s0
	v_add_co_u32_e32 v130, vcc, s14, v128
	s_mov_b32 s14, 0x4a000
	s_nop 0
	v_addc_co_u32_e32 v131, vcc, 0, v129, vcc
	global_store_short v[130:131], v164, off
	v_mul_f32_e32 v164, v96, v161
	v_cvt_pk_bf16_f32 v164, v164, s0
	global_store_short v[130:131], v164, off offset:32
	v_mul_f32_e32 v164, v80, v160
	v_cvt_pk_bf16_f32 v164, v164, s0
	global_store_short v[130:131], v164, off offset:64
	v_mul_f32_e32 v164, v64, v144
	v_cvt_pk_bf16_f32 v164, v164, s0
	global_store_short v[130:131], v164, off offset:96
	v_mul_f32_e32 v164, v48, v135
	v_cvt_pk_bf16_f32 v164, v164, s0
	global_store_short v[130:131], v164, off offset:256
	v_mul_f32_e32 v164, v32, v134
	v_cvt_pk_bf16_f32 v164, v164, s0
	global_store_short v[130:131], v164, off offset:288
	v_mul_f32_e32 v164, v16, v133
	v_cvt_pk_bf16_f32 v164, v164, s0
	global_store_short v[130:131], v164, off offset:320
	v_mul_f32_e32 v164, v0, v132
	v_cvt_pk_bf16_f32 v164, v164, s0
	global_store_short v[130:131], v164, off offset:352
	v_mul_f32_e32 v130, v113, v162
	v_cvt_pk_bf16_f32 v164, v130, s0
	v_add_co_u32_e32 v130, vcc, s14, v128
	s_mov_b32 s14, 0x4c000
	s_nop 0
	v_addc_co_u32_e32 v131, vcc, 0, v129, vcc
	global_store_short v[130:131], v164, off
	v_mul_f32_e32 v164, v97, v161
	v_cvt_pk_bf16_f32 v164, v164, s0
	global_store_short v[130:131], v164, off offset:32
	v_mul_f32_e32 v164, v81, v160
	v_cvt_pk_bf16_f32 v164, v164, s0
	global_store_short v[130:131], v164, off offset:64
	v_mul_f32_e32 v164, v65, v144
	v_cvt_pk_bf16_f32 v164, v164, s0
	global_store_short v[130:131], v164, off offset:96
	v_mul_f32_e32 v164, v49, v135
	v_cvt_pk_bf16_f32 v164, v164, s0
	global_store_short v[130:131], v164, off offset:256
	v_mul_f32_e32 v164, v33, v134
	v_cvt_pk_bf16_f32 v164, v164, s0
	global_store_short v[130:131], v164, off offset:288
	v_mul_f32_e32 v164, v17, v133
	v_cvt_pk_bf16_f32 v164, v164, s0
	global_store_short v[130:131], v164, off offset:320
	v_mul_f32_e32 v164, v1, v132
	v_cvt_pk_bf16_f32 v164, v164, s0
	global_store_short v[130:131], v164, off offset:352
	v_mul_f32_e32 v130, v114, v162
	v_cvt_pk_bf16_f32 v164, v130, s0
	v_add_co_u32_e32 v130, vcc, s14, v128
	s_mov_b32 s14, 0x4e000
	s_nop 0
	v_addc_co_u32_e32 v131, vcc, 0, v129, vcc
	global_store_short v[130:131], v164, off
	v_mul_f32_e32 v164, v98, v161
	v_cvt_pk_bf16_f32 v164, v164, s0
	global_store_short v[130:131], v164, off offset:32
	v_mul_f32_e32 v164, v82, v160
	v_cvt_pk_bf16_f32 v164, v164, s0
	global_store_short v[130:131], v164, off offset:64
	v_mul_f32_e32 v164, v66, v144
	v_cvt_pk_bf16_f32 v164, v164, s0
	global_store_short v[130:131], v164, off offset:96
	v_mul_f32_e32 v164, v50, v135
	v_cvt_pk_bf16_f32 v164, v164, s0
	global_store_short v[130:131], v164, off offset:256
	v_mul_f32_e32 v164, v34, v134
	v_cvt_pk_bf16_f32 v164, v164, s0
	global_store_short v[130:131], v164, off offset:288
	v_mul_f32_e32 v164, v18, v133
	v_cvt_pk_bf16_f32 v164, v164, s0
	global_store_short v[130:131], v164, off offset:320
	v_mul_f32_e32 v164, v2, v132
	v_cvt_pk_bf16_f32 v164, v164, s0
	global_store_short v[130:131], v164, off offset:352
	v_mul_f32_e32 v130, v115, v162
	v_add_co_u32_e32 v128, vcc, s14, v128
	v_cvt_pk_bf16_f32 v130, v130, s0
	s_nop 0
	v_addc_co_u32_e32 v129, vcc, 0, v129, vcc
	global_store_short v[128:129], v130, off
	v_mul_f32_e32 v130, v99, v161
	v_cvt_pk_bf16_f32 v130, v130, s0
	global_store_short v[128:129], v130, off offset:32
	v_mul_f32_e32 v130, v83, v160
	v_cvt_pk_bf16_f32 v130, v130, s0
	global_store_short v[128:129], v130, off offset:64
	v_mul_f32_e32 v130, v67, v144
	v_cvt_pk_bf16_f32 v130, v130, s0
	global_store_short v[128:129], v130, off offset:96
	v_mul_f32_e32 v130, v51, v135
	v_cvt_pk_bf16_f32 v130, v130, s0
	global_store_short v[128:129], v130, off offset:256
	v_mul_f32_e32 v130, v35, v134
	v_cvt_pk_bf16_f32 v130, v130, s0
	global_store_short v[128:129], v130, off offset:288
	v_mul_f32_e32 v130, v19, v133
	v_cvt_pk_bf16_f32 v130, v130, s0
	global_store_short v[128:129], v130, off offset:320
	v_mul_f32_e32 v130, v3, v132
	v_cvt_pk_bf16_f32 v130, v130, s0
	global_store_short v[128:129], v130, off offset:352
.LBB0_1421:
	s_andn2_b64 vcc, exec, s[38:39]
	s_cbranch_vccnz .LBB0_1423
	v_lshl_add_u32 v160, s36, 8, v163
	v_ashrrev_i32_e32 v161, 31, v160
	v_lshl_add_u64 v[128:129], v[160:161], 2, s[10:11]
	s_waitcnt vmcnt(0)
	v_mov_b32_e32 v166, v243
	v_mov_b32_e32 v170, v244
	v_mov_b32_e32 v172, v245
	v_mov_b32_e32 v174, v246
	v_mov_b32_e32 v192, v247
	v_mov_b32_e32 v193, v248
	v_mov_b32_e32 v194, v249
	v_mov_b32_e32 v197, v250
	v_and_b32_e32 v186, 64, v177
	v_pk_mul_f32 v[130:131], v[126:127], v[126:127]
	v_pk_mul_f32 v[132:133], v[124:125], v[124:125]
	v_pk_mul_f32 v[128:129], v[122:123], v[122:123]
	v_pk_mul_f32 v[134:135], v[120:121], v[120:121]
	v_add_u32_e32 v206, 64, v186
	v_pk_mov_b32 v[186:187], v[132:133], v[130:131] op_sel:[1,0]
	v_mov_b32_e32 v133, v131
	v_pk_mov_b32 v[130:131], v[134:135], v[128:129] op_sel:[1,0]
	v_mov_b32_e32 v135, v129
	v_mul_f32_e32 v144, v117, v117
	v_mul_f32_e32 v162, v119, v119
	v_pk_add_f32 v[132:133], v[186:187], v[132:133]
	v_pk_add_f32 v[130:131], v[130:131], v[134:135]
	v_mul_f32_e32 v198, v112, v112
	v_mul_f32_e32 v199, v113, v113
	v_mul_f32_e32 v200, v114, v114
	v_mul_f32_e32 v201, v115, v115
	v_pk_fma_f32 v[128:129], v[116:117], v[116:117], v[144:145] op_sel_hi:[1,1,0]
	v_pk_fma_f32 v[188:189], v[118:119], v[118:119], v[162:163] op_sel_hi:[1,1,0]
	v_pk_add_f32 v[132:133], v[132:133], v[132:133] op_sel:[0,1] op_sel_hi:[1,0]
	v_pk_add_f32 v[130:131], v[130:131], v[130:131] op_sel:[0,1] op_sel_hi:[1,0]
	v_xor_b32_e32 v195, 16, v177
	v_mov_b32_e32 v129, v200
	v_mov_b32_e32 v189, v201
	v_mov_b32_e32 v133, v198
	v_mov_b32_e32 v131, v199
	v_cmp_lt_i32_e32 vcc, v195, v206
	v_pk_add_f32 v[128:129], v[128:129], v[188:189]
	v_pk_add_f32 v[130:131], v[132:133], v[130:131]
	v_cndmask_b32_e32 v144, v177, v195, vcc
	v_pk_add_f32 v[128:129], v[130:131], v[128:129]
	v_lshlrev_b32_e32 v186, 2, v144
	v_add_f32_e32 v130, v128, v129
	v_pk_mul_f32 v[168:169], v[110:111], v[110:111]
	v_pk_mul_f32 v[178:179], v[108:109], v[108:109]
	v_pk_mul_f32 v[180:181], v[102:103], v[102:103]
	v_pk_mul_f32 v[182:183], v[100:101], v[100:101]
	ds_bpermute_b32 v131, v186, v130
	v_pk_mov_b32 v[190:191], v[178:179], v[168:169] op_sel:[1,0]
	v_mov_b32_e32 v179, v169
	v_pk_mov_b32 v[168:169], v[182:183], v[180:181] op_sel:[1,0]
	v_mov_b32_e32 v183, v181
	v_pk_add_f32 v[134:135], v[190:191], v[178:179]
	v_pk_add_f32 v[168:169], v[168:169], v[182:183]
	v_mul_f32_e32 v202, v96, v96
	v_mul_f32_e32 v203, v97, v97
	v_pk_add_f32 v[134:135], v[134:135], v[134:135] op_sel:[0,1] op_sel_hi:[1,0]
	v_pk_add_f32 v[128:129], v[168:169], v[168:169] op_sel:[0,1] op_sel_hi:[1,0]
	v_mov_b32_e32 v135, v202
	v_mov_b32_e32 v129, v203
	v_mul_f32_e32 v164, v105, v105
	v_pk_add_f32 v[128:129], v[134:135], v[128:129]
	s_waitcnt lgkmcnt(0)
	v_add_f32_e32 v134, v130, v131
	v_xor_b32_e32 v196, 32, v177
	v_mul_f32_e32 v204, v98, v98
	v_mul_f32_e32 v205, v99, v99
	v_cmp_lt_i32_e32 vcc, v196, v206
	v_pk_mul_f32 v[178:179], v[22:23], v[22:23]
	v_pk_mul_f32 v[180:181], v[20:21], v[20:21]
	v_cndmask_b32_e32 v162, v177, v196, vcc
	v_lshlrev_b32_e32 v187, 2, v162
	ds_bpermute_b32 v135, v187, v134
	v_pk_mov_b32 v[182:183], v[180:181], v[178:179] op_sel:[1,0]
	v_mov_b32_e32 v181, v179
	v_pk_add_f32 v[178:179], v[182:183], v[180:181]
	v_mul_f32_e32 v180, v17, v17
	v_pk_add_f32 v[178:179], v[178:179], v[178:179] op_sel:[0,1] op_sel_hi:[1,0]
	v_mul_f32_e32 v181, v18, v18
	v_mov_b32_e32 v179, v180
	v_mul_f32_e32 v182, v19, v19
	s_lshl_b32 s14, s80, 8
	s_waitcnt vmcnt(0)
	v_fmamk_f32 v130, v166, 0x3a800000, v176
	v_fmamk_f32 v131, v170, 0x3a800000, v176
	v_fmamk_f32 v132, v172, 0x3a800000, v176
	v_fmamk_f32 v133, v174, 0x3a800000, v176
	v_rsq_f32_e32 v170, v132
	v_mul_f32_e32 v132, v107, v107
	v_rsq_f32_e32 v168, v130
	v_rsq_f32_e32 v169, v131
	v_rsq_f32_e32 v172, v133
	v_pk_fma_f32 v[130:131], v[104:105], v[104:105], v[164:165] op_sel_hi:[1,1,0]
	v_pk_fma_f32 v[132:133], v[106:107], v[106:107], v[132:133] op_sel_hi:[1,1,0]
	v_mov_b32_e32 v131, v204
	v_mov_b32_e32 v133, v205
	v_pk_add_f32 v[130:131], v[130:131], v[132:133]
	v_fmamk_f32 v162, v193, 0x3a800000, v176
	v_pk_add_f32 v[128:129], v[128:129], v[130:131]
	s_waitcnt lgkmcnt(0)
	v_add_f32_e32 v130, v134, v135
	v_add_f32_e32 v128, v128, v129
	ds_bpermute_b32 v129, v186, v128
	v_rsq_f32_e32 v188, v162
	v_mul_f32_e32 v162, v168, v130
	v_pk_mul_f32 v[130:131], v[92:93], v[92:93]
	v_fmamk_f32 v166, v194, 0x3a800000, v176
	s_waitcnt lgkmcnt(0)
	v_add_f32_e32 v164, v128, v129
	v_pk_mul_f32 v[128:129], v[94:95], v[94:95]
	v_rsq_f32_e32 v189, v166
	v_pk_mov_b32 v[132:133], v[130:131], v[128:129] op_sel:[1,0]
	v_mov_b32_e32 v131, v129
	v_pk_add_f32 v[128:129], v[132:133], v[130:131]
	v_pk_mul_f32 v[130:131], v[86:87], v[86:87]
	v_pk_mul_f32 v[132:133], v[84:85], v[84:85]
	v_pk_add_f32 v[128:129], v[128:129], v[128:129] op_sel:[0,1] op_sel_hi:[1,0]
	v_pk_mov_b32 v[134:135], v[132:133], v[130:131] op_sel:[1,0]
	v_mov_b32_e32 v133, v131
	v_pk_add_f32 v[130:131], v[134:135], v[132:133]
	v_mul_f32_e32 v132, v80, v80
	v_mul_f32_e32 v133, v81, v81
	v_pk_add_f32 v[130:131], v[130:131], v[130:131] op_sel:[0,1] op_sel_hi:[1,0]
	v_mov_b32_e32 v129, v132
	v_mov_b32_e32 v131, v133
	v_pk_add_f32 v[128:129], v[128:129], v[130:131]
	v_mul_f32_e32 v130, v89, v89
	v_mul_f32_e32 v132, v91, v91
	v_mul_f32_e32 v134, v82, v82
	v_mul_f32_e32 v135, v83, v83
	v_pk_fma_f32 v[130:131], v[88:89], v[88:89], v[130:131] op_sel_hi:[1,1,0]
	v_pk_fma_f32 v[132:133], v[90:91], v[90:91], v[132:133] op_sel_hi:[1,1,0]
	v_mov_b32_e32 v131, v134
	v_mov_b32_e32 v133, v135
	v_pk_add_f32 v[130:131], v[130:131], v[132:133]
	ds_bpermute_b32 v166, v187, v164
	v_pk_add_f32 v[128:129], v[128:129], v[130:131]
	v_mul_f32_e32 v130, v168, v162
	v_add_f32_e32 v128, v128, v129
	ds_bpermute_b32 v129, v186, v128
	v_fmamk_f32 v130, v130, 0x3c800000, v176
	v_rsq_f32_e32 v162, v130
	s_waitcnt lgkmcnt(1)
	v_add_f32_e32 v130, v164, v166
	v_mul_f32_e32 v130, v169, v130
	s_waitcnt lgkmcnt(0)
	v_add_f32_e32 v128, v128, v129
	ds_bpermute_b32 v129, v187, v128
	v_mul_f32_e32 v130, v169, v130
	v_fmamk_f32 v130, v130, 0x3c800000, v176
	v_rsq_f32_e32 v166, v130
	v_pk_mul_f32 v[130:131], v[76:77], v[76:77]
	s_waitcnt lgkmcnt(0)
	v_add_f32_e32 v164, v128, v129
	v_pk_mul_f32 v[128:129], v[78:79], v[78:79]
	v_fmamk_f32 v144, v192, 0x3a800000, v176
	v_pk_mov_b32 v[132:133], v[130:131], v[128:129] op_sel:[1,0]
	v_mov_b32_e32 v131, v129
	v_pk_add_f32 v[128:129], v[132:133], v[130:131]
	v_pk_mul_f32 v[130:131], v[70:71], v[70:71]
	v_pk_mul_f32 v[132:133], v[68:69], v[68:69]
	v_pk_add_f32 v[128:129], v[128:129], v[128:129] op_sel:[0,1] op_sel_hi:[1,0]
	v_pk_mov_b32 v[134:135], v[132:133], v[130:131] op_sel:[1,0]
	v_mov_b32_e32 v133, v131
	v_pk_add_f32 v[130:131], v[134:135], v[132:133]
	v_mul_f32_e32 v132, v64, v64
	v_mul_f32_e32 v133, v65, v65
	v_pk_add_f32 v[130:131], v[130:131], v[130:131] op_sel:[0,1] op_sel_hi:[1,0]
	v_mov_b32_e32 v129, v132
	v_mov_b32_e32 v131, v133
	v_pk_add_f32 v[128:129], v[128:129], v[130:131]
	v_mul_f32_e32 v130, v73, v73
	v_mul_f32_e32 v132, v75, v75
	v_mul_f32_e32 v134, v66, v66
	v_mul_f32_e32 v135, v67, v67
	v_pk_fma_f32 v[130:131], v[72:73], v[72:73], v[130:131] op_sel_hi:[1,1,0]
	v_pk_fma_f32 v[132:133], v[74:75], v[74:75], v[132:133] op_sel_hi:[1,1,0]
	v_mov_b32_e32 v131, v134
	v_mov_b32_e32 v133, v135
	v_pk_add_f32 v[130:131], v[130:131], v[132:133]
	v_rsq_f32_e32 v174, v144
	v_pk_add_f32 v[128:129], v[128:129], v[130:131]
	v_mul_f32_e32 v130, v170, v164
	v_add_f32_e32 v128, v128, v129
	ds_bpermute_b32 v129, v186, v128
	v_mul_f32_e32 v130, v170, v130
	v_fmamk_f32 v130, v130, 0x3c800000, v176
	v_rsq_f32_e32 v130, v130
	v_fmamk_f32 v144, v197, 0x3a800000, v176
	s_waitcnt lgkmcnt(0)
	v_add_f32_e32 v128, v128, v129
	ds_bpermute_b32 v129, v187, v128
	v_rsq_f32_e32 v190, v144
	v_mul_f32_e32 v164, v168, v162
	v_mul_f32_e32 v162, v169, v166
	v_mul_f32_e32 v144, v170, v130
	s_waitcnt lgkmcnt(0)
	v_add_f32_e32 v166, v128, v129
	v_pk_mul_f32 v[128:129], v[62:63], v[62:63]
	v_pk_mul_f32 v[130:131], v[60:61], v[60:61]
	v_mul_f32_e32 v170, v16, v16
	v_pk_mov_b32 v[132:133], v[130:131], v[128:129] op_sel:[1,0]
	v_mov_b32_e32 v131, v129
	v_pk_add_f32 v[128:129], v[132:133], v[130:131]
	v_pk_mul_f32 v[130:131], v[54:55], v[54:55]
	v_pk_mul_f32 v[132:133], v[52:53], v[52:53]
	v_pk_add_f32 v[128:129], v[128:129], v[128:129] op_sel:[0,1] op_sel_hi:[1,0]
	v_pk_mov_b32 v[134:135], v[132:133], v[130:131] op_sel:[1,0]
	v_mov_b32_e32 v133, v131
	v_pk_add_f32 v[130:131], v[134:135], v[132:133]
	v_mul_f32_e32 v132, v48, v48
	v_mul_f32_e32 v133, v49, v49
	v_pk_add_f32 v[130:131], v[130:131], v[130:131] op_sel:[0,1] op_sel_hi:[1,0]
	v_mov_b32_e32 v129, v132
	v_mov_b32_e32 v131, v133
	v_pk_add_f32 v[128:129], v[128:129], v[130:131]
	v_mul_f32_e32 v130, v57, v57
	v_mul_f32_e32 v132, v59, v59
	v_mul_f32_e32 v134, v50, v50
	v_mul_f32_e32 v135, v51, v51
	v_pk_fma_f32 v[130:131], v[56:57], v[56:57], v[130:131] op_sel_hi:[1,1,0]
	v_pk_fma_f32 v[132:133], v[58:59], v[58:59], v[132:133] op_sel_hi:[1,1,0]
	v_mov_b32_e32 v131, v134
	v_mov_b32_e32 v133, v135
	v_pk_add_f32 v[130:131], v[130:131], v[132:133]
	s_or_b32 s14, s14, s72
	v_pk_add_f32 v[128:129], v[128:129], v[130:131]
	v_mul_f32_e32 v130, v172, v166
	v_add_f32_e32 v128, v128, v129
	ds_bpermute_b32 v129, v186, v128
	v_mul_f32_e32 v130, v172, v130
	v_fmamk_f32 v130, v130, 0x3c800000, v176
	v_rsq_f32_e32 v166, v130
	v_pk_mul_f32 v[130:131], v[44:45], v[44:45]
	s_waitcnt lgkmcnt(0)
	v_add_f32_e32 v168, v128, v129
	v_pk_mul_f32 v[128:129], v[46:47], v[46:47]
	ds_bpermute_b32 v169, v187, v168
	v_pk_mov_b32 v[132:133], v[130:131], v[128:129] op_sel:[1,0]
	v_mov_b32_e32 v131, v129
	v_pk_add_f32 v[128:129], v[132:133], v[130:131]
	v_pk_mul_f32 v[130:131], v[38:39], v[38:39]
	v_pk_mul_f32 v[132:133], v[36:37], v[36:37]
	v_pk_add_f32 v[128:129], v[128:129], v[128:129] op_sel:[0,1] op_sel_hi:[1,0]
	v_pk_mov_b32 v[134:135], v[132:133], v[130:131] op_sel:[1,0]
	v_mov_b32_e32 v133, v131
	v_pk_add_f32 v[130:131], v[134:135], v[132:133]
	v_mul_f32_e32 v132, v32, v32
	v_mul_f32_e32 v133, v33, v33
	v_pk_add_f32 v[130:131], v[130:131], v[130:131] op_sel:[0,1] op_sel_hi:[1,0]
	v_mov_b32_e32 v129, v132
	v_mov_b32_e32 v131, v133
	v_pk_add_f32 v[128:129], v[128:129], v[130:131]
	v_mul_f32_e32 v130, v41, v41
	v_mul_f32_e32 v132, v43, v43
	v_mul_f32_e32 v134, v34, v34
	v_mul_f32_e32 v135, v35, v35
	v_pk_fma_f32 v[130:131], v[40:41], v[40:41], v[130:131] op_sel_hi:[1,1,0]
	v_pk_fma_f32 v[132:133], v[42:43], v[42:43], v[132:133] op_sel_hi:[1,1,0]
	v_mov_b32_e32 v131, v134
	v_mov_b32_e32 v133, v135
	v_pk_add_f32 v[130:131], v[130:131], v[132:133]
	v_mul_f32_e32 v166, v172, v166
	v_pk_add_f32 v[128:129], v[128:129], v[130:131]
	s_waitcnt lgkmcnt(0)
	v_add_f32_e32 v130, v168, v169
	v_add_f32_e32 v128, v128, v129
	ds_bpermute_b32 v129, v186, v128
	v_mul_f32_e32 v130, v174, v130
	v_mul_f32_e32 v172, v174, v130
	v_pk_mul_f32 v[130:131], v[28:29], v[28:29]
	s_ashr_i32 s15, s14, 31
	s_waitcnt lgkmcnt(0)
	v_add_f32_e32 v191, v128, v129
	v_pk_mul_f32 v[128:129], v[30:31], v[30:31]
	ds_bpermute_b32 v192, v187, v191
	v_pk_mov_b32 v[132:133], v[130:131], v[128:129] op_sel:[1,0]
	v_mov_b32_e32 v131, v129
	v_pk_add_f32 v[168:169], v[132:133], v[130:131]
	global_load_dwordx4 v[128:131], v[150:151], off offset:16
	global_load_dwordx4 v[132:135], v[150:151], off
	v_pk_add_f32 v[168:169], v[168:169], v[168:169] op_sel:[0,1] op_sel_hi:[1,0]
	s_nop 0
	v_mov_b32_e32 v169, v170
	v_mul_f32_e32 v170, v25, v25
	v_pk_add_f32 v[168:169], v[168:169], v[178:179]
	v_pk_fma_f32 v[178:179], v[24:25], v[24:25], v[170:171] op_sel_hi:[1,1,0]
	v_mul_f32_e32 v170, v27, v27
	v_mov_b32_e32 v179, v181
	v_pk_fma_f32 v[180:181], v[26:27], v[26:27], v[170:171] op_sel_hi:[1,1,0]
	v_fmamk_f32 v170, v172, 0x3c800000, v176
	v_mov_b32_e32 v181, v182
	v_pk_add_f32 v[178:179], v[178:179], v[180:181]
	v_rsq_f32_e32 v172, v170
	v_pk_add_f32 v[168:169], v[168:169], v[178:179]
	s_waitcnt lgkmcnt(0)
	v_add_f32_e32 v170, v191, v192
	v_add_f32_e32 v168, v168, v169
	ds_bpermute_b32 v169, v186, v168
	v_pk_mul_f32 v[178:179], v[12:13], v[12:13]
	v_mul_f32_e32 v191, v188, v170
	v_mul_f32_e32 v170, v0, v0
	v_mul_f32_e32 v174, v174, v172
	s_waitcnt lgkmcnt(0)
	v_add_f32_e32 v192, v168, v169
	v_pk_mul_f32 v[168:169], v[14:15], v[14:15]
	ds_bpermute_b32 v193, v187, v192
	v_pk_mov_b32 v[180:181], v[178:179], v[168:169] op_sel:[1,0]
	v_mov_b32_e32 v179, v169
	v_pk_add_f32 v[168:169], v[180:181], v[178:179]
	v_pk_mul_f32 v[178:179], v[6:7], v[6:7]
	v_pk_mul_f32 v[180:181], v[4:5], v[4:5]
	v_pk_add_f32 v[168:169], v[168:169], v[168:169] op_sel:[0,1] op_sel_hi:[1,0]
	v_pk_mov_b32 v[182:183], v[180:181], v[178:179] op_sel:[1,0]
	v_mov_b32_e32 v181, v179
	v_pk_add_f32 v[178:179], v[182:183], v[180:181]
	v_mul_f32_e32 v180, v1, v1
	v_pk_add_f32 v[178:179], v[178:179], v[178:179] op_sel:[0,1] op_sel_hi:[1,0]
	v_mov_b32_e32 v169, v170
	v_mov_b32_e32 v179, v180
	v_mul_f32_e32 v170, v9, v9
	v_mul_f32_e32 v181, v2, v2
	v_pk_add_f32 v[168:169], v[168:169], v[178:179]
	v_pk_fma_f32 v[178:179], v[8:9], v[8:9], v[170:171] op_sel_hi:[1,1,0]
	v_mul_f32_e32 v170, v11, v11
	v_mul_f32_e32 v182, v3, v3
	v_mov_b32_e32 v179, v181
	v_pk_fma_f32 v[180:181], v[10:11], v[10:11], v[170:171] op_sel_hi:[1,1,0]
	v_mul_f32_e32 v170, v188, v191
	v_mov_b32_e32 v181, v182
	v_pk_add_f32 v[178:179], v[178:179], v[180:181]
	v_fmamk_f32 v170, v170, 0x3c800000, v176
	v_pk_add_f32 v[168:169], v[168:169], v[178:179]
	s_waitcnt lgkmcnt(0)
	v_add_f32_e32 v178, v192, v193
	v_add_f32_e32 v168, v168, v169
	ds_bpermute_b32 v169, v186, v168
	v_mul_f32_e32 v178, v189, v178
	v_mul_f32_e32 v178, v189, v178
	v_fmamk_f32 v178, v178, 0x3c800000, v176
	v_rsq_f32_e32 v170, v170
	s_waitcnt lgkmcnt(0)
	v_add_f32_e32 v168, v168, v169
	ds_bpermute_b32 v169, v187, v168
	v_rsq_f32_e32 v178, v178
	v_mul_f32_e32 v172, v188, v170
	v_lshl_add_u64 v[182:183], s[14:15], 1, v[148:149]
	s_waitcnt lgkmcnt(0)
	v_add_f32_e32 v168, v168, v169
	v_mul_f32_e32 v168, v190, v168
	v_mul_f32_e32 v168, v190, v168
	v_fmamk_f32 v168, v168, 0x3c800000, v176
	v_rsq_f32_e32 v168, v168
	v_mul_f32_e32 v170, v189, v178
	v_mul_f32_e32 v168, v190, v168
	s_waitcnt vmcnt(1)
	v_pk_mul_f32 v[188:189], v[120:121], v[128:129]
	s_waitcnt vmcnt(0)
	v_pk_mul_f32 v[178:179], v[126:127], v[134:135]
	v_pk_mul_f32 v[180:181], v[124:125], v[132:133]
	v_pk_mul_f32 v[186:187], v[164:165], v[178:179] op_sel_hi:[0,1]
	v_pk_mul_f32 v[178:179], v[164:165], v[180:181] op_sel_hi:[0,1]
	v_pk_mul_f32 v[180:181], v[122:123], v[130:131]
	v_cvt_pk_bf16_f32 v178, v178, v179
	v_pk_mul_f32 v[190:191], v[164:165], v[180:181] op_sel_hi:[0,1]
	v_pk_mul_f32 v[180:181], v[164:165], v[188:189] op_sel_hi:[0,1]
	v_cvt_pk_bf16_f32 v179, v186, v187
	v_lshlrev_b64 v[186:187], 11, v[160:161]
	v_cvt_pk_bf16_f32 v180, v180, v181
	v_cvt_pk_bf16_f32 v181, v190, v191
	v_lshl_add_u64 v[186:187], v[182:183], 0, v[186:187]
	global_store_dwordx4 v[186:187], v[178:181], off
	v_or_b32_e32 v188, 16, v160
	v_pk_mul_f32 v[192:193], v[100:101], v[128:129]
	v_pk_mul_f32 v[178:179], v[110:111], v[134:135]
	v_pk_mul_f32 v[180:181], v[108:109], v[132:133]
	v_pk_mul_f32 v[190:191], v[162:163], v[178:179] op_sel_hi:[0,1]
	v_pk_mul_f32 v[178:179], v[162:163], v[180:181] op_sel_hi:[0,1]
	v_pk_mul_f32 v[180:181], v[102:103], v[130:131]
	v_ashrrev_i32_e32 v189, 31, v188
	v_pk_mul_f32 v[194:195], v[162:163], v[180:181] op_sel_hi:[0,1]
	v_pk_mul_f32 v[180:181], v[162:163], v[192:193] op_sel_hi:[0,1]
	v_lshlrev_b64 v[188:189], 11, v[188:189]
	v_cvt_pk_bf16_f32 v178, v178, v179
	v_cvt_pk_bf16_f32 v179, v190, v191
	v_cvt_pk_bf16_f32 v180, v180, v181
	v_cvt_pk_bf16_f32 v181, v194, v195
	v_lshl_add_u64 v[188:189], v[182:183], 0, v[188:189]
	global_store_dwordx4 v[188:189], v[178:181], off
	v_or_b32_e32 v190, 32, v160
	v_pk_mul_f32 v[194:195], v[84:85], v[128:129]
	v_pk_mul_f32 v[178:179], v[94:95], v[134:135]
	v_pk_mul_f32 v[180:181], v[92:93], v[132:133]
	v_pk_mul_f32 v[192:193], v[144:145], v[178:179] op_sel_hi:[0,1]
	v_pk_mul_f32 v[178:179], v[144:145], v[180:181] op_sel_hi:[0,1]
	v_pk_mul_f32 v[180:181], v[86:87], v[130:131]
	v_ashrrev_i32_e32 v191, 31, v190
	v_pk_mul_f32 v[196:197], v[144:145], v[180:181] op_sel_hi:[0,1]
	v_pk_mul_f32 v[180:181], v[144:145], v[194:195] op_sel_hi:[0,1]
	v_lshlrev_b64 v[190:191], 11, v[190:191]
	v_cvt_pk_bf16_f32 v178, v178, v179
	v_cvt_pk_bf16_f32 v179, v192, v193
	v_cvt_pk_bf16_f32 v180, v180, v181
	v_cvt_pk_bf16_f32 v181, v196, v197
	v_lshl_add_u64 v[190:191], v[182:183], 0, v[190:191]
	global_store_dwordx4 v[190:191], v[178:181], off
	v_or_b32_e32 v192, 48, v160
	v_pk_mul_f32 v[196:197], v[68:69], v[128:129]
	v_pk_mul_f32 v[178:179], v[78:79], v[134:135]
	v_pk_mul_f32 v[180:181], v[76:77], v[132:133]
	v_pk_mul_f32 v[194:195], v[166:167], v[178:179] op_sel_hi:[0,1]
	v_pk_mul_f32 v[178:179], v[166:167], v[180:181] op_sel_hi:[0,1]
	v_pk_mul_f32 v[180:181], v[70:71], v[130:131]
	v_ashrrev_i32_e32 v193, 31, v192
	v_pk_mul_f32 v[198:199], v[166:167], v[180:181] op_sel_hi:[0,1]
	v_pk_mul_f32 v[180:181], v[166:167], v[196:197] op_sel_hi:[0,1]
	v_lshlrev_b64 v[192:193], 11, v[192:193]
	v_cvt_pk_bf16_f32 v178, v178, v179
	v_cvt_pk_bf16_f32 v179, v194, v195
	v_cvt_pk_bf16_f32 v180, v180, v181
	v_cvt_pk_bf16_f32 v181, v198, v199
	v_lshl_add_u64 v[192:193], v[182:183], 0, v[192:193]
	global_store_dwordx4 v[192:193], v[178:181], off
	v_add_u32_e32 v194, 0x80, v160
	v_pk_mul_f32 v[198:199], v[52:53], v[128:129]
	v_pk_mul_f32 v[178:179], v[62:63], v[134:135]
	v_pk_mul_f32 v[180:181], v[60:61], v[132:133]
	v_pk_mul_f32 v[196:197], v[178:179], v[174:175] op_sel_hi:[1,0]
	v_pk_mul_f32 v[178:179], v[180:181], v[174:175] op_sel_hi:[1,0]
	v_pk_mul_f32 v[180:181], v[54:55], v[130:131]
	v_ashrrev_i32_e32 v195, 31, v194
	v_pk_mul_f32 v[200:201], v[180:181], v[174:175] op_sel_hi:[1,0]
	v_pk_mul_f32 v[180:181], v[198:199], v[174:175] op_sel_hi:[1,0]
	v_lshlrev_b64 v[194:195], 11, v[194:195]
	v_cvt_pk_bf16_f32 v178, v178, v179
	v_cvt_pk_bf16_f32 v179, v196, v197
	v_cvt_pk_bf16_f32 v180, v180, v181
	v_cvt_pk_bf16_f32 v181, v200, v201
	v_lshl_add_u64 v[194:195], v[182:183], 0, v[194:195]
	global_store_dwordx4 v[194:195], v[178:181], off
	v_add_u32_e32 v196, 0x90, v160
	v_pk_mul_f32 v[200:201], v[36:37], v[128:129]
	v_pk_mul_f32 v[178:179], v[46:47], v[134:135]
	v_pk_mul_f32 v[180:181], v[44:45], v[132:133]
	v_pk_mul_f32 v[198:199], v[178:179], v[172:173] op_sel_hi:[1,0]
	v_pk_mul_f32 v[178:179], v[180:181], v[172:173] op_sel_hi:[1,0]
	v_pk_mul_f32 v[180:181], v[38:39], v[130:131]
	v_ashrrev_i32_e32 v197, 31, v196
	v_pk_mul_f32 v[202:203], v[180:181], v[172:173] op_sel_hi:[1,0]
	v_pk_mul_f32 v[180:181], v[200:201], v[172:173] op_sel_hi:[1,0]
	v_lshlrev_b64 v[196:197], 11, v[196:197]
	v_cvt_pk_bf16_f32 v178, v178, v179
	v_cvt_pk_bf16_f32 v179, v198, v199
	v_cvt_pk_bf16_f32 v180, v180, v181
	v_cvt_pk_bf16_f32 v181, v202, v203
	v_lshl_add_u64 v[196:197], v[182:183], 0, v[196:197]
	global_store_dwordx4 v[196:197], v[178:181], off
	v_add_u32_e32 v198, 0xa0, v160
	v_pk_mul_f32 v[202:203], v[20:21], v[128:129]
	v_pk_mul_f32 v[178:179], v[30:31], v[134:135]
	v_pk_mul_f32 v[180:181], v[28:29], v[132:133]
	v_pk_mul_f32 v[200:201], v[178:179], v[170:171] op_sel_hi:[1,0]
	v_pk_mul_f32 v[178:179], v[180:181], v[170:171] op_sel_hi:[1,0]
	v_pk_mul_f32 v[180:181], v[22:23], v[130:131]
	v_ashrrev_i32_e32 v199, 31, v198
	v_pk_mul_f32 v[204:205], v[180:181], v[170:171] op_sel_hi:[1,0]
	v_pk_mul_f32 v[180:181], v[202:203], v[170:171] op_sel_hi:[1,0]
	v_lshlrev_b64 v[198:199], 11, v[198:199]
	v_add_u32_e32 v160, 0xb0, v160
	v_pk_mul_f32 v[132:133], v[12:13], v[132:133]
	v_cvt_pk_bf16_f32 v178, v178, v179
	v_cvt_pk_bf16_f32 v179, v200, v201
	v_cvt_pk_bf16_f32 v180, v180, v181
	v_cvt_pk_bf16_f32 v181, v204, v205
	v_lshl_add_u64 v[198:199], v[182:183], 0, v[198:199]
	v_pk_mul_f32 v[134:135], v[14:15], v[134:135]
	v_pk_mul_f32 v[132:133], v[132:133], v[168:169] op_sel_hi:[1,0]
	v_pk_mul_f32 v[130:131], v[6:7], v[130:131]
	v_pk_mul_f32 v[128:129], v[4:5], v[128:129]
	v_ashrrev_i32_e32 v161, 31, v160
	global_store_dwordx4 v[198:199], v[178:181], off
	v_pk_mul_f32 v[134:135], v[134:135], v[168:169] op_sel_hi:[1,0]
	s_nop 0
	v_pk_mul_f32 v[178:179], v[130:131], v[168:169] op_sel_hi:[1,0]
	v_pk_mul_f32 v[130:131], v[128:129], v[168:169] op_sel_hi:[1,0]
	v_cvt_pk_bf16_f32 v128, v132, v133
	v_lshlrev_b64 v[132:133], 11, v[160:161]
	v_cvt_pk_bf16_f32 v129, v134, v135
	v_cvt_pk_bf16_f32 v130, v130, v131
	v_cvt_pk_bf16_f32 v131, v178, v179
	v_lshl_add_u64 v[160:161], v[182:183], 0, v[132:133]
	global_store_dwordx4 v[160:161], v[128:131], off
	global_load_dwordx4 v[128:131], v[150:151], off offset:128
	global_load_dwordx4 v[132:135], v[150:151], off offset:144
	s_waitcnt vmcnt(1)
	v_pk_mul_f32 v[178:179], v[118:119], v[130:131]
	v_pk_mul_f32 v[180:181], v[116:117], v[128:129]
	v_pk_mul_f32 v[182:183], v[164:165], v[178:179] op_sel_hi:[0,1]
	v_pk_mul_f32 v[178:179], v[164:165], v[180:181] op_sel_hi:[0,1]
	s_waitcnt vmcnt(0)
	v_pk_mul_f32 v[180:181], v[114:115], v[134:135]
	v_pk_mul_f32 v[200:201], v[112:113], v[132:133]
	v_pk_mul_f32 v[202:203], v[164:165], v[180:181] op_sel_hi:[0,1]
	v_pk_mul_f32 v[180:181], v[164:165], v[200:201] op_sel_hi:[0,1]
	v_cvt_pk_bf16_f32 v178, v178, v179
	v_cvt_pk_bf16_f32 v179, v182, v183
	v_cvt_pk_bf16_f32 v180, v180, v181
	v_cvt_pk_bf16_f32 v181, v202, v203
	global_store_dwordx4 v[186:187], v[178:181], off offset:64
	v_pk_mul_f32 v[186:187], v[96:97], v[132:133]
	s_nop 0
	v_pk_mul_f32 v[178:179], v[106:107], v[130:131]
	v_pk_mul_f32 v[180:181], v[104:105], v[128:129]
	v_pk_mul_f32 v[182:183], v[162:163], v[178:179] op_sel_hi:[0,1]
	v_pk_mul_f32 v[178:179], v[162:163], v[180:181] op_sel_hi:[0,1]
	v_pk_mul_f32 v[180:181], v[98:99], v[134:135]
	v_cvt_pk_bf16_f32 v178, v178, v179
	v_pk_mul_f32 v[200:201], v[162:163], v[180:181] op_sel_hi:[0,1]
	v_pk_mul_f32 v[180:181], v[162:163], v[186:187] op_sel_hi:[0,1]
	v_cvt_pk_bf16_f32 v179, v182, v183
	v_cvt_pk_bf16_f32 v180, v180, v181
	v_cvt_pk_bf16_f32 v181, v200, v201
	global_store_dwordx4 v[188:189], v[178:181], off offset:64
	v_pk_mul_f32 v[186:187], v[80:81], v[132:133]
	s_nop 0
	v_pk_mul_f32 v[178:179], v[90:91], v[130:131]
	v_pk_mul_f32 v[180:181], v[88:89], v[128:129]
	v_pk_mul_f32 v[182:183], v[144:145], v[178:179] op_sel_hi:[0,1]
	v_pk_mul_f32 v[178:179], v[144:145], v[180:181] op_sel_hi:[0,1]
	v_pk_mul_f32 v[180:181], v[82:83], v[134:135]
	v_cvt_pk_bf16_f32 v178, v178, v179
	v_pk_mul_f32 v[188:189], v[144:145], v[180:181] op_sel_hi:[0,1]
	v_pk_mul_f32 v[180:181], v[144:145], v[186:187] op_sel_hi:[0,1]
	v_cvt_pk_bf16_f32 v179, v182, v183
	v_cvt_pk_bf16_f32 v180, v180, v181
	v_cvt_pk_bf16_f32 v181, v188, v189
	global_store_dwordx4 v[190:191], v[178:181], off offset:64
	v_pk_mul_f32 v[186:187], v[64:65], v[132:133]
	s_nop 0
	v_pk_mul_f32 v[178:179], v[74:75], v[130:131]
	v_pk_mul_f32 v[180:181], v[72:73], v[128:129]
	v_pk_mul_f32 v[182:183], v[166:167], v[178:179] op_sel_hi:[0,1]
	v_pk_mul_f32 v[178:179], v[166:167], v[180:181] op_sel_hi:[0,1]
	v_pk_mul_f32 v[180:181], v[66:67], v[134:135]
	v_cvt_pk_bf16_f32 v178, v178, v179
	v_pk_mul_f32 v[188:189], v[166:167], v[180:181] op_sel_hi:[0,1]
	v_pk_mul_f32 v[180:181], v[166:167], v[186:187] op_sel_hi:[0,1]
	v_cvt_pk_bf16_f32 v179, v182, v183
	v_cvt_pk_bf16_f32 v180, v180, v181
	v_cvt_pk_bf16_f32 v181, v188, v189
	global_store_dwordx4 v[192:193], v[178:181], off offset:64
	v_pk_mul_f32 v[186:187], v[48:49], v[132:133]
	s_nop 0
	v_pk_mul_f32 v[178:179], v[58:59], v[130:131]
	v_pk_mul_f32 v[180:181], v[56:57], v[128:129]
	v_pk_mul_f32 v[182:183], v[174:175], v[178:179] op_sel_hi:[0,1]
	v_pk_mul_f32 v[178:179], v[174:175], v[180:181] op_sel_hi:[0,1]
	v_pk_mul_f32 v[180:181], v[50:51], v[134:135]
	v_cvt_pk_bf16_f32 v178, v178, v179
	v_pk_mul_f32 v[188:189], v[174:175], v[180:181] op_sel_hi:[0,1]
	v_pk_mul_f32 v[180:181], v[174:175], v[186:187] op_sel_hi:[0,1]
	v_cvt_pk_bf16_f32 v179, v182, v183
	v_cvt_pk_bf16_f32 v180, v180, v181
	v_cvt_pk_bf16_f32 v181, v188, v189
	global_store_dwordx4 v[194:195], v[178:181], off offset:64
	v_pk_mul_f32 v[186:187], v[32:33], v[132:133]
	s_nop 0
	v_pk_mul_f32 v[178:179], v[42:43], v[130:131]
	v_pk_mul_f32 v[180:181], v[40:41], v[128:129]
	v_pk_mul_f32 v[182:183], v[172:173], v[178:179] op_sel_hi:[0,1]
	v_pk_mul_f32 v[178:179], v[172:173], v[180:181] op_sel_hi:[0,1]
	v_pk_mul_f32 v[180:181], v[34:35], v[134:135]
	v_cvt_pk_bf16_f32 v178, v178, v179
	v_pk_mul_f32 v[188:189], v[172:173], v[180:181] op_sel_hi:[0,1]
	v_pk_mul_f32 v[180:181], v[172:173], v[186:187] op_sel_hi:[0,1]
	v_cvt_pk_bf16_f32 v179, v182, v183
	v_cvt_pk_bf16_f32 v180, v180, v181
	v_cvt_pk_bf16_f32 v181, v188, v189
	global_store_dwordx4 v[196:197], v[178:181], off offset:64
	v_pk_mul_f32 v[186:187], v[16:17], v[132:133]
	v_pk_mul_f32 v[132:133], v[0:1], v[132:133]
	v_pk_mul_f32 v[178:179], v[26:27], v[130:131]
	v_pk_mul_f32 v[180:181], v[24:25], v[128:129]
	v_pk_mul_f32 v[182:183], v[170:171], v[178:179] op_sel_hi:[0,1]
	v_pk_mul_f32 v[178:179], v[170:171], v[180:181] op_sel_hi:[0,1]
	v_pk_mul_f32 v[180:181], v[18:19], v[134:135]
	v_pk_mul_f32 v[130:131], v[10:11], v[130:131]
	v_pk_mul_f32 v[188:189], v[170:171], v[180:181] op_sel_hi:[0,1]
	v_pk_mul_f32 v[180:181], v[170:171], v[186:187] op_sel_hi:[0,1]
	v_pk_mul_f32 v[128:129], v[8:9], v[128:129]
	v_pk_mul_f32 v[134:135], v[2:3], v[134:135]
	v_cvt_pk_bf16_f32 v178, v178, v179
	v_cvt_pk_bf16_f32 v179, v182, v183
	v_cvt_pk_bf16_f32 v180, v180, v181
	v_cvt_pk_bf16_f32 v181, v188, v189
	v_pk_mul_f32 v[130:131], v[168:169], v[130:131] op_sel_hi:[0,1]
	v_pk_mul_f32 v[128:129], v[168:169], v[128:129] op_sel_hi:[0,1]
	v_pk_mul_f32 v[134:135], v[168:169], v[134:135] op_sel_hi:[0,1]
	v_pk_mul_f32 v[132:133], v[168:169], v[132:133] op_sel_hi:[0,1]
	global_store_dwordx4 v[198:199], v[178:181], off offset:64
	v_cvt_pk_bf16_f32 v128, v128, v129
	v_cvt_pk_bf16_f32 v129, v130, v131
	v_cvt_pk_bf16_f32 v130, v132, v133
	v_cvt_pk_bf16_f32 v131, v134, v135
	global_store_dwordx4 v[160:161], v[128:131], off offset:64

.LBB0_1727:
	ds_read_b128 v[128:131], v163
	ds_read_b128 v[132:135], v163 offset:1024
	ds_read_b128 v[172:175], v163 offset:2048
	ds_read_b128 v[176:179], v163 offset:3072
	ds_read_b128 v[180:183], v165
	ds_read_b128 v[186:189], v165 offset:1024
	ds_read_b128 v[190:193], v165 offset:2048
	ds_read_b128 v[194:197], v165 offset:3072
	s_add_u32 s26, s24, 0xfffc0080
	s_addc_u32 s27, s25, -1
	s_cmp_eq_u32 s51, 12
	s_cselect_b32 s29, s15, s27
	s_cselect_b32 s28, s47, s26
	s_cselect_b32 s27, s17, s50
	s_cselect_b32 s26, s48, s49
	s_add_i32 m0, s23, 0xc000
	ds_read_b128 v[198:201], v167
	ds_read_b128 v[202:205], v167 offset:1024
	ds_read_b128 v[206:209], v167 offset:2048
	ds_read_b128 v[210:213], v167 offset:3072
	ds_read_b128 v[214:217], v167 offset:4096
	ds_read_b128 v[218:221], v167 offset:5120
	ds_read_b128 v[222:225], v167 offset:6144
	ds_read_b128 v[226:229], v167 offset:7168
	global_load_lds_dwordx4 v148, s[24:25]
	s_add_i32 m0, s23, 0xe000
	s_nop 0
	global_load_lds_dwordx4 v150, s[24:25]
	s_waitcnt vmcnt(8)
	s_waitcnt lgkmcnt(0)
	s_barrier
	s_waitcnt lgkmcnt(0)
	v_mfma_f32_16x16x32_bf16 v[124:127], v[128:131], v[198:201], v[124:127]
	v_mfma_f32_16x16x32_bf16 v[120:123], v[172:175], v[198:201], v[120:123]
	v_mfma_f32_16x16x32_bf16 v[116:119], v[128:131], v[206:209], v[116:119]
	v_mfma_f32_16x16x32_bf16 v[112:115], v[172:175], v[206:209], v[112:115]
	v_mfma_f32_16x16x32_bf16 v[108:111], v[128:131], v[214:217], v[108:111]
	v_mfma_f32_16x16x32_bf16 v[104:107], v[172:175], v[214:217], v[104:107]
	v_mfma_f32_16x16x32_bf16 v[100:103], v[128:131], v[222:225], v[100:103]
	v_mfma_f32_16x16x32_bf16 v[96:99], v[172:175], v[222:225], v[96:99]
	v_mfma_f32_16x16x32_bf16 v[124:127], v[132:135], v[202:205], v[124:127]
	v_mfma_f32_16x16x32_bf16 v[120:123], v[176:179], v[202:205], v[120:123]
	v_mfma_f32_16x16x32_bf16 v[116:119], v[132:135], v[210:213], v[116:119]
	v_mfma_f32_16x16x32_bf16 v[112:115], v[176:179], v[210:213], v[112:115]
	v_mfma_f32_16x16x32_bf16 v[108:111], v[132:135], v[218:221], v[108:111]
	v_mfma_f32_16x16x32_bf16 v[104:107], v[176:179], v[218:221], v[104:107]
	v_mfma_f32_16x16x32_bf16 v[100:103], v[132:135], v[226:229], v[100:103]
	v_mfma_f32_16x16x32_bf16 v[96:99], v[176:179], v[226:229], v[96:99]
	v_mfma_f32_16x16x32_bf16 v[72:75], v[180:183], v[198:201], v[72:75]
	v_mfma_f32_16x16x32_bf16 v[64:67], v[190:193], v[198:201], v[64:67]
	v_mfma_f32_16x16x32_bf16 v[56:59], v[180:183], v[206:209], v[56:59]
	v_mfma_f32_16x16x32_bf16 v[48:51], v[190:193], v[206:209], v[48:51]
	v_mfma_f32_16x16x32_bf16 v[44:47], v[180:183], v[214:217], v[44:47]
	v_mfma_f32_16x16x32_bf16 v[40:43], v[190:193], v[214:217], v[40:43]
	v_mfma_f32_16x16x32_bf16 v[36:39], v[180:183], v[222:225], v[36:39]
	v_mfma_f32_16x16x32_bf16 v[32:35], v[190:193], v[222:225], v[32:35]
	v_mfma_f32_16x16x32_bf16 v[72:75], v[186:189], v[202:205], v[72:75]
	v_mfma_f32_16x16x32_bf16 v[64:67], v[194:197], v[202:205], v[64:67]
	v_mfma_f32_16x16x32_bf16 v[56:59], v[186:189], v[210:213], v[56:59]
	v_mfma_f32_16x16x32_bf16 v[48:51], v[194:197], v[210:213], v[48:51]
	v_mfma_f32_16x16x32_bf16 v[44:47], v[186:189], v[218:221], v[44:47]
	v_mfma_f32_16x16x32_bf16 v[40:43], v[194:197], v[218:221], v[40:43]
	v_mfma_f32_16x16x32_bf16 v[36:39], v[186:189], v[226:229], v[36:39]
	v_mfma_f32_16x16x32_bf16 v[32:35], v[194:197], v[226:229], v[32:35]
	s_barrier
	s_add_i32 s52, s44, s34
	s_mov_b32 m0, s52
	ds_read_b128 v[198:201], v167 offset:16384
	ds_read_b128 v[202:205], v167 offset:17408
	ds_read_b128 v[206:209], v167 offset:18432
	ds_read_b128 v[210:213], v167 offset:19456
	ds_read_b128 v[214:217], v167 offset:20480
	ds_read_b128 v[218:221], v167 offset:21504
	ds_read_b128 v[222:225], v167 offset:22528
	ds_read_b128 v[226:229], v167 offset:23552
	global_load_lds_dwordx4 v138, s[26:27]
	s_add_i32 m0, s52, 0x2000
	s_add_u32 s52, s26, 0x40000
	s_addc_u32 s53, s27, 0
	s_add_i32 s54, s45, s34
	global_load_lds_dwordx4 v142, s[26:27]
	s_mov_b32 m0, s54
	global_load_lds_dwordx4 v138, s[52:53]
	s_add_i32 m0, s54, 0x2000
	s_nop 0
	global_load_lds_dwordx4 v142, s[52:53]
	s_mov_b32 m0, s23
	s_nop 0
	global_load_lds_dwordx4 v136, s[28:29]
	s_mov_b32 m0, s35
	s_nop 0
	global_load_lds_dwordx4 v140, s[28:29]
	s_add_u32 s98, s26, s10
	s_addc_u32 s99, s27, s11
	s_add_u32 s100, s28, s10
	s_addc_u32 s101, s29, s11
	s_waitcnt vmcnt(8)
	s_waitcnt lgkmcnt(0)
	s_barrier
	s_waitcnt lgkmcnt(0)
	v_mfma_f32_16x16x32_bf16 v[92:95], v[128:131], v[198:201], v[92:95]
	v_mfma_f32_16x16x32_bf16 v[88:91], v[172:175], v[198:201], v[88:91]
	v_mfma_f32_16x16x32_bf16 v[84:87], v[128:131], v[206:209], v[84:87]
	v_mfma_f32_16x16x32_bf16 v[80:83], v[172:175], v[206:209], v[80:83]
	v_mfma_f32_16x16x32_bf16 v[76:79], v[128:131], v[214:217], v[76:79]
	v_mfma_f32_16x16x32_bf16 v[68:71], v[172:175], v[214:217], v[68:71]
	v_mfma_f32_16x16x32_bf16 v[60:63], v[128:131], v[222:225], v[60:63]
	v_mfma_f32_16x16x32_bf16 v[52:55], v[172:175], v[222:225], v[52:55]
	v_mfma_f32_16x16x32_bf16 v[92:95], v[132:135], v[202:205], v[92:95]
	v_mfma_f32_16x16x32_bf16 v[88:91], v[176:179], v[202:205], v[88:91]
	v_mfma_f32_16x16x32_bf16 v[84:87], v[132:135], v[210:213], v[84:87]
	v_mfma_f32_16x16x32_bf16 v[80:83], v[176:179], v[210:213], v[80:83]
	v_mfma_f32_16x16x32_bf16 v[76:79], v[132:135], v[218:221], v[76:79]
	v_mfma_f32_16x16x32_bf16 v[68:71], v[176:179], v[218:221], v[68:71]
	v_mfma_f32_16x16x32_bf16 v[60:63], v[132:135], v[226:229], v[60:63]
	v_mfma_f32_16x16x32_bf16 v[52:55], v[176:179], v[226:229], v[52:55]
	v_mfma_f32_16x16x32_bf16 v[28:31], v[180:183], v[198:201], v[28:31]
	v_mfma_f32_16x16x32_bf16 v[24:27], v[190:193], v[198:201], v[24:27]
	v_mfma_f32_16x16x32_bf16 v[20:23], v[180:183], v[206:209], v[20:23]
	v_mfma_f32_16x16x32_bf16 v[16:19], v[190:193], v[206:209], v[16:19]
	v_mfma_f32_16x16x32_bf16 v[12:15], v[180:183], v[214:217], v[12:15]
	v_mfma_f32_16x16x32_bf16 v[8:11], v[190:193], v[214:217], v[8:11]
	v_mfma_f32_16x16x32_bf16 v[4:7], v[180:183], v[222:225], v[4:7]
	v_mfma_f32_16x16x32_bf16 v[0:3], v[190:193], v[222:225], v[0:3]
	v_mfma_f32_16x16x32_bf16 v[28:31], v[186:189], v[202:205], v[28:31]
	v_mfma_f32_16x16x32_bf16 v[24:27], v[194:197], v[202:205], v[24:27]
	v_mfma_f32_16x16x32_bf16 v[20:23], v[186:189], v[210:213], v[20:23]
	v_mfma_f32_16x16x32_bf16 v[16:19], v[194:197], v[210:213], v[16:19]
	v_mfma_f32_16x16x32_bf16 v[12:15], v[186:189], v[218:221], v[12:15]
	v_mfma_f32_16x16x32_bf16 v[8:11], v[194:197], v[218:221], v[8:11]
	v_mfma_f32_16x16x32_bf16 v[4:7], v[186:189], v[226:229], v[4:7]
	v_mfma_f32_16x16x32_bf16 v[0:3], v[194:197], v[226:229], v[0:3]
	s_barrier
	s_add_i32 s52, 0, 0x18000
	v_add_u32_e32 v158, s52, v161
	s_add_i32 s53, 0, 0x1c000
	ds_read_b128 v[128:131], v158
	ds_read_b128 v[132:135], v158 offset:1024
	ds_read_b128 v[172:175], v158 offset:2048
	ds_read_b128 v[176:179], v158 offset:3072
	v_add_u32_e32 v158, s53, v161
	ds_read_b128 v[180:183], v158
	ds_read_b128 v[186:189], v158 offset:1024
	ds_read_b128 v[190:193], v158 offset:2048
	ds_read_b128 v[194:197], v158 offset:3072
	s_add_u32 s28, s28, 0x40000
	s_addc_u32 s29, s29, 0
	s_mov_b32 m0, s36
	ds_read_b128 v[198:201], v167 offset:32768
	ds_read_b128 v[202:205], v167 offset:33792
	ds_read_b128 v[206:209], v167 offset:34816
	ds_read_b128 v[210:213], v167 offset:35840
	ds_read_b128 v[214:217], v167 offset:36864
	ds_read_b128 v[218:221], v167 offset:37888
	ds_read_b128 v[222:225], v167 offset:38912
	ds_read_b128 v[226:229], v167 offset:39936
	global_load_lds_dwordx4 v136, s[28:29]
	s_mov_b32 m0, s37
	s_nop 0
	global_load_lds_dwordx4 v140, s[28:29]
	s_waitcnt vmcnt(8)
	s_waitcnt lgkmcnt(0)
	s_barrier
	s_waitcnt lgkmcnt(0)
	v_mfma_f32_16x16x32_bf16 v[124:127], v[128:131], v[198:201], v[124:127]
	v_mfma_f32_16x16x32_bf16 v[120:123], v[172:175], v[198:201], v[120:123]
	v_mfma_f32_16x16x32_bf16 v[116:119], v[128:131], v[206:209], v[116:119]
	v_mfma_f32_16x16x32_bf16 v[112:115], v[172:175], v[206:209], v[112:115]
	v_mfma_f32_16x16x32_bf16 v[108:111], v[128:131], v[214:217], v[108:111]
	v_mfma_f32_16x16x32_bf16 v[104:107], v[172:175], v[214:217], v[104:107]
	v_mfma_f32_16x16x32_bf16 v[100:103], v[128:131], v[222:225], v[100:103]
	v_mfma_f32_16x16x32_bf16 v[96:99], v[172:175], v[222:225], v[96:99]
	v_mfma_f32_16x16x32_bf16 v[124:127], v[132:135], v[202:205], v[124:127]
	v_mfma_f32_16x16x32_bf16 v[120:123], v[176:179], v[202:205], v[120:123]
	v_mfma_f32_16x16x32_bf16 v[116:119], v[132:135], v[210:213], v[116:119]
	v_mfma_f32_16x16x32_bf16 v[112:115], v[176:179], v[210:213], v[112:115]
	v_mfma_f32_16x16x32_bf16 v[108:111], v[132:135], v[218:221], v[108:111]
	v_mfma_f32_16x16x32_bf16 v[104:107], v[176:179], v[218:221], v[104:107]
	v_mfma_f32_16x16x32_bf16 v[100:103], v[132:135], v[226:229], v[100:103]
	v_mfma_f32_16x16x32_bf16 v[96:99], v[176:179], v[226:229], v[96:99]
	v_mfma_f32_16x16x32_bf16 v[72:75], v[180:183], v[198:201], v[72:75]
	v_mfma_f32_16x16x32_bf16 v[64:67], v[190:193], v[198:201], v[64:67]
	v_mfma_f32_16x16x32_bf16 v[56:59], v[180:183], v[206:209], v[56:59]
	v_mfma_f32_16x16x32_bf16 v[48:51], v[190:193], v[206:209], v[48:51]
	v_mfma_f32_16x16x32_bf16 v[44:47], v[180:183], v[214:217], v[44:47]
	v_mfma_f32_16x16x32_bf16 v[40:43], v[190:193], v[214:217], v[40:43]
	v_mfma_f32_16x16x32_bf16 v[36:39], v[180:183], v[222:225], v[36:39]
	v_mfma_f32_16x16x32_bf16 v[32:35], v[190:193], v[222:225], v[32:35]
	v_mfma_f32_16x16x32_bf16 v[72:75], v[186:189], v[202:205], v[72:75]
	v_mfma_f32_16x16x32_bf16 v[64:67], v[194:197], v[202:205], v[64:67]
	v_mfma_f32_16x16x32_bf16 v[56:59], v[186:189], v[210:213], v[56:59]
	v_mfma_f32_16x16x32_bf16 v[48:51], v[194:197], v[210:213], v[48:51]
	v_mfma_f32_16x16x32_bf16 v[44:47], v[186:189], v[218:221], v[44:47]
	v_mfma_f32_16x16x32_bf16 v[40:43], v[194:197], v[218:221], v[40:43]
	v_mfma_f32_16x16x32_bf16 v[36:39], v[186:189], v[226:229], v[36:39]
	v_mfma_f32_16x16x32_bf16 v[32:35], v[194:197], v[226:229], v[32:35]
	s_barrier
	s_add_i32 s28, s52, s34
	s_mov_b32 m0, s28
	ds_read_b128 v[198:201], v167 offset:49152
	ds_read_b128 v[202:205], v167 offset:50176
	ds_read_b128 v[206:209], v167 offset:51200
	ds_read_b128 v[210:213], v167 offset:52224
	ds_read_b128 v[214:217], v167 offset:53248
	ds_read_b128 v[218:221], v167 offset:54272
	ds_read_b128 v[222:225], v167 offset:55296
	ds_read_b128 v[226:229], v167 offset:56320
	global_load_lds_dwordx4 v138, s[98:99]
	s_add_i32 m0, s28, 0x2000
	s_add_u32 s26, s26, 0x40080
	s_addc_u32 s27, s27, 0
	s_add_i32 s28, s53, s34
	global_load_lds_dwordx4 v142, s[98:99]
	s_mov_b32 m0, s28
	s_nop 0
	global_load_lds_dwordx4 v138, s[26:27]
	s_add_i32 m0, s28, 0x2000
	s_nop 0
	global_load_lds_dwordx4 v142, s[26:27]
	s_mov_b32 m0, s39
	s_nop 0
	global_load_lds_dwordx4 v136, s[100:101]
	s_mov_b32 m0, s40
	s_nop 0
	global_load_lds_dwordx4 v140, s[100:101]
	s_waitcnt vmcnt(8)
	s_waitcnt lgkmcnt(0)
	s_barrier
	s_waitcnt lgkmcnt(0)
	v_mfma_f32_16x16x32_bf16 v[92:95], v[128:131], v[198:201], v[92:95]
	v_mfma_f32_16x16x32_bf16 v[88:91], v[172:175], v[198:201], v[88:91]
	s_cmp_eq_u32 s51, 12
	s_cbranch_scc0 .Lrs_skip_1727
	v_lshl_add_u32 v252, s22, 8, v159
	v_ashrrev_i32_e32 v253, 31, v252
	v_lshl_add_u64 v[254:255], v[252:253], 2, s[8:9]
	global_load_dword v243, v[254:255], off
	global_load_dword v244, v[254:255], off offset:64
	global_load_dword v245, v[254:255], off offset:128
	global_load_dword v246, v[254:255], off offset:192
	global_load_dword v247, v[254:255], off offset:512
	global_load_dword v248, v[254:255], off offset:576
	global_load_dword v249, v[254:255], off offset:640
	global_load_dword v250, v[254:255], off offset:704
.Lrs_skip_1727:
	v_mfma_f32_16x16x32_bf16 v[84:87], v[128:131], v[206:209], v[84:87]
	v_mfma_f32_16x16x32_bf16 v[80:83], v[172:175], v[206:209], v[80:83]
	v_mfma_f32_16x16x32_bf16 v[76:79], v[128:131], v[214:217], v[76:79]
	v_mfma_f32_16x16x32_bf16 v[68:71], v[172:175], v[214:217], v[68:71]
	v_mfma_f32_16x16x32_bf16 v[60:63], v[128:131], v[222:225], v[60:63]
	v_mfma_f32_16x16x32_bf16 v[52:55], v[172:175], v[222:225], v[52:55]
	v_mfma_f32_16x16x32_bf16 v[92:95], v[132:135], v[202:205], v[92:95]
	v_mfma_f32_16x16x32_bf16 v[88:91], v[176:179], v[202:205], v[88:91]
	v_mfma_f32_16x16x32_bf16 v[84:87], v[132:135], v[210:213], v[84:87]
	v_mfma_f32_16x16x32_bf16 v[80:83], v[176:179], v[210:213], v[80:83]
	v_mfma_f32_16x16x32_bf16 v[76:79], v[132:135], v[218:221], v[76:79]
	v_mfma_f32_16x16x32_bf16 v[68:71], v[176:179], v[218:221], v[68:71]
	v_mfma_f32_16x16x32_bf16 v[60:63], v[132:135], v[226:229], v[60:63]
	v_mfma_f32_16x16x32_bf16 v[52:55], v[176:179], v[226:229], v[52:55]
	v_mfma_f32_16x16x32_bf16 v[28:31], v[180:183], v[198:201], v[28:31]
	v_mfma_f32_16x16x32_bf16 v[24:27], v[190:193], v[198:201], v[24:27]
	v_mfma_f32_16x16x32_bf16 v[20:23], v[180:183], v[206:209], v[20:23]
	v_mfma_f32_16x16x32_bf16 v[16:19], v[190:193], v[206:209], v[16:19]
	v_mfma_f32_16x16x32_bf16 v[12:15], v[180:183], v[214:217], v[12:15]
	v_mfma_f32_16x16x32_bf16 v[8:11], v[190:193], v[214:217], v[8:11]
	v_mfma_f32_16x16x32_bf16 v[4:7], v[180:183], v[222:225], v[4:7]
	v_mfma_f32_16x16x32_bf16 v[0:3], v[190:193], v[222:225], v[0:3]
	v_mfma_f32_16x16x32_bf16 v[28:31], v[186:189], v[202:205], v[28:31]
	v_mfma_f32_16x16x32_bf16 v[24:27], v[194:197], v[202:205], v[24:27]
	v_mfma_f32_16x16x32_bf16 v[20:23], v[186:189], v[210:213], v[20:23]
	v_mfma_f32_16x16x32_bf16 v[16:19], v[194:197], v[210:213], v[16:19]
	v_mfma_f32_16x16x32_bf16 v[12:15], v[186:189], v[218:221], v[12:15]
	v_mfma_f32_16x16x32_bf16 v[8:11], v[194:197], v[218:221], v[8:11]
	v_mfma_f32_16x16x32_bf16 v[4:7], v[186:189], v[226:229], v[4:7]
	v_mfma_f32_16x16x32_bf16 v[0:3], v[194:197], v[226:229], v[0:3]
	s_barrier
	s_add_i32 s51, s51, 2
	s_add_u32 s24, s24, 0x100
	s_addc_u32 s25, s25, 0
	s_add_u32 s49, s49, 0x100
	s_addc_u32 s50, s50, 0
	s_cmp_gt_u32 s51, 13
	s_cbranch_scc0 .LBB0_1727
	s_and_b64 vcc, exec, s[12:13]
	s_cbranch_vccz .LBB0_1730
	s_barrier
.LBB0_1730:
	v_lshl_add_u32 v156, s22, 8, v159
	v_ashrrev_i32_e32 v157, 31, v156
	v_lshl_add_u64 v[128:129], v[156:157], 2, s[8:9]
	s_waitcnt vmcnt(0)
	v_mov_b32_e32 v162, v243
	v_mov_b32_e32 v164, v244
	v_mov_b32_e32 v166, v245
	v_mov_b32_e32 v168, v246
	v_mov_b32_e32 v170, v247
	v_mov_b32_e32 v188, v248
	v_mov_b32_e32 v189, v249
	v_mov_b32_e32 v190, v250
	v_and_b32_e32 v180, 64, v171
	v_pk_mul_f32 v[128:129], v[126:127], v[126:127]
	v_pk_mul_f32 v[130:131], v[124:125], v[124:125]
	v_pk_mul_f32 v[132:133], v[122:123], v[122:123]
	v_pk_mul_f32 v[134:135], v[120:121], v[120:121]
	v_add_u32_e32 v201, 64, v180
	v_pk_mov_b32 v[180:181], v[130:131], v[128:129] op_sel:[1,0]
	v_mov_b32_e32 v131, v129
	v_pk_mov_b32 v[128:129], v[134:135], v[132:133] op_sel:[1,0]
	v_mov_b32_e32 v135, v133
	v_mul_f32_e32 v158, v73, v73
	v_mul_f32_e32 v160, v75, v75
	v_pk_add_f32 v[130:131], v[180:181], v[130:131]
	v_pk_add_f32 v[128:129], v[128:129], v[134:135]
	v_mul_f32_e32 v193, v64, v64
	v_mul_f32_e32 v194, v65, v65
	v_mul_f32_e32 v195, v66, v66
	v_mul_f32_e32 v196, v67, v67
	v_pk_fma_f32 v[132:133], v[72:73], v[72:73], v[158:159] op_sel_hi:[1,1,0]
	v_pk_fma_f32 v[182:183], v[74:75], v[74:75], v[160:161] op_sel_hi:[1,1,0]
	v_pk_add_f32 v[130:131], v[130:131], v[130:131] op_sel:[0,1] op_sel_hi:[1,0]
	v_pk_add_f32 v[128:129], v[128:129], v[128:129] op_sel:[0,1] op_sel_hi:[1,0]
	v_xor_b32_e32 v191, 16, v171
	v_mov_b32_e32 v133, v195
	v_mov_b32_e32 v183, v196
	v_mov_b32_e32 v131, v193
	v_mov_b32_e32 v129, v194
	v_cmp_lt_i32_e32 vcc, v191, v201
	v_pk_add_f32 v[132:133], v[132:133], v[182:183]
	v_pk_add_f32 v[128:129], v[130:131], v[128:129]
	v_cndmask_b32_e32 v158, v171, v191, vcc
	v_pk_add_f32 v[128:129], v[128:129], v[132:133]
	v_lshlrev_b32_e32 v180, 2, v158
	v_add_f32_e32 v130, v128, v129
	ds_bpermute_b32 v131, v180, v130
	v_xor_b32_e32 v192, 32, v171
	v_cmp_lt_i32_e32 vcc, v192, v201
	v_pk_mul_f32 v[172:173], v[118:119], v[118:119]
	v_pk_mul_f32 v[174:175], v[116:117], v[116:117]
	v_cndmask_b32_e32 v132, v171, v192, vcc
	v_lshlrev_b32_e32 v181, 2, v132
	s_waitcnt lgkmcnt(0)
	v_add_f32_e32 v132, v130, v131
	v_pk_mul_f32 v[176:177], v[114:115], v[114:115]
	v_pk_mul_f32 v[178:179], v[112:113], v[112:113]
	ds_bpermute_b32 v133, v181, v132
	v_pk_mov_b32 v[186:187], v[174:175], v[172:173] op_sel:[1,0]
	v_mov_b32_e32 v175, v173
	v_pk_mov_b32 v[172:173], v[178:179], v[176:177] op_sel:[1,0]
	v_mov_b32_e32 v179, v177
	v_pk_add_f32 v[130:131], v[172:173], v[178:179]
	v_pk_add_f32 v[128:129], v[186:187], v[174:175]
	v_pk_add_f32 v[130:131], v[130:131], v[130:131] op_sel:[0,1] op_sel_hi:[1,0]
	v_mul_f32_e32 v197, v48, v48
	v_mul_f32_e32 v198, v49, v49
	v_pk_add_f32 v[128:129], v[128:129], v[128:129] op_sel:[0,1] op_sel_hi:[1,0]
	s_waitcnt lgkmcnt(0)
	v_add_f32_e32 v134, v132, v133
	v_mov_b32_e32 v129, v197
	v_mul_f32_e32 v199, v50, v50
	v_mul_f32_e32 v200, v51, v51
	v_pk_mul_f32 v[174:175], v[70:71], v[70:71]
	v_pk_mul_f32 v[176:177], v[68:69], v[68:69]
	s_lshl_b32 s15, s46, 8
	v_pk_mov_b32 v[178:179], v[176:177], v[174:175] op_sel:[1,0]
	v_mov_b32_e32 v177, v175
	v_pk_add_f32 v[174:175], v[178:179], v[176:177]
	v_mul_f32_e32 v176, v9, v9
	v_pk_add_f32 v[174:175], v[174:175], v[174:175] op_sel:[0,1] op_sel_hi:[1,0]
	v_mul_f32_e32 v177, v10, v10
	v_mov_b32_e32 v175, v176
	v_mul_f32_e32 v178, v11, v11
	s_or_b32 s24, s15, s41
	s_ashr_i32 s25, s24, 31
	s_waitcnt vmcnt(0)
	v_fmamk_f32 v131, v162, 0x3a800000, v169
	v_fmamk_f32 v132, v164, 0x3a800000, v169
	v_fmamk_f32 v133, v166, 0x3a800000, v169
	v_rsq_f32_e32 v166, v131
	v_mov_b32_e32 v131, v198
	v_fmamk_f32 v135, v168, 0x3a800000, v169
	v_rsq_f32_e32 v168, v132
	v_pk_add_f32 v[128:129], v[128:129], v[130:131]
	v_mul_f32_e32 v130, v57, v57
	v_mul_f32_e32 v132, v59, v59
	v_fmamk_f32 v158, v170, 0x3a800000, v169
	v_rsq_f32_e32 v170, v133
	v_pk_fma_f32 v[130:131], v[56:57], v[56:57], v[130:131] op_sel_hi:[1,1,0]
	v_pk_fma_f32 v[132:133], v[58:59], v[58:59], v[132:133] op_sel_hi:[1,1,0]
	v_mov_b32_e32 v131, v199
	v_mov_b32_e32 v133, v200
	v_pk_add_f32 v[130:131], v[130:131], v[132:133]
	v_fmamk_f32 v160, v188, 0x3a800000, v169
	v_pk_add_f32 v[128:129], v[128:129], v[130:131]
	v_mul_f32_e32 v130, v166, v134
	v_add_f32_e32 v128, v128, v129
	ds_bpermute_b32 v129, v180, v128
	v_mul_f32_e32 v130, v166, v130
	v_fmamk_f32 v130, v130, 0x3c800000, v169
	v_rsq_f32_e32 v173, v158
	v_rsq_f32_e32 v182, v160
	v_rsq_f32_e32 v158, v130
	s_waitcnt lgkmcnt(0)
	v_add_f32_e32 v160, v128, v129
	v_pk_mul_f32 v[128:129], v[110:111], v[110:111]
	v_pk_mul_f32 v[130:131], v[108:109], v[108:109]
	v_rsq_f32_e32 v172, v135
	v_pk_mov_b32 v[132:133], v[130:131], v[128:129] op_sel:[1,0]
	v_mov_b32_e32 v131, v129
	v_pk_add_f32 v[128:129], v[132:133], v[130:131]
	v_pk_mul_f32 v[130:131], v[106:107], v[106:107]
	v_pk_mul_f32 v[132:133], v[104:105], v[104:105]
	v_pk_add_f32 v[128:129], v[128:129], v[128:129] op_sel:[0,1] op_sel_hi:[1,0]
	v_pk_mov_b32 v[134:135], v[132:133], v[130:131] op_sel:[1,0]
	v_mov_b32_e32 v133, v131
	v_pk_add_f32 v[130:131], v[134:135], v[132:133]
	v_mul_f32_e32 v132, v40, v40
	v_mul_f32_e32 v133, v41, v41
	v_pk_add_f32 v[130:131], v[130:131], v[130:131] op_sel:[0,1] op_sel_hi:[1,0]
	v_mov_b32_e32 v129, v132
	v_mov_b32_e32 v131, v133
	v_pk_add_f32 v[128:129], v[128:129], v[130:131]
	v_mul_f32_e32 v130, v45, v45
	v_mul_f32_e32 v132, v47, v47
	v_mul_f32_e32 v134, v42, v42
	v_mul_f32_e32 v135, v43, v43
	v_pk_fma_f32 v[130:131], v[44:45], v[44:45], v[130:131] op_sel_hi:[1,1,0]
	v_pk_fma_f32 v[132:133], v[46:47], v[46:47], v[132:133] op_sel_hi:[1,1,0]
	v_mov_b32_e32 v131, v134
	v_mov_b32_e32 v133, v135
	v_pk_add_f32 v[130:131], v[130:131], v[132:133]
	v_fmamk_f32 v162, v189, 0x3a800000, v169
	v_pk_add_f32 v[128:129], v[128:129], v[130:131]
	v_rsq_f32_e32 v183, v162
	v_add_f32_e32 v128, v128, v129
	ds_bpermute_b32 v129, v180, v128
	ds_bpermute_b32 v162, v181, v160
	v_mul_f32_e32 v130, 0x3e38aa3b, v166
	v_mul_f32_e32 v158, v130, v158
	v_fmamk_f32 v164, v190, 0x3a800000, v169
	s_waitcnt lgkmcnt(1)
	v_add_f32_e32 v128, v128, v129
	ds_bpermute_b32 v129, v181, v128
	s_waitcnt lgkmcnt(1)
	v_add_f32_e32 v130, v160, v162
	v_mul_f32_e32 v130, v168, v130
	v_mul_f32_e32 v130, v168, v130
	v_fmamk_f32 v130, v130, 0x3c800000, v169
	v_rsq_f32_e32 v160, v130
	s_waitcnt lgkmcnt(0)
	v_add_f32_e32 v162, v128, v129
	v_pk_mul_f32 v[128:129], v[102:103], v[102:103]
	v_pk_mul_f32 v[130:131], v[100:101], v[100:101]
	v_rsq_f32_e32 v186, v164
	v_pk_mov_b32 v[132:133], v[130:131], v[128:129] op_sel:[1,0]
	v_mov_b32_e32 v131, v129
	v_pk_add_f32 v[128:129], v[132:133], v[130:131]
	v_pk_mul_f32 v[130:131], v[98:99], v[98:99]
	v_pk_mul_f32 v[132:133], v[96:97], v[96:97]
	v_pk_add_f32 v[128:129], v[128:129], v[128:129] op_sel:[0,1] op_sel_hi:[1,0]
	v_pk_mov_b32 v[134:135], v[132:133], v[130:131] op_sel:[1,0]
	v_mov_b32_e32 v133, v131
	v_pk_add_f32 v[130:131], v[134:135], v[132:133]
	v_mul_f32_e32 v132, v32, v32
	v_mul_f32_e32 v133, v33, v33
	v_pk_add_f32 v[130:131], v[130:131], v[130:131] op_sel:[0,1] op_sel_hi:[1,0]
	v_mov_b32_e32 v129, v132
	v_mov_b32_e32 v131, v133
	v_pk_add_f32 v[128:129], v[128:129], v[130:131]
	v_mul_f32_e32 v130, v37, v37
	v_mul_f32_e32 v132, v39, v39
	v_mul_f32_e32 v134, v34, v34
	v_mul_f32_e32 v135, v35, v35
	v_pk_fma_f32 v[130:131], v[36:37], v[36:37], v[130:131] op_sel_hi:[1,1,0]
	v_pk_fma_f32 v[132:133], v[38:39], v[38:39], v[132:133] op_sel_hi:[1,1,0]
	v_mov_b32_e32 v131, v134
	v_mov_b32_e32 v133, v135
	v_pk_add_f32 v[130:131], v[130:131], v[132:133]
	s_andn2_b64 vcc, exec, s[4:5]
	v_pk_add_f32 v[128:129], v[128:129], v[130:131]
	v_mul_f32_e32 v130, v170, v162
	v_add_f32_e32 v128, v128, v129
	ds_bpermute_b32 v129, v180, v128
	v_mul_f32_e32 v130, v170, v130
	v_fmamk_f32 v130, v130, 0x3c800000, v169
	v_rsq_f32_e32 v130, v130
	v_mul_f32_e32 v131, 0x3e38aa3b, v168
	s_waitcnt lgkmcnt(0)
	v_add_f32_e32 v128, v128, v129
	ds_bpermute_b32 v129, v181, v128
	v_mul_f32_e32 v162, v131, v160
	v_mul_f32_e32 v131, 0x3e38aa3b, v170
	v_mul_f32_e32 v160, v131, v130
	v_pk_mul_f32 v[130:131], v[92:93], v[92:93]
	s_waitcnt lgkmcnt(0)
	v_add_f32_e32 v164, v128, v129
	v_pk_mul_f32 v[128:129], v[94:95], v[94:95]
	s_mov_b64 s[4:5], -1
	v_pk_mov_b32 v[132:133], v[130:131], v[128:129] op_sel:[1,0]
	v_mov_b32_e32 v131, v129
	v_pk_add_f32 v[128:129], v[132:133], v[130:131]
	v_pk_mul_f32 v[130:131], v[90:91], v[90:91]
	v_pk_mul_f32 v[132:133], v[88:89], v[88:89]
	v_pk_add_f32 v[128:129], v[128:129], v[128:129] op_sel:[0,1] op_sel_hi:[1,0]
	v_pk_mov_b32 v[134:135], v[132:133], v[130:131] op_sel:[1,0]
	v_mov_b32_e32 v133, v131
	v_pk_add_f32 v[130:131], v[134:135], v[132:133]
	v_mul_f32_e32 v132, v24, v24
	v_mul_f32_e32 v133, v25, v25
	v_pk_add_f32 v[130:131], v[130:131], v[130:131] op_sel:[0,1] op_sel_hi:[1,0]
	v_mov_b32_e32 v129, v132
	v_mov_b32_e32 v131, v133
	v_pk_add_f32 v[128:129], v[128:129], v[130:131]
	v_mul_f32_e32 v130, v29, v29
	v_mul_f32_e32 v132, v31, v31
	v_mul_f32_e32 v134, v26, v26
	v_mul_f32_e32 v135, v27, v27
	v_pk_fma_f32 v[130:131], v[28:29], v[28:29], v[130:131] op_sel_hi:[1,1,0]
	v_pk_fma_f32 v[132:133], v[30:31], v[30:31], v[132:133] op_sel_hi:[1,1,0]
	v_mov_b32_e32 v131, v134
	v_mov_b32_e32 v133, v135
	v_pk_add_f32 v[130:131], v[130:131], v[132:133]
	s_nop 0
	v_pk_add_f32 v[128:129], v[128:129], v[130:131]
	v_mul_f32_e32 v130, v172, v164
	v_add_f32_e32 v128, v128, v129
	ds_bpermute_b32 v129, v180, v128
	v_mul_f32_e32 v130, v172, v130
	v_fmamk_f32 v130, v130, 0x3c800000, v169
	v_rsq_f32_e32 v164, v130
	v_pk_mul_f32 v[130:131], v[84:85], v[84:85]
	s_waitcnt lgkmcnt(0)
	v_add_f32_e32 v166, v128, v129
	v_pk_mul_f32 v[128:129], v[86:87], v[86:87]
	ds_bpermute_b32 v168, v181, v166
	v_pk_mov_b32 v[132:133], v[130:131], v[128:129] op_sel:[1,0]
	v_mov_b32_e32 v131, v129
	v_pk_add_f32 v[128:129], v[132:133], v[130:131]
	v_pk_mul_f32 v[130:131], v[82:83], v[82:83]
	v_pk_mul_f32 v[132:133], v[80:81], v[80:81]
	v_pk_add_f32 v[128:129], v[128:129], v[128:129] op_sel:[0,1] op_sel_hi:[1,0]
	v_pk_mov_b32 v[134:135], v[132:133], v[130:131] op_sel:[1,0]
	v_mov_b32_e32 v133, v131
	v_pk_add_f32 v[130:131], v[134:135], v[132:133]
	v_mul_f32_e32 v132, v16, v16
	v_mul_f32_e32 v133, v17, v17
	v_pk_add_f32 v[130:131], v[130:131], v[130:131] op_sel:[0,1] op_sel_hi:[1,0]
	v_mov_b32_e32 v129, v132
	v_mov_b32_e32 v131, v133
	v_pk_add_f32 v[128:129], v[128:129], v[130:131]
	v_mul_f32_e32 v130, v21, v21
	v_mul_f32_e32 v132, v23, v23
	v_mul_f32_e32 v134, v18, v18
	v_mul_f32_e32 v135, v19, v19
	v_pk_fma_f32 v[130:131], v[20:21], v[20:21], v[130:131] op_sel_hi:[1,1,0]
	v_pk_fma_f32 v[132:133], v[22:23], v[22:23], v[132:133] op_sel_hi:[1,1,0]
	v_mov_b32_e32 v131, v134
	v_mov_b32_e32 v133, v135
	v_pk_add_f32 v[130:131], v[130:131], v[132:133]
	s_nop 0
	v_pk_add_f32 v[128:129], v[128:129], v[130:131]
	v_mul_f32_e32 v130, 0x3e38aa3b, v172
	v_add_f32_e32 v128, v128, v129
	ds_bpermute_b32 v129, v180, v128
	v_mul_f32_e32 v164, v130, v164
	s_waitcnt lgkmcnt(1)
	v_add_f32_e32 v130, v166, v168
	v_mul_f32_e32 v130, v173, v130
	v_mul_f32_e32 v130, v173, v130
	s_waitcnt lgkmcnt(0)
	v_add_f32_e32 v128, v128, v129
	ds_bpermute_b32 v129, v181, v128
	v_fmamk_f32 v130, v130, 0x3c800000, v169
	v_rsq_f32_e32 v170, v130
	v_pk_mul_f32 v[130:131], v[76:77], v[76:77]
	v_mul_f32_e32 v168, 0x3e38aa3b, v173
	s_waitcnt lgkmcnt(0)
	v_add_f32_e32 v187, v128, v129
	v_pk_mul_f32 v[128:129], v[78:79], v[78:79]
	v_mul_f32_e32 v166, v8, v8
	v_pk_mov_b32 v[132:133], v[130:131], v[128:129] op_sel:[1,0]
	v_mov_b32_e32 v131, v129
	v_pk_add_f32 v[172:173], v[132:133], v[130:131]
	global_load_dwordx4 v[128:131], v[146:147], off offset:16
	global_load_dwordx4 v[132:135], v[146:147], off
	v_pk_add_f32 v[172:173], v[172:173], v[172:173] op_sel:[0,1] op_sel_hi:[1,0]
	s_waitcnt vmcnt(1)
	v_pk_mul_f32 v[122:123], v[122:123], v[130:131]
	v_mov_b32_e32 v173, v166
	v_mul_f32_e32 v166, v13, v13
	v_pk_add_f32 v[172:173], v[172:173], v[174:175]
	v_pk_fma_f32 v[174:175], v[12:13], v[12:13], v[166:167] op_sel_hi:[1,1,0]
	v_mul_f32_e32 v166, v15, v15
	v_mov_b32_e32 v175, v177
	v_pk_fma_f32 v[176:177], v[14:15], v[14:15], v[166:167] op_sel_hi:[1,1,0]
	s_waitcnt vmcnt(0)
	v_pk_mul_f32 v[124:125], v[124:125], v[132:133]
	v_mov_b32_e32 v177, v178
	v_pk_add_f32 v[174:175], v[174:175], v[176:177]
	v_pk_mul_f32 v[126:127], v[126:127], v[134:135]
	v_pk_add_f32 v[172:173], v[172:173], v[174:175]
	v_pk_mul_f32 v[174:175], v[60:61], v[60:61]
	v_add_f32_e32 v166, v172, v173
	ds_bpermute_b32 v172, v180, v166
	v_mul_f32_e32 v173, v182, v187
	v_mul_f32_e32 v173, v182, v173
	v_fmamk_f32 v173, v173, 0x3c800000, v169
	v_rsq_f32_e32 v187, v173
	s_waitcnt lgkmcnt(0)
	v_add_f32_e32 v188, v166, v172
	v_pk_mul_f32 v[172:173], v[62:63], v[62:63]
	v_mul_f32_e32 v166, v0, v0
	v_pk_mov_b32 v[176:177], v[174:175], v[172:173] op_sel:[1,0]
	v_mov_b32_e32 v175, v173
	v_pk_add_f32 v[172:173], v[176:177], v[174:175]
	v_pk_mul_f32 v[174:175], v[54:55], v[54:55]
	v_pk_mul_f32 v[176:177], v[52:53], v[52:53]
	v_pk_add_f32 v[172:173], v[172:173], v[172:173] op_sel:[0,1] op_sel_hi:[1,0]
	v_pk_mov_b32 v[178:179], v[176:177], v[174:175] op_sel:[1,0]
	v_mov_b32_e32 v177, v175
	v_pk_add_f32 v[174:175], v[178:179], v[176:177]
	v_mul_f32_e32 v176, v1, v1
	v_pk_add_f32 v[174:175], v[174:175], v[174:175] op_sel:[0,1] op_sel_hi:[1,0]
	v_mov_b32_e32 v173, v166
	v_mov_b32_e32 v175, v176
	v_mul_f32_e32 v166, v5, v5
	v_mul_f32_e32 v177, v2, v2
	v_pk_add_f32 v[172:173], v[172:173], v[174:175]
	v_pk_fma_f32 v[174:175], v[4:5], v[4:5], v[166:167] op_sel_hi:[1,1,0]
	v_mul_f32_e32 v166, v7, v7
	v_mul_f32_e32 v178, v3, v3
	v_mov_b32_e32 v175, v177
	v_pk_fma_f32 v[176:177], v[6:7], v[6:7], v[166:167] op_sel_hi:[1,1,0]
	v_pk_mul_f32 v[124:125], v[158:159], v[124:125] op_sel_hi:[0,1]
	v_mov_b32_e32 v177, v178
	v_pk_add_f32 v[174:175], v[174:175], v[176:177]
	v_pk_mul_f32 v[120:121], v[120:121], v[128:129]
	v_pk_add_f32 v[172:173], v[172:173], v[174:175]
	v_lshl_add_u64 v[174:175], s[24:25], 1, v[144:145]
	v_pk_mul_f32 v[126:127], v[158:159], v[126:127] op_sel_hi:[0,1]
	v_pk_mul_f32 v[176:177], v[158:159], v[122:123] op_sel_hi:[0,1]
	v_pk_mul_f32 v[122:123], v[158:159], v[120:121] op_sel_hi:[0,1]
	v_cvt_pk_bf16_f32 v120, v124, v125
	v_lshlrev_b64 v[124:125], 11, v[156:157]
	ds_bpermute_b32 v189, v181, v188
	v_add_f32_e32 v166, v172, v173
	v_cvt_pk_bf16_f32 v121, v126, v127
	v_cvt_pk_bf16_f32 v122, v122, v123
	v_cvt_pk_bf16_f32 v123, v176, v177
	v_lshl_add_u64 v[124:125], v[174:175], 0, v[124:125]
	ds_bpermute_b32 v173, v180, v166
	global_store_dwordx4 v[124:125], v[120:123], off
	v_pk_mul_f32 v[116:117], v[116:117], v[132:133]
	v_pk_mul_f32 v[118:119], v[118:119], v[134:135]
	v_or_b32_e32 v120, 16, v156
	v_pk_mul_f32 v[116:117], v[162:163], v[116:117] op_sel_hi:[0,1]
	v_pk_mul_f32 v[114:115], v[114:115], v[130:131]
	v_pk_mul_f32 v[112:113], v[112:113], v[128:129]
	v_ashrrev_i32_e32 v121, 31, v120
	v_pk_mul_f32 v[118:119], v[162:163], v[118:119] op_sel_hi:[0,1]
	v_pk_mul_f32 v[122:123], v[162:163], v[114:115] op_sel_hi:[0,1]
	v_pk_mul_f32 v[114:115], v[162:163], v[112:113] op_sel_hi:[0,1]
	v_cvt_pk_bf16_f32 v112, v116, v117
	v_lshlrev_b64 v[116:117], 11, v[120:121]
	v_mul_f32_e32 v172, v168, v170
	v_mul_f32_e32 v168, 0x3e38aa3b, v182
	v_cvt_pk_bf16_f32 v113, v118, v119
	v_cvt_pk_bf16_f32 v114, v114, v115
	v_cvt_pk_bf16_f32 v115, v122, v123
	v_lshl_add_u64 v[116:117], v[174:175], 0, v[116:117]
	v_mul_f32_e32 v170, v168, v187
	s_waitcnt lgkmcnt(1)
	v_add_f32_e32 v168, v188, v189
	global_store_dwordx4 v[116:117], v[112:115], off
	v_pk_mul_f32 v[108:109], v[108:109], v[132:133]
	s_waitcnt lgkmcnt(0)
	v_add_f32_e32 v166, v166, v173
	v_or_b32_e32 v112, 32, v156
	v_mul_f32_e32 v168, v183, v168
	v_pk_mul_f32 v[110:111], v[110:111], v[134:135]
	v_pk_mul_f32 v[108:109], v[160:161], v[108:109] op_sel_hi:[0,1]
	v_pk_mul_f32 v[106:107], v[106:107], v[130:131]
	v_pk_mul_f32 v[104:105], v[104:105], v[128:129]
	v_ashrrev_i32_e32 v113, 31, v112
	ds_bpermute_b32 v173, v181, v166
	v_mul_f32_e32 v168, v183, v168
	v_pk_mul_f32 v[110:111], v[160:161], v[110:111] op_sel_hi:[0,1]
	v_pk_mul_f32 v[114:115], v[160:161], v[106:107] op_sel_hi:[0,1]
	v_pk_mul_f32 v[106:107], v[160:161], v[104:105] op_sel_hi:[0,1]
	v_cvt_pk_bf16_f32 v104, v108, v109
	v_lshlrev_b64 v[108:109], 11, v[112:113]
	v_fmamk_f32 v168, v168, 0x3c800000, v169
	v_cvt_pk_bf16_f32 v105, v110, v111
	v_cvt_pk_bf16_f32 v106, v106, v107
	v_cvt_pk_bf16_f32 v107, v114, v115
	v_lshl_add_u64 v[108:109], v[174:175], 0, v[108:109]
	v_rsq_f32_e32 v168, v168
	global_store_dwordx4 v[108:109], v[104:107], off
	v_pk_mul_f32 v[100:101], v[100:101], v[132:133]
	v_pk_mul_f32 v[102:103], v[102:103], v[134:135]
	v_or_b32_e32 v104, 48, v156
	v_pk_mul_f32 v[100:101], v[164:165], v[100:101] op_sel_hi:[0,1]
	v_pk_mul_f32 v[98:99], v[98:99], v[130:131]
	v_pk_mul_f32 v[96:97], v[96:97], v[128:129]
	v_ashrrev_i32_e32 v105, 31, v104
	v_pk_mul_f32 v[102:103], v[164:165], v[102:103] op_sel_hi:[0,1]
	v_pk_mul_f32 v[106:107], v[164:165], v[98:99] op_sel_hi:[0,1]
	v_pk_mul_f32 v[98:99], v[164:165], v[96:97] op_sel_hi:[0,1]
	v_cvt_pk_bf16_f32 v96, v100, v101
	v_lshlrev_b64 v[100:101], 11, v[104:105]
	s_waitcnt lgkmcnt(0)
	v_add_f32_e32 v166, v166, v173
	v_mul_f32_e32 v173, 0x3e38aa3b, v183
	v_cvt_pk_bf16_f32 v97, v102, v103
	v_cvt_pk_bf16_f32 v98, v98, v99
	v_cvt_pk_bf16_f32 v99, v106, v107
	v_lshl_add_u64 v[100:101], v[174:175], 0, v[100:101]
	v_mul_f32_e32 v168, v173, v168
	v_mul_f32_e32 v173, 0x3e38aa3b, v186
	global_store_dwordx4 v[100:101], v[96:99], off
	v_pk_mul_f32 v[92:93], v[92:93], v[132:133]
	v_pk_mul_f32 v[94:95], v[94:95], v[134:135]
	v_add_u32_e32 v96, 0x80, v156
	v_pk_mul_f32 v[92:93], v[92:93], v[172:173] op_sel_hi:[1,0]
	v_pk_mul_f32 v[90:91], v[90:91], v[130:131]
	v_pk_mul_f32 v[88:89], v[88:89], v[128:129]
	v_ashrrev_i32_e32 v97, 31, v96
	v_pk_mul_f32 v[94:95], v[94:95], v[172:173] op_sel_hi:[1,0]
	v_pk_mul_f32 v[98:99], v[90:91], v[172:173] op_sel_hi:[1,0]
	v_pk_mul_f32 v[90:91], v[88:89], v[172:173] op_sel_hi:[1,0]
	v_cvt_pk_bf16_f32 v88, v92, v93
	v_lshlrev_b64 v[92:93], 11, v[96:97]
	v_cvt_pk_bf16_f32 v89, v94, v95
	v_cvt_pk_bf16_f32 v90, v90, v91
	v_cvt_pk_bf16_f32 v91, v98, v99
	v_lshl_add_u64 v[92:93], v[174:175], 0, v[92:93]
	global_store_dwordx4 v[92:93], v[88:91], off
	v_pk_mul_f32 v[84:85], v[84:85], v[132:133]
	v_mul_f32_e32 v166, v186, v166
	v_add_u32_e32 v88, 0x90, v156
	v_pk_mul_f32 v[86:87], v[86:87], v[134:135]
	v_pk_mul_f32 v[84:85], v[84:85], v[170:171] op_sel_hi:[1,0]
	v_pk_mul_f32 v[82:83], v[82:83], v[130:131]
	v_pk_mul_f32 v[80:81], v[80:81], v[128:129]
	v_ashrrev_i32_e32 v89, 31, v88
	v_mul_f32_e32 v166, v186, v166
	v_pk_mul_f32 v[86:87], v[86:87], v[170:171] op_sel_hi:[1,0]
	v_pk_mul_f32 v[90:91], v[82:83], v[170:171] op_sel_hi:[1,0]
	v_pk_mul_f32 v[82:83], v[80:81], v[170:171] op_sel_hi:[1,0]
	v_cvt_pk_bf16_f32 v80, v84, v85
	v_lshlrev_b64 v[84:85], 11, v[88:89]
	v_fmamk_f32 v166, v166, 0x3c800000, v169
	v_cvt_pk_bf16_f32 v81, v86, v87
	v_cvt_pk_bf16_f32 v82, v82, v83
	v_cvt_pk_bf16_f32 v83, v90, v91
	v_lshl_add_u64 v[84:85], v[174:175], 0, v[84:85]
	v_rsq_f32_e32 v166, v166
	global_store_dwordx4 v[84:85], v[80:83], off
	v_pk_mul_f32 v[76:77], v[76:77], v[132:133]
	v_pk_mul_f32 v[78:79], v[78:79], v[134:135]
	v_add_u32_e32 v80, 0xa0, v156
	v_pk_mul_f32 v[76:77], v[76:77], v[168:169] op_sel_hi:[1,0]
	v_pk_mul_f32 v[70:71], v[70:71], v[130:131]
	v_pk_mul_f32 v[68:69], v[68:69], v[128:129]
	v_ashrrev_i32_e32 v81, 31, v80
	v_pk_mul_f32 v[78:79], v[78:79], v[168:169] op_sel_hi:[1,0]
	v_pk_mul_f32 v[82:83], v[70:71], v[168:169] op_sel_hi:[1,0]
	v_pk_mul_f32 v[70:71], v[68:69], v[168:169] op_sel_hi:[1,0]
	v_cvt_pk_bf16_f32 v68, v76, v77
	v_lshlrev_b64 v[76:77], 11, v[80:81]
	v_cvt_pk_bf16_f32 v69, v78, v79
	v_cvt_pk_bf16_f32 v70, v70, v71
	v_cvt_pk_bf16_f32 v71, v82, v83
	v_lshl_add_u64 v[76:77], v[174:175], 0, v[76:77]
	v_mul_f32_e32 v166, v173, v166
	global_store_dwordx4 v[76:77], v[68:71], off
	v_pk_mul_f32 v[60:61], v[60:61], v[132:133]
	v_pk_mul_f32 v[62:63], v[62:63], v[134:135]
	v_add_u32_e32 v68, 0xb0, v156
	v_pk_mul_f32 v[60:61], v[60:61], v[166:167] op_sel_hi:[1,0]
	v_pk_mul_f32 v[54:55], v[54:55], v[130:131]
	v_pk_mul_f32 v[52:53], v[52:53], v[128:129]
	v_ashrrev_i32_e32 v69, 31, v68
	v_pk_mul_f32 v[62:63], v[62:63], v[166:167] op_sel_hi:[1,0]
	v_pk_mul_f32 v[70:71], v[54:55], v[166:167] op_sel_hi:[1,0]
	v_pk_mul_f32 v[54:55], v[52:53], v[166:167] op_sel_hi:[1,0]
	v_cvt_pk_bf16_f32 v52, v60, v61
	v_lshlrev_b64 v[60:61], 11, v[68:69]
	v_cvt_pk_bf16_f32 v53, v62, v63
	v_cvt_pk_bf16_f32 v54, v54, v55
	v_cvt_pk_bf16_f32 v55, v70, v71
	v_lshl_add_u64 v[68:69], v[174:175], 0, v[60:61]
	global_store_dwordx4 v[68:69], v[52:55], off
	global_load_dwordx4 v[52:55], v[146:147], off offset:128
	global_load_dwordx4 v[60:63], v[146:147], off offset:144
	s_waitcnt vmcnt(1)
	v_pk_mul_f32 v[70:71], v[74:75], v[54:55]
	v_pk_mul_f32 v[72:73], v[72:73], v[52:53]
	s_waitcnt vmcnt(0)
	v_pk_mul_f32 v[66:67], v[66:67], v[62:63]
	v_pk_mul_f32 v[64:65], v[64:65], v[60:61]
	v_pk_mul_f32 v[70:71], v[158:159], v[70:71] op_sel_hi:[0,1]
	v_pk_mul_f32 v[72:73], v[158:159], v[72:73] op_sel_hi:[0,1]
	v_pk_mul_f32 v[74:75], v[158:159], v[66:67] op_sel_hi:[0,1]
	v_pk_mul_f32 v[66:67], v[158:159], v[64:65] op_sel_hi:[0,1]
	v_cvt_pk_bf16_f32 v64, v72, v73
	v_cvt_pk_bf16_f32 v65, v70, v71
	v_cvt_pk_bf16_f32 v66, v66, v67
	v_cvt_pk_bf16_f32 v67, v74, v75
	v_pk_mul_f32 v[58:59], v[58:59], v[54:55]
	v_pk_mul_f32 v[56:57], v[56:57], v[52:53]
	v_pk_mul_f32 v[50:51], v[50:51], v[62:63]
	v_pk_mul_f32 v[48:49], v[48:49], v[60:61]
	global_store_dwordx4 v[124:125], v[64:67], off offset:64
	v_pk_mul_f32 v[58:59], v[162:163], v[58:59] op_sel_hi:[0,1]
	v_pk_mul_f32 v[56:57], v[162:163], v[56:57] op_sel_hi:[0,1]
	v_pk_mul_f32 v[64:65], v[162:163], v[50:51] op_sel_hi:[0,1]
	v_pk_mul_f32 v[50:51], v[162:163], v[48:49] op_sel_hi:[0,1]
	v_cvt_pk_bf16_f32 v48, v56, v57
	v_cvt_pk_bf16_f32 v49, v58, v59
	v_cvt_pk_bf16_f32 v50, v50, v51
	v_cvt_pk_bf16_f32 v51, v64, v65
	v_pk_mul_f32 v[46:47], v[46:47], v[54:55]
	v_pk_mul_f32 v[44:45], v[44:45], v[52:53]
	v_pk_mul_f32 v[42:43], v[42:43], v[62:63]
	v_pk_mul_f32 v[40:41], v[40:41], v[60:61]
	global_store_dwordx4 v[116:117], v[48:51], off offset:64
	v_pk_mul_f32 v[46:47], v[160:161], v[46:47] op_sel_hi:[0,1]
	v_pk_mul_f32 v[44:45], v[160:161], v[44:45] op_sel_hi:[0,1]
	v_pk_mul_f32 v[48:49], v[160:161], v[42:43] op_sel_hi:[0,1]
	v_pk_mul_f32 v[42:43], v[160:161], v[40:41] op_sel_hi:[0,1]
	v_cvt_pk_bf16_f32 v40, v44, v45
	v_cvt_pk_bf16_f32 v41, v46, v47
	v_cvt_pk_bf16_f32 v42, v42, v43
	v_cvt_pk_bf16_f32 v43, v48, v49
	v_pk_mul_f32 v[38:39], v[38:39], v[54:55]
	v_pk_mul_f32 v[36:37], v[36:37], v[52:53]
	v_pk_mul_f32 v[34:35], v[34:35], v[62:63]
	v_pk_mul_f32 v[32:33], v[32:33], v[60:61]
	global_store_dwordx4 v[108:109], v[40:43], off offset:64
	v_pk_mul_f32 v[38:39], v[164:165], v[38:39] op_sel_hi:[0,1]
	v_pk_mul_f32 v[36:37], v[164:165], v[36:37] op_sel_hi:[0,1]
	v_pk_mul_f32 v[40:41], v[164:165], v[34:35] op_sel_hi:[0,1]
	v_pk_mul_f32 v[34:35], v[164:165], v[32:33] op_sel_hi:[0,1]
	v_cvt_pk_bf16_f32 v32, v36, v37
	v_cvt_pk_bf16_f32 v33, v38, v39
	v_cvt_pk_bf16_f32 v34, v34, v35
	v_cvt_pk_bf16_f32 v35, v40, v41
	v_pk_mul_f32 v[30:31], v[30:31], v[54:55]
	v_pk_mul_f32 v[28:29], v[28:29], v[52:53]
	v_pk_mul_f32 v[26:27], v[26:27], v[62:63]
	v_pk_mul_f32 v[24:25], v[24:25], v[60:61]
	global_store_dwordx4 v[100:101], v[32:35], off offset:64
	v_pk_mul_f32 v[30:31], v[172:173], v[30:31] op_sel_hi:[0,1]
	v_pk_mul_f32 v[28:29], v[172:173], v[28:29] op_sel_hi:[0,1]
	v_pk_mul_f32 v[32:33], v[172:173], v[26:27] op_sel_hi:[0,1]
	v_pk_mul_f32 v[26:27], v[172:173], v[24:25] op_sel_hi:[0,1]
	v_cvt_pk_bf16_f32 v24, v28, v29
	v_cvt_pk_bf16_f32 v25, v30, v31
	v_cvt_pk_bf16_f32 v26, v26, v27
	v_cvt_pk_bf16_f32 v27, v32, v33
	v_pk_mul_f32 v[22:23], v[22:23], v[54:55]
	v_pk_mul_f32 v[20:21], v[20:21], v[52:53]
	v_pk_mul_f32 v[18:19], v[18:19], v[62:63]
	v_pk_mul_f32 v[16:17], v[16:17], v[60:61]
	global_store_dwordx4 v[92:93], v[24:27], off offset:64
	v_pk_mul_f32 v[22:23], v[170:171], v[22:23] op_sel_hi:[0,1]
	v_pk_mul_f32 v[20:21], v[170:171], v[20:21] op_sel_hi:[0,1]
	v_pk_mul_f32 v[24:25], v[170:171], v[18:19] op_sel_hi:[0,1]
	v_pk_mul_f32 v[18:19], v[170:171], v[16:17] op_sel_hi:[0,1]
	v_cvt_pk_bf16_f32 v16, v20, v21
	v_cvt_pk_bf16_f32 v17, v22, v23
	v_cvt_pk_bf16_f32 v18, v18, v19
	v_cvt_pk_bf16_f32 v19, v24, v25
	v_pk_mul_f32 v[14:15], v[14:15], v[54:55]
	v_pk_mul_f32 v[12:13], v[12:13], v[52:53]
	v_pk_mul_f32 v[10:11], v[10:11], v[62:63]
	v_pk_mul_f32 v[8:9], v[8:9], v[60:61]
	global_store_dwordx4 v[84:85], v[16:19], off offset:64
	v_pk_mul_f32 v[14:15], v[168:169], v[14:15] op_sel_hi:[0,1]
	v_pk_mul_f32 v[12:13], v[168:169], v[12:13] op_sel_hi:[0,1]
	v_pk_mul_f32 v[16:17], v[168:169], v[10:11] op_sel_hi:[0,1]
	v_pk_mul_f32 v[10:11], v[168:169], v[8:9] op_sel_hi:[0,1]
	v_cvt_pk_bf16_f32 v8, v12, v13
	v_cvt_pk_bf16_f32 v9, v14, v15
	v_cvt_pk_bf16_f32 v10, v10, v11
	v_cvt_pk_bf16_f32 v11, v16, v17
	v_pk_mul_f32 v[6:7], v[6:7], v[54:55]
	v_pk_mul_f32 v[4:5], v[4:5], v[52:53]
	v_pk_mul_f32 v[2:3], v[2:3], v[62:63]
	v_pk_mul_f32 v[0:1], v[0:1], v[60:61]
	global_store_dwordx4 v[76:77], v[8:11], off offset:64
	v_pk_mul_f32 v[6:7], v[166:167], v[6:7] op_sel_hi:[0,1]
	v_pk_mul_f32 v[4:5], v[166:167], v[4:5] op_sel_hi:[0,1]
	v_pk_mul_f32 v[8:9], v[166:167], v[2:3] op_sel_hi:[0,1]
	v_pk_mul_f32 v[2:3], v[166:167], v[0:1] op_sel_hi:[0,1]
	v_cvt_pk_bf16_f32 v0, v4, v5
	v_cvt_pk_bf16_f32 v1, v6, v7
	v_cvt_pk_bf16_f32 v2, v2, v3
	v_cvt_pk_bf16_f32 v3, v8, v9
	global_store_dwordx4 v[68:69], v[0:3], off offset:64
	s_cbranch_vccnz .LBB0_1719
	s_andn2_b64 vcc, exec, s[6:7]
	s_cbranch_vccnz .LBB0_1718
	s_barrier
	s_branch .LBB0_1718

.LBB0_1975:
	ds_read_b128 v[144:147], v155
	ds_read_b128 v[160:163], v155 offset:1024
	ds_read_b128 v[164:167], v155 offset:2048
	ds_read_b128 v[168:171], v155 offset:3072
	ds_read_b128 v[172:175], v157
	ds_read_b128 v[176:179], v157 offset:1024
	ds_read_b128 v[180:183], v157 offset:2048
	ds_read_b128 v[186:189], v157 offset:3072
	s_add_u32 s26, s24, 0xfffc0080
	s_addc_u32 s27, s25, -1
	s_cmp_eq_u32 s51, 12
	s_cselect_b32 s29, s15, s27
	s_cselect_b32 s28, s47, s26
	s_cselect_b32 s27, s17, s50
	s_cselect_b32 s26, s48, s49
	s_add_i32 m0, s23, 0xc000
	ds_read_b128 v[190:193], v158
	ds_read_b128 v[194:197], v158 offset:1024
	ds_read_b128 v[198:201], v158 offset:2048
	ds_read_b128 v[202:205], v158 offset:3072
	ds_read_b128 v[206:209], v158 offset:4096
	ds_read_b128 v[210:213], v158 offset:5120
	ds_read_b128 v[214:217], v158 offset:6144
	ds_read_b128 v[218:221], v158 offset:7168
	global_load_lds_dwordx4 v136, s[24:25]
	s_add_i32 m0, s23, 0xe000
	s_nop 0
	global_load_lds_dwordx4 v138, s[24:25]
	s_waitcnt vmcnt(8)
	s_waitcnt lgkmcnt(0)
	s_barrier
	s_waitcnt lgkmcnt(0)
	v_mfma_f32_16x16x32_bf16 v[124:127], v[144:147], v[190:193], v[124:127]
	v_mfma_f32_16x16x32_bf16 v[120:123], v[164:167], v[190:193], v[120:123]
	v_mfma_f32_16x16x32_bf16 v[116:119], v[144:147], v[198:201], v[116:119]
	v_mfma_f32_16x16x32_bf16 v[104:107], v[164:167], v[198:201], v[104:107]
	v_mfma_f32_16x16x32_bf16 v[92:95], v[144:147], v[206:209], v[92:95]
	v_mfma_f32_16x16x32_bf16 v[88:91], v[164:167], v[206:209], v[88:91]
	v_mfma_f32_16x16x32_bf16 v[76:79], v[144:147], v[214:217], v[76:79]
	v_mfma_f32_16x16x32_bf16 v[72:75], v[164:167], v[214:217], v[72:75]
	v_mfma_f32_16x16x32_bf16 v[124:127], v[160:163], v[194:197], v[124:127]
	v_mfma_f32_16x16x32_bf16 v[120:123], v[168:171], v[194:197], v[120:123]
	v_mfma_f32_16x16x32_bf16 v[116:119], v[160:163], v[202:205], v[116:119]
	v_mfma_f32_16x16x32_bf16 v[104:107], v[168:171], v[202:205], v[104:107]
	v_mfma_f32_16x16x32_bf16 v[92:95], v[160:163], v[210:213], v[92:95]
	v_mfma_f32_16x16x32_bf16 v[88:91], v[168:171], v[210:213], v[88:91]
	v_mfma_f32_16x16x32_bf16 v[76:79], v[160:163], v[218:221], v[76:79]
	v_mfma_f32_16x16x32_bf16 v[72:75], v[168:171], v[218:221], v[72:75]
	v_mfma_f32_16x16x32_bf16 v[112:115], v[172:175], v[190:193], v[112:115]
	v_mfma_f32_16x16x32_bf16 v[108:111], v[180:183], v[190:193], v[108:111]
	v_mfma_f32_16x16x32_bf16 v[100:103], v[172:175], v[198:201], v[100:103]
	v_mfma_f32_16x16x32_bf16 v[96:99], v[180:183], v[198:201], v[96:99]
	v_mfma_f32_16x16x32_bf16 v[84:87], v[172:175], v[206:209], v[84:87]
	v_mfma_f32_16x16x32_bf16 v[80:83], v[180:183], v[206:209], v[80:83]
	v_mfma_f32_16x16x32_bf16 v[68:71], v[172:175], v[214:217], v[68:71]
	v_mfma_f32_16x16x32_bf16 v[64:67], v[180:183], v[214:217], v[64:67]
	v_mfma_f32_16x16x32_bf16 v[112:115], v[176:179], v[194:197], v[112:115]
	v_mfma_f32_16x16x32_bf16 v[108:111], v[186:189], v[194:197], v[108:111]
	v_mfma_f32_16x16x32_bf16 v[100:103], v[176:179], v[202:205], v[100:103]
	v_mfma_f32_16x16x32_bf16 v[96:99], v[186:189], v[202:205], v[96:99]
	v_mfma_f32_16x16x32_bf16 v[84:87], v[176:179], v[210:213], v[84:87]
	v_mfma_f32_16x16x32_bf16 v[80:83], v[186:189], v[210:213], v[80:83]
	v_mfma_f32_16x16x32_bf16 v[68:71], v[176:179], v[218:221], v[68:71]
	v_mfma_f32_16x16x32_bf16 v[64:67], v[186:189], v[218:221], v[64:67]
	s_barrier
	s_add_i32 s52, s43, s31
	s_mov_b32 m0, s52
	ds_read_b128 v[190:193], v158 offset:16384
	ds_read_b128 v[194:197], v158 offset:17408
	ds_read_b128 v[198:201], v158 offset:18432
	ds_read_b128 v[202:205], v158 offset:19456
	ds_read_b128 v[206:209], v158 offset:20480
	ds_read_b128 v[210:213], v158 offset:21504
	ds_read_b128 v[214:217], v158 offset:22528
	ds_read_b128 v[218:221], v158 offset:23552
	global_load_lds_dwordx4 v132, s[26:27]
	s_add_i32 m0, s52, 0x2000
	s_add_u32 s52, s26, 0x40000
	s_addc_u32 s53, s27, 0
	s_add_i32 s54, s44, s31
	global_load_lds_dwordx4 v128, s[26:27]
	s_mov_b32 m0, s54
	global_load_lds_dwordx4 v132, s[52:53]
	s_add_i32 m0, s54, 0x2000
	s_nop 0
	global_load_lds_dwordx4 v128, s[52:53]
	s_mov_b32 m0, s23
	s_nop 0
	global_load_lds_dwordx4 v134, s[28:29]
	s_mov_b32 m0, s35
	s_nop 0
	global_load_lds_dwordx4 v130, s[28:29]
	s_add_u32 s98, s26, s10
	s_addc_u32 s99, s27, s11
	s_add_u32 s100, s28, s10
	s_addc_u32 s101, s29, s11
	s_waitcnt vmcnt(8)
	s_waitcnt lgkmcnt(0)
	s_barrier
	s_waitcnt lgkmcnt(0)
	v_mfma_f32_16x16x32_bf16 v[60:63], v[144:147], v[190:193], v[60:63]
	v_mfma_f32_16x16x32_bf16 v[56:59], v[164:167], v[190:193], v[56:59]
	v_mfma_f32_16x16x32_bf16 v[44:47], v[144:147], v[198:201], v[44:47]
	v_mfma_f32_16x16x32_bf16 v[40:43], v[164:167], v[198:201], v[40:43]
	v_mfma_f32_16x16x32_bf16 v[28:31], v[144:147], v[206:209], v[28:31]
	v_mfma_f32_16x16x32_bf16 v[24:27], v[164:167], v[206:209], v[24:27]
	v_mfma_f32_16x16x32_bf16 v[12:15], v[144:147], v[214:217], v[12:15]
	v_mfma_f32_16x16x32_bf16 v[8:11], v[164:167], v[214:217], v[8:11]
	v_mfma_f32_16x16x32_bf16 v[60:63], v[160:163], v[194:197], v[60:63]
	v_mfma_f32_16x16x32_bf16 v[56:59], v[168:171], v[194:197], v[56:59]
	v_mfma_f32_16x16x32_bf16 v[44:47], v[160:163], v[202:205], v[44:47]
	v_mfma_f32_16x16x32_bf16 v[40:43], v[168:171], v[202:205], v[40:43]
	v_mfma_f32_16x16x32_bf16 v[28:31], v[160:163], v[210:213], v[28:31]
	v_mfma_f32_16x16x32_bf16 v[24:27], v[168:171], v[210:213], v[24:27]
	v_mfma_f32_16x16x32_bf16 v[12:15], v[160:163], v[218:221], v[12:15]
	v_mfma_f32_16x16x32_bf16 v[8:11], v[168:171], v[218:221], v[8:11]
	v_mfma_f32_16x16x32_bf16 v[52:55], v[172:175], v[190:193], v[52:55]
	v_mfma_f32_16x16x32_bf16 v[48:51], v[180:183], v[190:193], v[48:51]
	v_mfma_f32_16x16x32_bf16 v[36:39], v[172:175], v[198:201], v[36:39]
	v_mfma_f32_16x16x32_bf16 v[32:35], v[180:183], v[198:201], v[32:35]
	v_mfma_f32_16x16x32_bf16 v[20:23], v[172:175], v[206:209], v[20:23]
	v_mfma_f32_16x16x32_bf16 v[16:19], v[180:183], v[206:209], v[16:19]
	v_mfma_f32_16x16x32_bf16 v[4:7], v[172:175], v[214:217], v[4:7]
	v_mfma_f32_16x16x32_bf16 v[0:3], v[180:183], v[214:217], v[0:3]
	v_mfma_f32_16x16x32_bf16 v[52:55], v[176:179], v[194:197], v[52:55]
	v_mfma_f32_16x16x32_bf16 v[48:51], v[186:189], v[194:197], v[48:51]
	v_mfma_f32_16x16x32_bf16 v[36:39], v[176:179], v[202:205], v[36:39]
	v_mfma_f32_16x16x32_bf16 v[32:35], v[186:189], v[202:205], v[32:35]
	v_mfma_f32_16x16x32_bf16 v[20:23], v[176:179], v[210:213], v[20:23]
	v_mfma_f32_16x16x32_bf16 v[16:19], v[186:189], v[210:213], v[16:19]
	v_mfma_f32_16x16x32_bf16 v[4:7], v[176:179], v[218:221], v[4:7]
	v_mfma_f32_16x16x32_bf16 v[0:3], v[186:189], v[218:221], v[0:3]
	s_barrier
	s_add_i32 s52, 0, 0x18000
	v_add_u32_e32 v148, s52, v151
	s_add_i32 s53, 0, 0x1c000
	ds_read_b128 v[144:147], v148
	ds_read_b128 v[160:163], v148 offset:1024
	ds_read_b128 v[164:167], v148 offset:2048
	ds_read_b128 v[168:171], v148 offset:3072
	v_add_u32_e32 v148, s53, v151
	ds_read_b128 v[172:175], v148
	ds_read_b128 v[176:179], v148 offset:1024
	ds_read_b128 v[180:183], v148 offset:2048
	ds_read_b128 v[186:189], v148 offset:3072
	s_add_u32 s28, s28, 0x40000
	s_addc_u32 s29, s29, 0
	s_mov_b32 m0, s36
	ds_read_b128 v[190:193], v158 offset:32768
	ds_read_b128 v[194:197], v158 offset:33792
	ds_read_b128 v[198:201], v158 offset:34816
	ds_read_b128 v[202:205], v158 offset:35840
	ds_read_b128 v[206:209], v158 offset:36864
	ds_read_b128 v[210:213], v158 offset:37888
	ds_read_b128 v[214:217], v158 offset:38912
	ds_read_b128 v[218:221], v158 offset:39936
	global_load_lds_dwordx4 v134, s[28:29]
	s_mov_b32 m0, s37
	s_nop 0
	global_load_lds_dwordx4 v130, s[28:29]
	s_waitcnt vmcnt(8)
	s_waitcnt lgkmcnt(0)
	s_barrier
	s_waitcnt lgkmcnt(0)
	v_mfma_f32_16x16x32_bf16 v[124:127], v[144:147], v[190:193], v[124:127]
	v_mfma_f32_16x16x32_bf16 v[120:123], v[164:167], v[190:193], v[120:123]
	v_mfma_f32_16x16x32_bf16 v[116:119], v[144:147], v[198:201], v[116:119]
	v_mfma_f32_16x16x32_bf16 v[104:107], v[164:167], v[198:201], v[104:107]
	v_mfma_f32_16x16x32_bf16 v[92:95], v[144:147], v[206:209], v[92:95]
	v_mfma_f32_16x16x32_bf16 v[88:91], v[164:167], v[206:209], v[88:91]
	v_mfma_f32_16x16x32_bf16 v[76:79], v[144:147], v[214:217], v[76:79]
	v_mfma_f32_16x16x32_bf16 v[72:75], v[164:167], v[214:217], v[72:75]
	v_mfma_f32_16x16x32_bf16 v[124:127], v[160:163], v[194:197], v[124:127]
	v_mfma_f32_16x16x32_bf16 v[120:123], v[168:171], v[194:197], v[120:123]
	v_mfma_f32_16x16x32_bf16 v[116:119], v[160:163], v[202:205], v[116:119]
	v_mfma_f32_16x16x32_bf16 v[104:107], v[168:171], v[202:205], v[104:107]
	v_mfma_f32_16x16x32_bf16 v[92:95], v[160:163], v[210:213], v[92:95]
	v_mfma_f32_16x16x32_bf16 v[88:91], v[168:171], v[210:213], v[88:91]
	v_mfma_f32_16x16x32_bf16 v[76:79], v[160:163], v[218:221], v[76:79]
	v_mfma_f32_16x16x32_bf16 v[72:75], v[168:171], v[218:221], v[72:75]
	v_mfma_f32_16x16x32_bf16 v[112:115], v[172:175], v[190:193], v[112:115]
	v_mfma_f32_16x16x32_bf16 v[108:111], v[180:183], v[190:193], v[108:111]
	v_mfma_f32_16x16x32_bf16 v[100:103], v[172:175], v[198:201], v[100:103]
	v_mfma_f32_16x16x32_bf16 v[96:99], v[180:183], v[198:201], v[96:99]
	v_mfma_f32_16x16x32_bf16 v[84:87], v[172:175], v[206:209], v[84:87]
	v_mfma_f32_16x16x32_bf16 v[80:83], v[180:183], v[206:209], v[80:83]
	v_mfma_f32_16x16x32_bf16 v[68:71], v[172:175], v[214:217], v[68:71]
	v_mfma_f32_16x16x32_bf16 v[64:67], v[180:183], v[214:217], v[64:67]
	v_mfma_f32_16x16x32_bf16 v[112:115], v[176:179], v[194:197], v[112:115]
	v_mfma_f32_16x16x32_bf16 v[108:111], v[186:189], v[194:197], v[108:111]
	v_mfma_f32_16x16x32_bf16 v[100:103], v[176:179], v[202:205], v[100:103]
	v_mfma_f32_16x16x32_bf16 v[96:99], v[186:189], v[202:205], v[96:99]
	v_mfma_f32_16x16x32_bf16 v[84:87], v[176:179], v[210:213], v[84:87]
	v_mfma_f32_16x16x32_bf16 v[80:83], v[186:189], v[210:213], v[80:83]
	v_mfma_f32_16x16x32_bf16 v[68:71], v[176:179], v[218:221], v[68:71]
	v_mfma_f32_16x16x32_bf16 v[64:67], v[186:189], v[218:221], v[64:67]
	s_barrier
	s_add_i32 s28, s52, s31
	s_mov_b32 m0, s28
	ds_read_b128 v[190:193], v158 offset:49152
	ds_read_b128 v[194:197], v158 offset:50176
	ds_read_b128 v[198:201], v158 offset:51200
	ds_read_b128 v[202:205], v158 offset:52224
	ds_read_b128 v[206:209], v158 offset:53248
	ds_read_b128 v[210:213], v158 offset:54272
	ds_read_b128 v[214:217], v158 offset:55296
	ds_read_b128 v[218:221], v158 offset:56320
	global_load_lds_dwordx4 v132, s[98:99]
	s_add_i32 m0, s28, 0x2000
	s_add_u32 s26, s26, 0x40080
	s_addc_u32 s27, s27, 0
	s_add_i32 s28, s53, s31
	global_load_lds_dwordx4 v128, s[98:99]
	s_mov_b32 m0, s28
	s_nop 0
	global_load_lds_dwordx4 v132, s[26:27]
	s_add_i32 m0, s28, 0x2000
	s_nop 0
	global_load_lds_dwordx4 v128, s[26:27]
	s_mov_b32 m0, s39
	s_nop 0
	global_load_lds_dwordx4 v134, s[100:101]
	s_mov_b32 m0, s40
	s_nop 0
	global_load_lds_dwordx4 v130, s[100:101]
	s_waitcnt vmcnt(8)
	s_waitcnt lgkmcnt(0)
	s_barrier
	s_waitcnt lgkmcnt(0)
	v_mfma_f32_16x16x32_bf16 v[60:63], v[144:147], v[190:193], v[60:63]
	v_mfma_f32_16x16x32_bf16 v[56:59], v[164:167], v[190:193], v[56:59]
	s_cmp_eq_u32 s51, 12
	s_cbranch_scc0 .Lrs_skip_1975
	v_lshl_add_u32 v252, s22, 8, v149
	v_ashrrev_i32_e32 v253, 31, v252
	v_lshl_add_u64 v[254:255], v[252:253], 2, s[8:9]
	global_load_dword v243, v[254:255], off
	global_load_dword v244, v[254:255], off offset:64
	global_load_dword v245, v[254:255], off offset:128
	global_load_dword v246, v[254:255], off offset:192
	global_load_dword v247, v[254:255], off offset:512
	global_load_dword v248, v[254:255], off offset:576
	global_load_dword v249, v[254:255], off offset:640
	global_load_dword v250, v[254:255], off offset:704
.Lrs_skip_1975:
	v_mfma_f32_16x16x32_bf16 v[44:47], v[144:147], v[198:201], v[44:47]
	v_mfma_f32_16x16x32_bf16 v[40:43], v[164:167], v[198:201], v[40:43]
	v_mfma_f32_16x16x32_bf16 v[28:31], v[144:147], v[206:209], v[28:31]
	v_mfma_f32_16x16x32_bf16 v[24:27], v[164:167], v[206:209], v[24:27]
	v_mfma_f32_16x16x32_bf16 v[12:15], v[144:147], v[214:217], v[12:15]
	v_mfma_f32_16x16x32_bf16 v[8:11], v[164:167], v[214:217], v[8:11]
	v_mfma_f32_16x16x32_bf16 v[60:63], v[160:163], v[194:197], v[60:63]
	v_mfma_f32_16x16x32_bf16 v[56:59], v[168:171], v[194:197], v[56:59]
	v_mfma_f32_16x16x32_bf16 v[44:47], v[160:163], v[202:205], v[44:47]
	v_mfma_f32_16x16x32_bf16 v[40:43], v[168:171], v[202:205], v[40:43]
	v_mfma_f32_16x16x32_bf16 v[28:31], v[160:163], v[210:213], v[28:31]
	v_mfma_f32_16x16x32_bf16 v[24:27], v[168:171], v[210:213], v[24:27]
	v_mfma_f32_16x16x32_bf16 v[12:15], v[160:163], v[218:221], v[12:15]
	v_mfma_f32_16x16x32_bf16 v[8:11], v[168:171], v[218:221], v[8:11]
	v_mfma_f32_16x16x32_bf16 v[52:55], v[172:175], v[190:193], v[52:55]
	v_mfma_f32_16x16x32_bf16 v[48:51], v[180:183], v[190:193], v[48:51]
	v_mfma_f32_16x16x32_bf16 v[36:39], v[172:175], v[198:201], v[36:39]
	v_mfma_f32_16x16x32_bf16 v[32:35], v[180:183], v[198:201], v[32:35]
	v_mfma_f32_16x16x32_bf16 v[20:23], v[172:175], v[206:209], v[20:23]
	v_mfma_f32_16x16x32_bf16 v[16:19], v[180:183], v[206:209], v[16:19]
	v_mfma_f32_16x16x32_bf16 v[4:7], v[172:175], v[214:217], v[4:7]
	v_mfma_f32_16x16x32_bf16 v[0:3], v[180:183], v[214:217], v[0:3]
	v_mfma_f32_16x16x32_bf16 v[52:55], v[176:179], v[194:197], v[52:55]
	v_mfma_f32_16x16x32_bf16 v[48:51], v[186:189], v[194:197], v[48:51]
	v_mfma_f32_16x16x32_bf16 v[36:39], v[176:179], v[202:205], v[36:39]
	v_mfma_f32_16x16x32_bf16 v[32:35], v[186:189], v[202:205], v[32:35]
	v_mfma_f32_16x16x32_bf16 v[20:23], v[176:179], v[210:213], v[20:23]
	v_mfma_f32_16x16x32_bf16 v[16:19], v[186:189], v[210:213], v[16:19]
	v_mfma_f32_16x16x32_bf16 v[4:7], v[176:179], v[218:221], v[4:7]
	v_mfma_f32_16x16x32_bf16 v[0:3], v[186:189], v[218:221], v[0:3]
	s_barrier
	s_add_i32 s51, s51, 2
	s_add_u32 s24, s24, 0x100
	s_addc_u32 s25, s25, 0
	s_add_u32 s49, s49, 0x100
	s_addc_u32 s50, s50, 0
	s_cmp_gt_u32 s51, 13
	s_cbranch_scc0 .LBB0_1975
	s_and_b64 vcc, exec, s[12:13]
	s_cbranch_vccz .LBB0_1978
	s_barrier
.LBB0_1978:
	v_lshl_add_u32 v144, s22, 8, v149
	v_ashrrev_i32_e32 v145, 31, v144
	v_lshl_add_u64 v[146:147], v[144:145], 2, s[8:9]
	s_waitcnt vmcnt(0)
	v_mov_b32_e32 v145, v243
	v_mov_b32_e32 v148, v244
	v_mov_b32_e32 v150, v245
	v_mov_b32_e32 v152, v246
	v_mov_b32_e32 v154, v247
	v_mov_b32_e32 v156, v248
	v_mov_b32_e32 v162, v249
	v_mov_b32_e32 v163, v250
	v_lshl_or_b32 v146, s46, 7, v153
	v_ashrrev_i32_e32 v147, 31, v146
	v_lshl_add_u64 v[146:147], v[146:147], 1, s[68:69]
	v_mad_i64_i32 v[160:161], s[24:25], v144, s45, v[146:147]
	s_andn2_b64 vcc, exec, s[4:5]
	s_mov_b64 s[4:5], -1
	s_waitcnt vmcnt(0)
	v_fmamk_f32 v145, v145, 0x3a800000, v159
	v_fmamk_f32 v148, v148, 0x3a800000, v159
	v_rsq_f32_e32 v164, v148
	v_fmamk_f32 v150, v150, 0x3a800000, v159
	v_fmamk_f32 v152, v152, 0x3a800000, v159
	v_fmamk_f32 v165, v156, 0x3a800000, v159
	v_fmamk_f32 v167, v162, 0x3a800000, v159
	v_rsq_f32_e32 v162, v145
	v_fmamk_f32 v163, v163, 0x3a800000, v159
	v_rsq_f32_e32 v166, v150
	v_rsq_f32_e32 v156, v152
	v_pk_mul_f32 v[124:125], v[124:125], v[162:163] op_sel_hi:[1,0]
	v_pk_mul_f32 v[126:127], v[126:127], v[162:163] op_sel_hi:[1,0]
	v_pk_mul_f32 v[120:121], v[120:121], v[162:163] op_sel_hi:[1,0]
	v_pk_mul_f32 v[122:123], v[122:123], v[162:163] op_sel_hi:[1,0]
	v_rsq_f32_e32 v152, v165
	v_rsq_f32_e32 v150, v167
	v_rsq_f32_e32 v148, v163
	v_pk_mul_f32 v[112:113], v[112:113], v[162:163] op_sel_hi:[1,0]
	v_pk_mul_f32 v[114:115], v[114:115], v[162:163] op_sel_hi:[1,0]
	v_pk_mul_f32 v[108:109], v[108:109], v[162:163] op_sel_hi:[1,0]
	v_pk_mul_f32 v[110:111], v[110:111], v[162:163] op_sel_hi:[1,0]
	v_pk_mul_f32 v[116:117], v[116:117], v[164:165] op_sel_hi:[1,0]
	v_pk_mul_f32 v[100:101], v[100:101], v[164:165] op_sel_hi:[1,0]
	v_pk_mul_f32 v[118:119], v[118:119], v[164:165] op_sel_hi:[1,0]
	v_mul_f32_e32 v145, 0xbfb8aa3b, v124
	v_mul_f32_e32 v162, 0xbfb8aa3b, v125
	v_mul_f32_e32 v163, 0xbfb8aa3b, v126
	v_mul_f32_e32 v165, 0xbfb8aa3b, v127
	v_mul_f32_e32 v167, 0xbfb8aa3b, v120
	v_mul_f32_e32 v168, 0xbfb8aa3b, v121
	v_mul_f32_e32 v169, 0xbfb8aa3b, v122
	v_mul_f32_e32 v170, 0xbfb8aa3b, v123
	v_mul_f32_e32 v171, 0xbfb8aa3b, v116
	v_mul_f32_e32 v172, 0xbfb8aa3b, v117
	v_mul_f32_e32 v173, 0xbfb8aa3b, v118
	v_exp_f32_e32 v145, v145
	v_exp_f32_e32 v162, v162
	v_exp_f32_e32 v163, v163
	v_exp_f32_e32 v165, v165
	v_exp_f32_e32 v167, v167
	v_exp_f32_e32 v168, v168
	v_exp_f32_e32 v169, v169
	v_exp_f32_e32 v170, v170
	v_exp_f32_e32 v171, v171
	v_exp_f32_e32 v172, v172
	v_exp_f32_e32 v173, v173
	v_add_f32_e32 v145, 1.0, v145
	v_add_f32_e32 v175, 1.0, v162
	v_add_f32_e32 v176, 1.0, v163
	v_add_f32_e32 v165, 1.0, v165
	v_add_f32_e32 v167, 1.0, v167
	v_add_f32_e32 v177, 1.0, v168
	v_add_f32_e32 v178, 1.0, v169
	v_add_f32_e32 v179, 1.0, v170
	v_mul_f32_e32 v174, 0xbfb8aa3b, v119
	v_add_f32_e32 v180, 1.0, v171
	v_add_f32_e32 v181, 1.0, v172
	v_add_f32_e32 v182, 1.0, v173
	v_rcp_f32_e32 v162, v145
	v_rcp_f32_e32 v163, v175
	v_rcp_f32_e32 v168, v176
	v_rcp_f32_e32 v169, v165
	v_rcp_f32_e32 v170, v167
	v_rcp_f32_e32 v171, v177
	v_rcp_f32_e32 v172, v178
	v_rcp_f32_e32 v173, v179
	v_exp_f32_e32 v174, v174
	v_pk_mul_f32 v[124:125], v[124:125], v[162:163]
	v_pk_mul_f32 v[126:127], v[126:127], v[168:169]
	v_pk_mul_f32 v[120:121], v[120:121], v[170:171]
	v_pk_mul_f32 v[122:123], v[122:123], v[172:173]
	v_add_f32_e32 v183, 1.0, v174
	v_rcp_f32_e32 v174, v180
	v_rcp_f32_e32 v175, v181
	v_pk_mul_f32 v[112:113], v[112:113], v[124:125]
	v_pk_mul_f32 v[114:115], v[114:115], v[126:127]
	v_pk_mul_f32 v[120:121], v[108:109], v[120:121]
	v_pk_mul_f32 v[122:123], v[110:111], v[122:123]
	v_rcp_f32_e32 v176, v182
	v_cvt_pk_bf16_f32 v108, v112, v113
	v_cvt_pk_bf16_f32 v109, v114, v115
	v_cvt_pk_bf16_f32 v110, v120, v121
	v_cvt_pk_bf16_f32 v111, v122, v123
	v_rcp_f32_e32 v177, v183
	v_pk_mul_f32 v[104:105], v[104:105], v[164:165] op_sel_hi:[1,0]
	global_store_dwordx4 v[160:161], v[108:111], off nt
	v_pk_mul_f32 v[102:103], v[102:103], v[164:165] op_sel_hi:[1,0]
	v_pk_mul_f32 v[106:107], v[106:107], v[164:165] op_sel_hi:[1,0]
	v_mul_f32_e32 v110, 0xbfb8aa3b, v104
	v_exp_f32_e32 v110, v110
	v_pk_mul_f32 v[108:109], v[116:117], v[174:175]
	v_mul_f32_e32 v111, 0xbfb8aa3b, v107
	v_pk_mul_f32 v[100:101], v[100:101], v[108:109]
	v_pk_mul_f32 v[108:109], v[118:119], v[176:177]
	v_exp_f32_e32 v111, v111
	v_pk_mul_f32 v[102:103], v[102:103], v[108:109]
	v_mul_f32_e32 v108, 0xbfb8aa3b, v105
	v_exp_f32_e32 v109, v108
	v_add_f32_e32 v108, 1.0, v110
	v_mul_f32_e32 v110, 0xbfb8aa3b, v106
	v_exp_f32_e32 v110, v110
	v_add_f32_e32 v109, 1.0, v109
	v_rcp_f32_e32 v108, v108
	v_rcp_f32_e32 v109, v109
	v_add_f32_e32 v110, 1.0, v110
	v_add_f32_e32 v111, 1.0, v111
	v_rcp_f32_e32 v110, v110
	v_rcp_f32_e32 v111, v111
	v_pk_mul_f32 v[96:97], v[96:97], v[164:165] op_sel_hi:[1,0]
	v_pk_mul_f32 v[104:105], v[104:105], v[108:109]
	v_or_b32_e32 v108, 16, v144
	v_pk_mul_f32 v[104:105], v[96:97], v[104:105]
	v_pk_mul_f32 v[96:97], v[98:99], v[164:165] op_sel_hi:[1,0]
	v_pk_mul_f32 v[98:99], v[106:107], v[110:111]
	v_pk_mul_f32 v[92:93], v[92:93], v[166:167] op_sel_hi:[1,0]
	v_pk_mul_f32 v[106:107], v[96:97], v[98:99]
	v_cvt_pk_bf16_f32 v96, v100, v101
	v_cvt_pk_bf16_f32 v97, v102, v103
	v_cvt_pk_bf16_f32 v98, v104, v105
	v_cvt_pk_bf16_f32 v99, v106, v107
	v_mad_i64_i32 v[100:101], s[24:25], v108, s45, v[146:147]
	v_mul_f32_e32 v102, 0xbfb8aa3b, v92
	global_store_dwordx4 v[100:101], v[96:99], off nt
	v_pk_mul_f32 v[94:95], v[94:95], v[166:167] op_sel_hi:[1,0]
	v_exp_f32_e32 v102, v102
	v_mul_f32_e32 v96, 0xbfb8aa3b, v93
	v_exp_f32_e32 v97, v96
	v_mul_f32_e32 v98, 0xbfb8aa3b, v94
	v_mul_f32_e32 v99, 0xbfb8aa3b, v95
	v_exp_f32_e32 v98, v98
	v_exp_f32_e32 v99, v99
	v_add_f32_e32 v96, 1.0, v102
	v_add_f32_e32 v97, 1.0, v97
	v_rcp_f32_e32 v96, v96
	v_rcp_f32_e32 v97, v97
	v_add_f32_e32 v98, 1.0, v98
	v_add_f32_e32 v99, 1.0, v99
	v_rcp_f32_e32 v98, v98
	v_rcp_f32_e32 v99, v99
	v_pk_mul_f32 v[84:85], v[84:85], v[166:167] op_sel_hi:[1,0]
	v_pk_mul_f32 v[92:93], v[92:93], v[96:97]
	v_pk_mul_f32 v[88:89], v[88:89], v[166:167] op_sel_hi:[1,0]
	v_pk_mul_f32 v[84:85], v[84:85], v[92:93]
	v_pk_mul_f32 v[92:93], v[94:95], v[98:99]
	v_mul_f32_e32 v94, 0xbfb8aa3b, v88
	v_exp_f32_e32 v94, v94
	v_pk_mul_f32 v[86:87], v[86:87], v[166:167] op_sel_hi:[1,0]
	v_pk_mul_f32 v[90:91], v[90:91], v[166:167] op_sel_hi:[1,0]
	v_pk_mul_f32 v[86:87], v[86:87], v[92:93]
	v_mul_f32_e32 v92, 0xbfb8aa3b, v89
	v_exp_f32_e32 v93, v92
	v_add_f32_e32 v92, 1.0, v94
	v_mul_f32_e32 v94, 0xbfb8aa3b, v90
	v_mul_f32_e32 v95, 0xbfb8aa3b, v91
	v_exp_f32_e32 v94, v94
	v_exp_f32_e32 v95, v95
	v_add_f32_e32 v93, 1.0, v93
	v_rcp_f32_e32 v92, v92
	v_rcp_f32_e32 v93, v93
	v_add_f32_e32 v94, 1.0, v94
	v_add_f32_e32 v95, 1.0, v95
	v_rcp_f32_e32 v94, v94
	v_rcp_f32_e32 v95, v95
	v_pk_mul_f32 v[80:81], v[80:81], v[166:167] op_sel_hi:[1,0]
	v_pk_mul_f32 v[88:89], v[88:89], v[92:93]
	v_or_b32_e32 v92, 32, v144
	v_pk_mul_f32 v[88:89], v[80:81], v[88:89]
	v_pk_mul_f32 v[80:81], v[82:83], v[166:167] op_sel_hi:[1,0]
	v_pk_mul_f32 v[82:83], v[90:91], v[94:95]
	v_pk_mul_f32 v[76:77], v[76:77], v[156:157] op_sel_hi:[1,0]
	v_pk_mul_f32 v[90:91], v[80:81], v[82:83]
	v_cvt_pk_bf16_f32 v80, v84, v85
	v_cvt_pk_bf16_f32 v81, v86, v87
	v_cvt_pk_bf16_f32 v82, v88, v89
	v_cvt_pk_bf16_f32 v83, v90, v91
	v_mad_i64_i32 v[84:85], s[24:25], v92, s45, v[146:147]
	v_mul_f32_e32 v86, 0xbfb8aa3b, v76
	global_store_dwordx4 v[84:85], v[80:83], off nt
	v_pk_mul_f32 v[78:79], v[78:79], v[156:157] op_sel_hi:[1,0]
	v_exp_f32_e32 v86, v86
	v_mul_f32_e32 v80, 0xbfb8aa3b, v77
	v_exp_f32_e32 v81, v80
	v_mul_f32_e32 v82, 0xbfb8aa3b, v78
	v_mul_f32_e32 v83, 0xbfb8aa3b, v79
	v_exp_f32_e32 v82, v82
	v_exp_f32_e32 v83, v83
	v_add_f32_e32 v80, 1.0, v86
	v_add_f32_e32 v81, 1.0, v81
	v_rcp_f32_e32 v80, v80
	v_rcp_f32_e32 v81, v81
	v_add_f32_e32 v82, 1.0, v82
	v_add_f32_e32 v83, 1.0, v83
	v_rcp_f32_e32 v82, v82
	v_rcp_f32_e32 v83, v83
	v_pk_mul_f32 v[68:69], v[68:69], v[156:157] op_sel_hi:[1,0]
	v_pk_mul_f32 v[76:77], v[76:77], v[80:81]
	v_pk_mul_f32 v[72:73], v[72:73], v[156:157] op_sel_hi:[1,0]
	v_pk_mul_f32 v[68:69], v[68:69], v[76:77]
	v_pk_mul_f32 v[76:77], v[78:79], v[82:83]
	v_mul_f32_e32 v78, 0xbfb8aa3b, v72
	v_exp_f32_e32 v78, v78
	v_pk_mul_f32 v[70:71], v[70:71], v[156:157] op_sel_hi:[1,0]
	v_pk_mul_f32 v[74:75], v[74:75], v[156:157] op_sel_hi:[1,0]
	v_pk_mul_f32 v[70:71], v[70:71], v[76:77]
	v_mul_f32_e32 v76, 0xbfb8aa3b, v73
	v_exp_f32_e32 v77, v76
	v_add_f32_e32 v76, 1.0, v78
	v_mul_f32_e32 v78, 0xbfb8aa3b, v74
	v_mul_f32_e32 v79, 0xbfb8aa3b, v75
	v_exp_f32_e32 v78, v78
	v_exp_f32_e32 v79, v79
	v_add_f32_e32 v77, 1.0, v77
	v_rcp_f32_e32 v76, v76
	v_rcp_f32_e32 v77, v77
	v_add_f32_e32 v78, 1.0, v78
	v_add_f32_e32 v79, 1.0, v79
	v_rcp_f32_e32 v78, v78
	v_rcp_f32_e32 v79, v79
	v_fmamk_f32 v154, v154, 0x3a800000, v159
	v_rsq_f32_e32 v154, v154
	v_pk_mul_f32 v[64:65], v[64:65], v[156:157] op_sel_hi:[1,0]
	v_pk_mul_f32 v[72:73], v[72:73], v[76:77]
	v_or_b32_e32 v76, 48, v144
	v_pk_mul_f32 v[72:73], v[64:65], v[72:73]
	v_pk_mul_f32 v[64:65], v[66:67], v[156:157] op_sel_hi:[1,0]
	v_pk_mul_f32 v[66:67], v[74:75], v[78:79]
	v_pk_mul_f32 v[60:61], v[60:61], v[154:155] op_sel_hi:[1,0]
	v_pk_mul_f32 v[74:75], v[64:65], v[66:67]
	v_cvt_pk_bf16_f32 v64, v68, v69
	v_cvt_pk_bf16_f32 v65, v70, v71
	v_cvt_pk_bf16_f32 v66, v72, v73
	v_cvt_pk_bf16_f32 v67, v74, v75
	v_mad_i64_i32 v[68:69], s[24:25], v76, s45, v[146:147]
	global_store_dwordx4 v[68:69], v[64:67], off nt
	v_pk_mul_f32 v[62:63], v[62:63], v[154:155] op_sel_hi:[1,0]
	v_pk_mul_f32 v[52:53], v[52:53], v[154:155] op_sel_hi:[1,0]
	v_mul_f32_e32 v64, 0xbfb8aa3b, v60
	v_mul_f32_e32 v65, 0xbfb8aa3b, v61
	v_exp_f32_e32 v64, v64
	v_exp_f32_e32 v65, v65
	v_mul_f32_e32 v66, 0xbfb8aa3b, v62
	v_mul_f32_e32 v67, 0xbfb8aa3b, v63
	v_exp_f32_e32 v66, v66
	v_exp_f32_e32 v67, v67
	v_add_f32_e32 v64, 1.0, v64
	v_add_f32_e32 v65, 1.0, v65
	v_rcp_f32_e32 v64, v64
	v_rcp_f32_e32 v65, v65
	v_add_f32_e32 v66, 1.0, v66
	v_add_f32_e32 v67, 1.0, v67
	v_rcp_f32_e32 v66, v66
	v_rcp_f32_e32 v67, v67
	v_pk_mul_f32 v[60:61], v[60:61], v[64:65]
	v_pk_mul_f32 v[56:57], v[56:57], v[154:155] op_sel_hi:[1,0]
	v_pk_mul_f32 v[52:53], v[52:53], v[60:61]
	v_pk_mul_f32 v[60:61], v[62:63], v[66:67]
	v_mul_f32_e32 v62, 0xbfb8aa3b, v56
	v_exp_f32_e32 v62, v62
	v_pk_mul_f32 v[54:55], v[54:55], v[154:155] op_sel_hi:[1,0]
	v_pk_mul_f32 v[58:59], v[58:59], v[154:155] op_sel_hi:[1,0]
	v_pk_mul_f32 v[54:55], v[54:55], v[60:61]
	v_mul_f32_e32 v60, 0xbfb8aa3b, v57
	v_exp_f32_e32 v61, v60
	v_add_f32_e32 v60, 1.0, v62
	v_mul_f32_e32 v62, 0xbfb8aa3b, v58
	v_mul_f32_e32 v63, 0xbfb8aa3b, v59
	v_exp_f32_e32 v62, v62
	v_exp_f32_e32 v63, v63
	v_add_f32_e32 v61, 1.0, v61
	v_rcp_f32_e32 v60, v60
	v_rcp_f32_e32 v61, v61
	v_add_f32_e32 v62, 1.0, v62
	v_add_f32_e32 v63, 1.0, v63
	v_rcp_f32_e32 v62, v62
	v_rcp_f32_e32 v63, v63
	v_pk_mul_f32 v[48:49], v[48:49], v[154:155] op_sel_hi:[1,0]
	v_pk_mul_f32 v[56:57], v[56:57], v[60:61]
	v_add_u32_e32 v68, 0x80, v144
	v_pk_mul_f32 v[56:57], v[48:49], v[56:57]
	v_pk_mul_f32 v[48:49], v[50:51], v[154:155] op_sel_hi:[1,0]
	v_pk_mul_f32 v[50:51], v[58:59], v[62:63]
	v_pk_mul_f32 v[44:45], v[44:45], v[152:153] op_sel_hi:[1,0]
	v_pk_mul_f32 v[58:59], v[48:49], v[50:51]
	v_cvt_pk_bf16_f32 v48, v52, v53
	v_cvt_pk_bf16_f32 v49, v54, v55
	v_cvt_pk_bf16_f32 v50, v56, v57
	v_cvt_pk_bf16_f32 v51, v58, v59
	v_mad_i64_i32 v[52:53], s[24:25], v68, s45, v[146:147]
	v_mul_f32_e32 v54, 0xbfb8aa3b, v44
	global_store_dwordx4 v[52:53], v[48:51], off nt
	v_pk_mul_f32 v[46:47], v[46:47], v[152:153] op_sel_hi:[1,0]
	v_exp_f32_e32 v54, v54
	v_mul_f32_e32 v48, 0xbfb8aa3b, v45
	v_exp_f32_e32 v49, v48
	v_mul_f32_e32 v50, 0xbfb8aa3b, v46
	v_mul_f32_e32 v51, 0xbfb8aa3b, v47
	v_exp_f32_e32 v50, v50
	v_exp_f32_e32 v51, v51
	v_add_f32_e32 v48, 1.0, v54
	v_add_f32_e32 v49, 1.0, v49
	v_rcp_f32_e32 v48, v48
	v_rcp_f32_e32 v49, v49
	v_add_f32_e32 v50, 1.0, v50
	v_add_f32_e32 v51, 1.0, v51
	v_rcp_f32_e32 v50, v50
	v_rcp_f32_e32 v51, v51
	v_pk_mul_f32 v[36:37], v[36:37], v[152:153] op_sel_hi:[1,0]
	v_pk_mul_f32 v[44:45], v[44:45], v[48:49]
	v_pk_mul_f32 v[40:41], v[40:41], v[152:153] op_sel_hi:[1,0]
	v_pk_mul_f32 v[36:37], v[36:37], v[44:45]
	v_pk_mul_f32 v[44:45], v[46:47], v[50:51]
	v_mul_f32_e32 v46, 0xbfb8aa3b, v40
	v_exp_f32_e32 v46, v46
	v_pk_mul_f32 v[38:39], v[38:39], v[152:153] op_sel_hi:[1,0]
	v_pk_mul_f32 v[42:43], v[42:43], v[152:153] op_sel_hi:[1,0]
	v_pk_mul_f32 v[38:39], v[38:39], v[44:45]
	v_mul_f32_e32 v44, 0xbfb8aa3b, v41
	v_exp_f32_e32 v45, v44
	v_add_f32_e32 v44, 1.0, v46
	v_mul_f32_e32 v46, 0xbfb8aa3b, v42
	v_mul_f32_e32 v47, 0xbfb8aa3b, v43
	v_exp_f32_e32 v46, v46
	v_exp_f32_e32 v47, v47
	v_add_f32_e32 v45, 1.0, v45
	v_rcp_f32_e32 v44, v44
	v_rcp_f32_e32 v45, v45
	v_add_f32_e32 v46, 1.0, v46
	v_add_f32_e32 v47, 1.0, v47
	v_rcp_f32_e32 v46, v46
	v_rcp_f32_e32 v47, v47
	v_pk_mul_f32 v[32:33], v[32:33], v[152:153] op_sel_hi:[1,0]
	v_pk_mul_f32 v[40:41], v[40:41], v[44:45]
	v_add_u32_e32 v44, 0x90, v144
	v_pk_mul_f32 v[40:41], v[32:33], v[40:41]
	v_pk_mul_f32 v[32:33], v[34:35], v[152:153] op_sel_hi:[1,0]
	v_pk_mul_f32 v[34:35], v[42:43], v[46:47]
	v_pk_mul_f32 v[28:29], v[28:29], v[150:151] op_sel_hi:[1,0]
	v_pk_mul_f32 v[42:43], v[32:33], v[34:35]
	v_cvt_pk_bf16_f32 v32, v36, v37
	v_cvt_pk_bf16_f32 v33, v38, v39
	v_cvt_pk_bf16_f32 v34, v40, v41
	v_cvt_pk_bf16_f32 v35, v42, v43
	v_mad_i64_i32 v[36:37], s[24:25], v44, s45, v[146:147]
	v_mul_f32_e32 v38, 0xbfb8aa3b, v28
	global_store_dwordx4 v[36:37], v[32:35], off nt
	v_pk_mul_f32 v[30:31], v[30:31], v[150:151] op_sel_hi:[1,0]
	v_exp_f32_e32 v38, v38
	v_mul_f32_e32 v32, 0xbfb8aa3b, v29
	v_exp_f32_e32 v33, v32
	v_mul_f32_e32 v34, 0xbfb8aa3b, v30
	v_mul_f32_e32 v35, 0xbfb8aa3b, v31
	v_exp_f32_e32 v34, v34
	v_exp_f32_e32 v35, v35
	v_add_f32_e32 v32, 1.0, v38
	v_add_f32_e32 v33, 1.0, v33
	v_rcp_f32_e32 v32, v32
	v_rcp_f32_e32 v33, v33
	v_add_f32_e32 v34, 1.0, v34
	v_add_f32_e32 v35, 1.0, v35
	v_rcp_f32_e32 v34, v34
	v_rcp_f32_e32 v35, v35
	v_pk_mul_f32 v[20:21], v[20:21], v[150:151] op_sel_hi:[1,0]
	v_pk_mul_f32 v[28:29], v[28:29], v[32:33]
	v_pk_mul_f32 v[24:25], v[24:25], v[150:151] op_sel_hi:[1,0]
	v_pk_mul_f32 v[20:21], v[20:21], v[28:29]
	v_pk_mul_f32 v[28:29], v[30:31], v[34:35]
	v_mul_f32_e32 v30, 0xbfb8aa3b, v24
	v_exp_f32_e32 v30, v30
	v_pk_mul_f32 v[22:23], v[22:23], v[150:151] op_sel_hi:[1,0]
	v_pk_mul_f32 v[26:27], v[26:27], v[150:151] op_sel_hi:[1,0]
	v_pk_mul_f32 v[22:23], v[22:23], v[28:29]
	v_mul_f32_e32 v28, 0xbfb8aa3b, v25
	v_exp_f32_e32 v29, v28
	v_add_f32_e32 v28, 1.0, v30
	v_mul_f32_e32 v30, 0xbfb8aa3b, v26
	v_mul_f32_e32 v31, 0xbfb8aa3b, v27
	v_exp_f32_e32 v30, v30
	v_exp_f32_e32 v31, v31
	v_add_f32_e32 v29, 1.0, v29
	v_rcp_f32_e32 v28, v28
	v_rcp_f32_e32 v29, v29
	v_add_f32_e32 v30, 1.0, v30
	v_add_f32_e32 v31, 1.0, v31
	v_rcp_f32_e32 v30, v30
	v_rcp_f32_e32 v31, v31
	v_pk_mul_f32 v[16:17], v[16:17], v[150:151] op_sel_hi:[1,0]
	v_pk_mul_f32 v[24:25], v[24:25], v[28:29]
	v_add_u32_e32 v28, 0xa0, v144
	v_pk_mul_f32 v[24:25], v[16:17], v[24:25]
	v_pk_mul_f32 v[16:17], v[18:19], v[150:151] op_sel_hi:[1,0]
	v_pk_mul_f32 v[18:19], v[26:27], v[30:31]
	v_pk_mul_f32 v[12:13], v[12:13], v[148:149] op_sel_hi:[1,0]
	v_pk_mul_f32 v[26:27], v[16:17], v[18:19]
	v_cvt_pk_bf16_f32 v16, v20, v21
	v_cvt_pk_bf16_f32 v17, v22, v23
	v_cvt_pk_bf16_f32 v18, v24, v25
	v_cvt_pk_bf16_f32 v19, v26, v27
	v_mad_i64_i32 v[20:21], s[24:25], v28, s45, v[146:147]
	v_mul_f32_e32 v22, 0xbfb8aa3b, v12
	global_store_dwordx4 v[20:21], v[16:19], off nt
	v_pk_mul_f32 v[14:15], v[14:15], v[148:149] op_sel_hi:[1,0]
	v_exp_f32_e32 v22, v22
	v_mul_f32_e32 v16, 0xbfb8aa3b, v13
	v_exp_f32_e32 v17, v16
	v_mul_f32_e32 v18, 0xbfb8aa3b, v14
	v_mul_f32_e32 v19, 0xbfb8aa3b, v15
	v_exp_f32_e32 v18, v18
	v_exp_f32_e32 v19, v19
	v_add_f32_e32 v16, 1.0, v22
	v_add_f32_e32 v17, 1.0, v17
	v_rcp_f32_e32 v16, v16
	v_rcp_f32_e32 v17, v17
	v_add_f32_e32 v18, 1.0, v18
	v_add_f32_e32 v19, 1.0, v19
	v_rcp_f32_e32 v18, v18
	v_rcp_f32_e32 v19, v19
	v_pk_mul_f32 v[4:5], v[4:5], v[148:149] op_sel_hi:[1,0]
	v_pk_mul_f32 v[12:13], v[12:13], v[16:17]
	v_pk_mul_f32 v[8:9], v[8:9], v[148:149] op_sel_hi:[1,0]
	v_pk_mul_f32 v[4:5], v[4:5], v[12:13]
	v_pk_mul_f32 v[12:13], v[14:15], v[18:19]
	v_mul_f32_e32 v14, 0xbfb8aa3b, v8
	v_exp_f32_e32 v14, v14
	v_pk_mul_f32 v[6:7], v[6:7], v[148:149] op_sel_hi:[1,0]
	v_pk_mul_f32 v[10:11], v[10:11], v[148:149] op_sel_hi:[1,0]
	v_pk_mul_f32 v[6:7], v[6:7], v[12:13]
	v_mul_f32_e32 v12, 0xbfb8aa3b, v9
	v_exp_f32_e32 v13, v12
	v_add_f32_e32 v12, 1.0, v14
	v_mul_f32_e32 v14, 0xbfb8aa3b, v10
	v_mul_f32_e32 v15, 0xbfb8aa3b, v11
	v_exp_f32_e32 v14, v14
	v_exp_f32_e32 v15, v15
	v_add_f32_e32 v13, 1.0, v13
	v_rcp_f32_e32 v12, v12
	v_rcp_f32_e32 v13, v13
	v_add_f32_e32 v14, 1.0, v14
	v_add_f32_e32 v15, 1.0, v15
	v_rcp_f32_e32 v14, v14
	v_rcp_f32_e32 v15, v15
	v_pk_mul_f32 v[0:1], v[0:1], v[148:149] op_sel_hi:[1,0]
	v_pk_mul_f32 v[8:9], v[8:9], v[12:13]
	v_add_u32_e32 v12, 0xb0, v144
	v_pk_mul_f32 v[8:9], v[0:1], v[8:9]
	v_pk_mul_f32 v[0:1], v[2:3], v[148:149] op_sel_hi:[1,0]
	v_pk_mul_f32 v[2:3], v[10:11], v[14:15]
	s_nop 0
	v_pk_mul_f32 v[10:11], v[0:1], v[2:3]
	v_cvt_pk_bf16_f32 v0, v4, v5
	v_cvt_pk_bf16_f32 v1, v6, v7
	v_cvt_pk_bf16_f32 v2, v8, v9
	v_cvt_pk_bf16_f32 v3, v10, v11
	v_mad_i64_i32 v[4:5], s[24:25], v12, s45, v[146:147]
	global_store_dwordx4 v[4:5], v[0:3], off nt
	s_cbranch_vccnz .LBB0_1971
	s_andn2_b64 vcc, exec, s[6:7]
	s_cbranch_vccnz .LBB0_1970
	s_barrier
	s_branch .LBB0_1970

	.amdhsa_kernel _Z10fwd_kernel4Args
		.amdhsa_group_segment_fixed_size 0
		.amdhsa_private_segment_fixed_size 0
		.amdhsa_kernarg_size 464
		.amdhsa_user_sgpr_count 2
		.amdhsa_user_sgpr_dispatch_ptr 0
		.amdhsa_user_sgpr_queue_ptr 0
		.amdhsa_user_sgpr_kernarg_segment_ptr 1
		.amdhsa_user_sgpr_dispatch_id 0
		.amdhsa_user_sgpr_kernarg_preload_length 0
		.amdhsa_user_sgpr_kernarg_preload_offset 0
		.amdhsa_user_sgpr_private_segment_size 0
		.amdhsa_uses_dynamic_stack 0
		.amdhsa_enable_private_segment 0
		.amdhsa_system_sgpr_workgroup_id_x 1
		.amdhsa_system_sgpr_workgroup_id_y 0
		.amdhsa_system_sgpr_workgroup_id_z 0
		.amdhsa_system_sgpr_workgroup_info 0
		.amdhsa_system_vgpr_workitem_id 2
		.amdhsa_next_free_vgpr 256
		.amdhsa_next_free_sgpr 102
		.amdhsa_accum_offset 256
		.amdhsa_reserve_vcc 1
		.amdhsa_float_round_mode_32 0
		.amdhsa_float_round_mode_16_64 0
		.amdhsa_float_denorm_mode_32 3
		.amdhsa_float_denorm_mode_16_64 3
		.amdhsa_dx10_clamp 1
		.amdhsa_ieee_mode 1
		.amdhsa_fp16_overflow 0
		.amdhsa_tg_split 0
		.amdhsa_exception_fp_ieee_invalid_op 0
		.amdhsa_exception_fp_denorm_src 0
		.amdhsa_exception_fp_ieee_div_zero 0
		.amdhsa_exception_fp_ieee_overflow 0
		.amdhsa_exception_fp_ieee_underflow 0
		.amdhsa_exception_fp_ieee_inexact 0
		.amdhsa_exception_int_div_zero 0
	.end_amdhsa_kernel

amdhsa.kernels:
  - .agpr_count:     0
    .args:
      - .offset:         0
        .size:           208
        .value_kind:     by_value
      - .offset:         208
        .size:           4
        .value_kind:     hidden_block_count_x
      - .offset:         212
        .size:           4
        .value_kind:     hidden_block_count_y
      - .offset:         216
        .size:           4
        .value_kind:     hidden_block_count_z
      - .offset:         220
        .size:           2
        .value_kind:     hidden_group_size_x
      - .offset:         222
        .size:           2
        .value_kind:     hidden_group_size_y
      - .offset:         224
        .size:           2
        .value_kind:     hidden_group_size_z
      - .offset:         226
        .size:           2
        .value_kind:     hidden_remainder_x
      - .offset:         228
        .size:           2
        .value_kind:     hidden_remainder_y
      - .offset:         230
        .size:           2
        .value_kind:     hidden_remainder_z
      - .offset:         248
        .size:           8
        .value_kind:     hidden_global_offset_x
      - .offset:         256
        .size:           8
        .value_kind:     hidden_global_offset_y
      - .offset:         264
        .size:           8
        .value_kind:     hidden_global_offset_z
      - .offset:         272
        .size:           2
        .value_kind:     hidden_grid_dims
      - .offset:         296
        .size:           8
        .value_kind:     hidden_multigrid_sync_arg
      - .offset:         328
        .size:           4
        .value_kind:     hidden_dynamic_lds_size
    .group_segment_fixed_size: 0
    .kernarg_segment_align: 8
    .kernarg_segment_size: 464
    .language:       OpenCL C
    .language_version:
      - 2
      - 0
    .max_flat_workgroup_size: 512
    .name:           _Z10fwd_kernel4Args
    .private_segment_fixed_size: 0
    .sgpr_count:     108
    .sgpr_spill_count: 64
    .symbol:         _Z10fwd_kernel4Args.kd
    .uniform_work_group_size: 1
    .uses_dynamic_stack: false
    .vgpr_count:     256
    .vgpr_spill_count: 0
    .wavefront_size: 64
